# sc0 cache policy on every LDS-DMA (global_load_lds) load
# speedup vs baseline: 1.0018x; 1.0018x over previous
.LBB0_201:
	v_lshlrev_b32_e32 v2, 4, v0
	v_and_b32_e32 v3, 32, v0
	v_lshrrev_b32_e32 v4, 1, v0
	v_lshrrev_b32_e32 v5, 5, v0
	s_ashr_i32 s0, s3, 3
	v_bfe_u32 v12, v0, 2, 4
	v_bitop3_b32 v10, v2, v3, 48 bitop3:0x6c
	v_and_b32_e32 v11, 64, v0
	v_and_b32_e32 v4, 24, v4
	v_and_b32_e32 v5, 4, v5
	v_bfe_u32 v6, v0, 2, 2
	v_or_b32_e32 v13, 0x2000, v2
	s_add_u32 s47, s94, 0x1f80000
	v_or_b32_e32 v3, v10, v11
	v_or3_b32 v4, v5, v6, v4
	v_and_or_b32 v5, v179, 48, v12
	v_lshrrev_b32_e32 v2, 7, v13
	s_movk_i32 s1, 0x70
	s_addc_u32 s48, s95, 0
	v_lshl_or_b32 v146, v5, 11, v3
	v_and_or_b32 v5, v2, s1, v12
	s_movk_i32 s1, 0x60
	s_add_i32 s0, s2, s0
	v_and_or_b32 v2, v2, s1, v4
	s_mul_hi_i32 s1, s0, 0x2e8ba2e9
	s_lshr_b32 s2, s1, 31
	s_ashr_i32 s1, s1, 5
	s_add_i32 s1, s1, s2
	s_lshl_b32 s2, s1, 3
	s_sub_i32 s3, 0x41, s2
	s_mulk_i32 s1, 0xb0
	v_and_or_b32 v6, v179, 32, v4
	s_min_u32 s3, s3, 8
	s_sub_i32 s6, s0, s1
	v_lshl_or_b32 v148, v6, 11, v3
	v_lshl_or_b32 v150, v5, 11, v3
	v_lshl_or_b32 v152, v2, 11, v3
	s_sext_i32_i16 s0, s6
	v_cvt_f32_ubyte0_e32 v3, s3
	v_cvt_f32_i32_e32 v2, s0
	v_rcp_iflag_f32_e32 v4, v3
	s_lshr_b32 s9, s5, 6
	s_ashr_i32 s0, s0, 30
	s_lshr_b32 s8, s5, 8
	v_mul_f32_e32 v4, v2, v4
	v_trunc_f32_e32 v4, v4
	v_fma_f32 v2, -v4, v3, v2
	v_cvt_i32_f32_e32 v4, v4
	s_lshl_b32 s49, s9, 10
	s_or_b32 s4, s0, 1
	v_cmp_ge_f32_e64 s[0:1], |v2|, v3
	s_and_b64 s[0:1], s[0:1], exec
	s_cselect_b32 s0, s4, 0
	v_readfirstlane_b32 s1, v4
	s_add_i32 s4, s1, s0
	s_mul_i32 s0, s4, s3
	s_sub_i32 s0, s6, s0
	s_sext_i32_i16 s0, s0
	s_add_i32 s0, s2, s0
	s_ashr_i32 s1, s0, 31
	s_bfe_i64 s[6:7], s[4:5], 0x100000
	s_lshl_b64 s[2:3], s[0:1], 19
	s_lshl_b64 s[6:7], s[6:7], 19
	s_add_u32 s6, s94, s6
	s_addc_u32 s7, s95, s7
	s_add_i32 s50, s49, 0
	s_add_i32 m0, s50, 0x10000
	v_writelane_b32 v248, s56, 41
	global_load_lds_dwordx4 v148, s[6:7] sc0
	s_add_i32 m0, s50, 0x12000
	s_add_u32 s2, s47, s2
	global_load_lds_dwordx4 v152, s[6:7] sc0
	s_addc_u32 s3, s48, s3
	s_mov_b32 m0, s50
	s_add_i32 s51, s50, 0x2000
	global_load_lds_dwordx4 v146, s[2:3] sc0
	s_mov_b32 m0, s51
	s_add_u32 s12, s6, 0x40000
	global_load_lds_dwordx4 v150, s[2:3] sc0
	s_addc_u32 s13, s7, 0
	s_add_i32 m0, s50, 0x14000
	v_mov_b32_e32 v155, 0
	global_load_lds_dwordx4 v148, s[12:13] sc0
	s_add_i32 m0, s50, 0x16000
	v_writelane_b32 v248, s57, 42
	global_load_lds_dwordx4 v152, s[12:13] sc0
	s_add_u32 s12, s2, 0x40000
	s_addc_u32 s13, s3, 0
	s_add_i32 s52, s50, 0x4000
	s_mov_b32 m0, s52
	s_add_i32 s53, s50, 0x6000
	global_load_lds_dwordx4 v146, s[12:13] sc0
	s_mov_b32 m0, s53
	s_cmp_eq_u32 s8, 1
	global_load_lds_dwordx4 v150, s[12:13] sc0
	v_mov_b32_e32 v149, v155
	v_mov_b32_e32 v153, v155
	v_mov_b32_e32 v147, v155
	v_mov_b32_e32 v151, v155
	s_cselect_b64 s[10:11], -1, 0
	s_mov_b32 s54, 0
	v_lshl_add_u64 v[6:7], s[6:7], 0, v[148:149]
	v_lshl_add_u64 v[4:5], s[6:7], 0, v[152:153]
	v_lshl_add_u64 v[2:3], s[2:3], 0, v[146:147]
	v_writelane_b32 v248, s10, 43
	s_cmp_lg_u32 s8, 1
	v_lshl_add_u64 v[8:9], s[2:3], 0, v[150:151]
	v_writelane_b32 v248, s11, 44
	s_cbranch_scc1 .LBB0_203
	s_barrier
.LBB0_203:
	s_add_u32 s30, s94, 0x72d2400
	s_addc_u32 s31, s95, 0
	s_add_u32 s62, s94, 0x4202000
	s_addc_u32 s63, s95, 0
	s_add_u32 s10, s94, 0xbd86c00
	s_addc_u32 s11, s95, 0
	v_writelane_b32 v248, s10, 45
	v_and_b32_e32 v169, 3, v1
	v_and_b32_e32 v167, 15, v0
	v_writelane_b32 v248, s11, 46
	s_add_u32 s10, s94, 0xbe08c00
	s_addc_u32 s11, s95, 0
	v_writelane_b32 v248, s10, 47
	v_lshlrev_b32_e32 v14, 4, v169
	s_sext_i32_i16 s70, s4
	v_writelane_b32 v248, s11, 48
	s_add_u32 s10, s94, 0xbe8ac00
	s_addc_u32 s11, s95, 0
	s_add_u32 s24, s92, 0x8720000
	s_addc_u32 s25, s93, 0
	v_lshl_or_b32 v15, v167, 6, v14
	s_lshl_b32 s4, s8, 13
	v_and_b32_e32 v16, 32, v165
	s_mov_b64 s[26:27], 0x80
	s_and_b32 s1, s9, 3
	v_bitop3_b32 v15, v15, s4, v16 bitop3:0xde
	v_lshlrev_b32_e32 v17, 6, v0
	s_movk_i32 s4, 0x3c0
	s_add_i32 m0, s50, 0x18000
	v_lshl_add_u64 v[6:7], v[6:7], 0, s[26:27]
	s_lshl_b32 s55, s8, 6
	v_and_or_b32 v14, v17, s4, v14
	s_lshl_b32 s4, s1, 12
	s_waitcnt vmcnt(4)
	s_barrier
	global_load_lds_dwordx4 v[6:7], off sc0
	v_lshl_add_u64 v[4:5], v[4:5], 0, s[26:27]
	s_add_i32 m0, s50, 0x1a000
	s_add_i32 s56, s50, 0x8000
	s_add_i32 s57, s50, 0xa000
	global_load_lds_dwordx4 v[4:5], off sc0
	v_lshl_add_u64 v[2:3], v[2:3], 0, s[26:27]
	s_mov_b32 m0, s56
	s_add_u32 s28, s6, 0x40080
	global_load_lds_dwordx4 v[2:3], off sc0
	v_lshl_add_u64 v[2:3], v[8:9], 0, s[26:27]
	s_mov_b32 m0, s57
	s_addc_u32 s29, s7, 0
	global_load_lds_dwordx4 v[2:3], off sc0
	s_add_i32 m0, s50, 0x1c000
	v_lshl_add_u64 v[2:3], s[28:29], 0, v[148:149]
	global_load_lds_dwordx4 v[2:3], off sc0
	v_lshl_add_u64 v[2:3], s[28:29], 0, v[152:153]
	s_add_i32 m0, s50, 0x1e000
	s_lshl_b32 s59, s8, 1
	global_load_lds_dwordx4 v[2:3], off sc0
	s_lshl_b32 s58, s1, 4
	s_add_i32 s59, s59, 0xfffff2
	s_cmpk_lt_u32 s5, 0x100
	v_writelane_b32 v248, s10, 49
	s_cselect_b64 s[28:29], -1, 0
	s_cmpk_gt_u32 s5, 0xff
	v_writelane_b32 v248, s11, 50
	v_bitop3_b32 v171, s4, v14, v16 bitop3:0xf6
	s_cselect_b64 s[4:5], -1, 0
	v_writelane_b32 v248, s4, 51
	s_waitcnt lgkmcnt(0)
	s_ashr_i32 s60, s96, 31
	s_lshl_b32 s1, s1, 6
	v_writelane_b32 v248, s5, 52
	s_lshl_b32 s4, s8, 9
	v_lshlrev_b32_e32 v2, 8, v0
	s_add_u32 s61, s94, s1
	v_readlane_b32 s8, v248, 18
	v_and_b32_e32 v2, 0x18000, v2
	v_lshlrev_b32_e32 v3, 11, v12
	s_addc_u32 s97, s95, 0
	v_readlane_b32 s20, v248, 30
	v_or3_b32 v2, v10, v2, v3
	v_readlane_b32 s21, v248, 31
	s_add_u32 s34, s20, 0x1000
	v_add_u32_e32 v156, v2, v11
	v_lshlrev_b32_e32 v2, 4, v13
	s_addc_u32 s35, s21, 0
	v_and_b32_e32 v2, 0x38000, v2
	s_waitcnt vmcnt(6)
	s_add_u32 s36, s20, 0x2000
	v_or3_b32 v2, v10, v2, v3
	s_addc_u32 s37, s21, 0
	s_add_i32 s65, s4, 0
	v_add_u32_e32 v158, v2, v11
	s_add_i32 s66, 0, 0x10000
	s_add_i32 s67, 0, 0x14000
	v_mbcnt_lo_u32_b32 v2, -1, 0
	s_add_i32 s77, s65, 0x20010
	s_add_i32 s64, s65, 0x1fe10
	s_add_i32 s65, s65, 0x1ff10
	v_mov_b32_e32 v157, v155
	v_mov_b32_e32 v159, v155
	v_mov_b64_e32 v[160:161], 0x596
	v_mov_b64_e32 v[162:163], 0x595
	v_add_u32_e32 v173, s66, v171
	v_add_u32_e32 v175, 0, v15
	v_add_u32_e32 v177, s67, v171
	s_add_i32 s68, 0, 0x20410
	s_movk_i32 s69, 0xc00
	v_mbcnt_hi_u32_b32 v189, -1, v2
	s_barrier
	v_readlane_b32 s9, v248, 19
	v_readlane_b32 s10, v248, 20
	v_readlane_b32 s11, v248, 21
	v_readlane_b32 s12, v248, 22
	v_readlane_b32 s13, v248, 23
	v_readlane_b32 s14, v248, 24
	v_readlane_b32 s15, v248, 25
	v_readlane_b32 s16, v248, 26
	v_readlane_b32 s17, v248, 27
	v_readlane_b32 s18, v248, 28
	v_readlane_b32 s19, v248, 29
	v_readlane_b32 s22, v248, 32
	v_readlane_b32 s23, v248, 33
	s_branch .LBB0_205

.Lpeel_p1:
	ds_read_b128 v[130:133], v173
	ds_read_b128 v[134:137], v173 offset:1024
	ds_read_b128 v[138:141], v173 offset:2048
	ds_read_b128 v[142:145], v173 offset:3072
	s_add_u32 s6, s2, 0xfffc0080
	s_addc_u32 s7, s3, -1
	s_cmp_eq_u32 s73, 12
	s_cselect_b32 s9, s1, s7
	s_cselect_b32 s8, s33, s6
	s_cselect_b32 s7, s39, s72
	s_cselect_b32 s6, s41, s71
	s_add_i32 m0, s50, 0xc000
	ds_read_b128 v[180:183], v175
	ds_read_b128 v[184:187], v175 offset:1024
	ds_read_b128 v[190:193], v175 offset:2048
	ds_read_b128 v[194:197], v175 offset:3072
	ds_read_b128 v[198:201], v175 offset:4096
	ds_read_b128 v[202:205], v175 offset:5120
	ds_read_b128 v[206:209], v175 offset:6144
	ds_read_b128 v[210:213], v175 offset:7168
	global_load_lds_dwordx4 v156, s[2:3] sc0
	s_add_i32 m0, s50, 0xe000
	s_nop 0
	global_load_lds_dwordx4 v158, s[2:3] sc0
	s_waitcnt lgkmcnt(8)
	s_barrier
	s_waitcnt lgkmcnt(0)
	v_mfma_f32_16x16x32_bf16 v[126:129], v[130:133], v[180:183], 0
	v_mfma_f32_16x16x32_bf16 v[122:125], v[138:141], v[180:183], 0
	v_mfma_f32_16x16x32_bf16 v[118:121], v[130:133], v[190:193], 0
	v_mfma_f32_16x16x32_bf16 v[110:113], v[138:141], v[190:193], 0
	v_mfma_f32_16x16x32_bf16 v[102:105], v[130:133], v[198:201], 0
	v_mfma_f32_16x16x32_bf16 v[94:97], v[138:141], v[198:201], 0
	v_mfma_f32_16x16x32_bf16 v[86:89], v[130:133], v[206:209], 0
	v_mfma_f32_16x16x32_bf16 v[78:81], v[138:141], v[206:209], 0
	v_mfma_f32_16x16x32_bf16 v[126:129], v[134:137], v[184:187], v[126:129]
	v_mfma_f32_16x16x32_bf16 v[122:125], v[142:145], v[184:187], v[122:125]
	v_mfma_f32_16x16x32_bf16 v[118:121], v[134:137], v[194:197], v[118:121]
	v_mfma_f32_16x16x32_bf16 v[110:113], v[142:145], v[194:197], v[110:113]
	v_mfma_f32_16x16x32_bf16 v[102:105], v[134:137], v[202:205], v[102:105]
	v_mfma_f32_16x16x32_bf16 v[94:97], v[142:145], v[202:205], v[94:97]
	v_mfma_f32_16x16x32_bf16 v[86:89], v[134:137], v[210:213], v[86:89]
	v_mfma_f32_16x16x32_bf16 v[78:81], v[142:145], v[210:213], v[78:81]
	s_barrier
	s_add_i32 s74, s66, s49
	s_add_u32 s98, s6, 0x80
	s_addc_u32 s99, s7, 0
	s_mov_b32 m0, s74
	ds_read_b128 v[214:217], v177
	ds_read_b128 v[218:221], v177 offset:1024
	ds_read_b128 v[222:225], v177 offset:2048
	ds_read_b128 v[226:229], v177 offset:3072
	global_load_lds_dwordx4 v148, s[6:7] sc0
	s_add_i32 m0, s74, 0x2000
	s_nop 0
	global_load_lds_dwordx4 v152, s[6:7] sc0
	s_barrier
	s_waitcnt lgkmcnt(0)
	v_mfma_f32_16x16x32_bf16 v[114:117], v[214:217], v[180:183], 0
	v_mfma_f32_16x16x32_bf16 v[106:109], v[222:225], v[180:183], 0
	v_mfma_f32_16x16x32_bf16 v[98:101], v[214:217], v[190:193], 0
	v_mfma_f32_16x16x32_bf16 v[90:93], v[222:225], v[190:193], 0
	v_mfma_f32_16x16x32_bf16 v[82:85], v[214:217], v[198:201], 0
	v_mfma_f32_16x16x32_bf16 v[74:77], v[222:225], v[198:201], 0
	v_mfma_f32_16x16x32_bf16 v[70:73], v[214:217], v[206:209], 0
	v_mfma_f32_16x16x32_bf16 v[66:69], v[222:225], v[206:209], 0
	v_mfma_f32_16x16x32_bf16 v[114:117], v[218:221], v[184:187], v[114:117]
	v_mfma_f32_16x16x32_bf16 v[106:109], v[226:229], v[184:187], v[106:109]
	v_mfma_f32_16x16x32_bf16 v[98:101], v[218:221], v[194:197], v[98:101]
	v_mfma_f32_16x16x32_bf16 v[90:93], v[226:229], v[194:197], v[90:93]
	v_mfma_f32_16x16x32_bf16 v[82:85], v[218:221], v[202:205], v[82:85]
	v_mfma_f32_16x16x32_bf16 v[74:77], v[226:229], v[202:205], v[74:77]
	v_mfma_f32_16x16x32_bf16 v[70:73], v[218:221], v[210:213], v[70:73]
	v_mfma_f32_16x16x32_bf16 v[66:69], v[226:229], v[210:213], v[66:69]
	s_barrier
	s_mov_b32 m0, s50
	s_add_u32 s100, s8, 0x80
	s_addc_u32 s101, s9, 0
	ds_read_b128 v[180:183], v175 offset:16384
	ds_read_b128 v[184:187], v175 offset:17408
	ds_read_b128 v[190:193], v175 offset:18432
	ds_read_b128 v[194:197], v175 offset:19456
	ds_read_b128 v[198:201], v175 offset:20480
	ds_read_b128 v[202:205], v175 offset:21504
	ds_read_b128 v[206:209], v175 offset:22528
	ds_read_b128 v[210:213], v175 offset:23552
	global_load_lds_dwordx4 v146, s[8:9] sc0
	s_mov_b32 m0, s51
	s_nop 0
	global_load_lds_dwordx4 v150, s[8:9] sc0
	s_barrier
	s_waitcnt lgkmcnt(0)
	v_mfma_f32_16x16x32_bf16 v[62:65], v[130:133], v[180:183], 0
	v_mfma_f32_16x16x32_bf16 v[58:61], v[138:141], v[180:183], 0
	v_mfma_f32_16x16x32_bf16 v[54:57], v[130:133], v[190:193], 0
	v_mfma_f32_16x16x32_bf16 v[46:49], v[138:141], v[190:193], 0
	v_mfma_f32_16x16x32_bf16 v[38:41], v[130:133], v[198:201], 0
	v_mfma_f32_16x16x32_bf16 v[30:33], v[138:141], v[198:201], 0
	v_mfma_f32_16x16x32_bf16 v[22:25], v[130:133], v[206:209], 0
	v_mfma_f32_16x16x32_bf16 v[14:17], v[138:141], v[206:209], 0
	v_mfma_f32_16x16x32_bf16 v[62:65], v[134:137], v[184:187], v[62:65]
	v_mfma_f32_16x16x32_bf16 v[58:61], v[142:145], v[184:187], v[58:61]
	v_mfma_f32_16x16x32_bf16 v[54:57], v[134:137], v[194:197], v[54:57]
	v_mfma_f32_16x16x32_bf16 v[46:49], v[142:145], v[194:197], v[46:49]
	v_mfma_f32_16x16x32_bf16 v[38:41], v[134:137], v[202:205], v[38:41]
	v_mfma_f32_16x16x32_bf16 v[30:33], v[142:145], v[202:205], v[30:33]
	v_mfma_f32_16x16x32_bf16 v[22:25], v[134:137], v[210:213], v[22:25]
	v_mfma_f32_16x16x32_bf16 v[14:17], v[142:145], v[210:213], v[14:17]
	s_barrier
	s_add_u32 s74, s6, 0x40000
	s_addc_u32 s75, s7, 0
	s_add_i32 s76, s67, s49
	s_mov_b32 m0, s76
	s_nop 0
	global_load_lds_dwordx4 v148, s[74:75] sc0
	s_add_i32 m0, s76, 0x2000
	s_nop 0
	global_load_lds_dwordx4 v152, s[74:75] sc0
	s_waitcnt vmcnt(6)
	s_barrier
	v_mfma_f32_16x16x32_bf16 v[50:53], v[214:217], v[180:183], 0
	v_mfma_f32_16x16x32_bf16 v[42:45], v[222:225], v[180:183], 0
	v_mfma_f32_16x16x32_bf16 v[34:37], v[214:217], v[190:193], 0
	v_mfma_f32_16x16x32_bf16 v[26:29], v[222:225], v[190:193], 0
	v_mfma_f32_16x16x32_bf16 v[18:21], v[214:217], v[198:201], 0
	v_mfma_f32_16x16x32_bf16 v[10:13], v[222:225], v[198:201], 0
	v_mfma_f32_16x16x32_bf16 v[6:9], v[214:217], v[206:209], 0
	v_mfma_f32_16x16x32_bf16 v[2:5], v[222:225], v[206:209], 0
	v_mfma_f32_16x16x32_bf16 v[50:53], v[218:221], v[184:187], v[50:53]
	v_mfma_f32_16x16x32_bf16 v[42:45], v[226:229], v[184:187], v[42:45]
	v_mfma_f32_16x16x32_bf16 v[34:37], v[218:221], v[194:197], v[34:37]
	v_mfma_f32_16x16x32_bf16 v[26:29], v[226:229], v[194:197], v[26:29]
	v_mfma_f32_16x16x32_bf16 v[18:21], v[218:221], v[202:205], v[18:21]
	v_mfma_f32_16x16x32_bf16 v[10:13], v[226:229], v[202:205], v[10:13]
	v_mfma_f32_16x16x32_bf16 v[6:9], v[218:221], v[210:213], v[6:9]
	v_mfma_f32_16x16x32_bf16 v[2:5], v[226:229], v[210:213], v[2:5]
	s_barrier
	s_add_i32 s74, 0, 0x18000
	v_add_u32_e32 v142, s74, v171
	ds_read_b128 v[130:133], v142
	ds_read_b128 v[134:137], v142 offset:1024
	ds_read_b128 v[138:141], v142 offset:2048
	ds_read_b128 v[142:145], v142 offset:3072
	s_add_u32 s8, s8, 0x40000
	s_addc_u32 s9, s9, 0
	s_mov_b32 m0, s52
	ds_read_b128 v[180:183], v175 offset:32768
	ds_read_b128 v[184:187], v175 offset:33792
	ds_read_b128 v[190:193], v175 offset:34816
	ds_read_b128 v[194:197], v175 offset:35840
	ds_read_b128 v[198:201], v175 offset:36864
	ds_read_b128 v[202:205], v175 offset:37888
	ds_read_b128 v[206:209], v175 offset:38912
	ds_read_b128 v[210:213], v175 offset:39936
	global_load_lds_dwordx4 v146, s[8:9] sc0
	s_mov_b32 m0, s53
	s_nop 0
	global_load_lds_dwordx4 v150, s[8:9] sc0
	s_waitcnt lgkmcnt(8)
	s_barrier
	s_waitcnt lgkmcnt(0)
	v_mfma_f32_16x16x32_bf16 v[126:129], v[130:133], v[180:183], v[126:129]
	v_mfma_f32_16x16x32_bf16 v[122:125], v[138:141], v[180:183], v[122:125]
	v_mfma_f32_16x16x32_bf16 v[118:121], v[130:133], v[190:193], v[118:121]
	v_mfma_f32_16x16x32_bf16 v[110:113], v[138:141], v[190:193], v[110:113]
	v_mfma_f32_16x16x32_bf16 v[102:105], v[130:133], v[198:201], v[102:105]
	v_mfma_f32_16x16x32_bf16 v[94:97], v[138:141], v[198:201], v[94:97]
	v_mfma_f32_16x16x32_bf16 v[86:89], v[130:133], v[206:209], v[86:89]
	v_mfma_f32_16x16x32_bf16 v[78:81], v[138:141], v[206:209], v[78:81]
	v_mfma_f32_16x16x32_bf16 v[126:129], v[134:137], v[184:187], v[126:129]
	v_mfma_f32_16x16x32_bf16 v[122:125], v[142:145], v[184:187], v[122:125]
	v_mfma_f32_16x16x32_bf16 v[118:121], v[134:137], v[194:197], v[118:121]
	v_mfma_f32_16x16x32_bf16 v[110:113], v[142:145], v[194:197], v[110:113]
	v_mfma_f32_16x16x32_bf16 v[102:105], v[134:137], v[202:205], v[102:105]
	v_mfma_f32_16x16x32_bf16 v[94:97], v[142:145], v[202:205], v[94:97]
	v_mfma_f32_16x16x32_bf16 v[86:89], v[134:137], v[210:213], v[86:89]
	v_mfma_f32_16x16x32_bf16 v[78:81], v[142:145], v[210:213], v[78:81]
	s_barrier
	s_add_i32 s8, 0, 0x1c000
	s_add_i32 s9, s74, s49
	v_add_u32_e32 v154, s8, v171
	s_mov_b32 m0, s9
	ds_read_b128 v[214:217], v154
	ds_read_b128 v[218:221], v154 offset:1024
	ds_read_b128 v[222:225], v154 offset:2048
	ds_read_b128 v[226:229], v154 offset:3072
	global_load_lds_dwordx4 v148, s[98:99] sc0
	s_add_i32 m0, s9, 0x2000
	s_nop 0
	global_load_lds_dwordx4 v152, s[98:99] sc0
	s_barrier
	s_waitcnt lgkmcnt(0)
	v_mfma_f32_16x16x32_bf16 v[114:117], v[214:217], v[180:183], v[114:117]
	v_mfma_f32_16x16x32_bf16 v[106:109], v[222:225], v[180:183], v[106:109]
	v_mfma_f32_16x16x32_bf16 v[98:101], v[214:217], v[190:193], v[98:101]
	v_mfma_f32_16x16x32_bf16 v[90:93], v[222:225], v[190:193], v[90:93]
	v_mfma_f32_16x16x32_bf16 v[82:85], v[214:217], v[198:201], v[82:85]
	v_mfma_f32_16x16x32_bf16 v[74:77], v[222:225], v[198:201], v[74:77]
	v_mfma_f32_16x16x32_bf16 v[70:73], v[214:217], v[206:209], v[70:73]
	v_mfma_f32_16x16x32_bf16 v[66:69], v[222:225], v[206:209], v[66:69]
	v_mfma_f32_16x16x32_bf16 v[114:117], v[218:221], v[184:187], v[114:117]
	v_mfma_f32_16x16x32_bf16 v[106:109], v[226:229], v[184:187], v[106:109]
	v_mfma_f32_16x16x32_bf16 v[98:101], v[218:221], v[194:197], v[98:101]
	v_mfma_f32_16x16x32_bf16 v[90:93], v[226:229], v[194:197], v[90:93]
	v_mfma_f32_16x16x32_bf16 v[82:85], v[218:221], v[202:205], v[82:85]
	v_mfma_f32_16x16x32_bf16 v[74:77], v[226:229], v[202:205], v[74:77]
	v_mfma_f32_16x16x32_bf16 v[70:73], v[218:221], v[210:213], v[70:73]
	v_mfma_f32_16x16x32_bf16 v[66:69], v[226:229], v[210:213], v[66:69]
	s_barrier
	s_mov_b32 m0, s56
	ds_read_b128 v[180:183], v175 offset:49152
	ds_read_b128 v[184:187], v175 offset:50176
	ds_read_b128 v[190:193], v175 offset:51200
	ds_read_b128 v[194:197], v175 offset:52224
	ds_read_b128 v[198:201], v175 offset:53248
	ds_read_b128 v[202:205], v175 offset:54272
	ds_read_b128 v[206:209], v175 offset:55296
	ds_read_b128 v[210:213], v175 offset:56320
	global_load_lds_dwordx4 v146, s[100:101] sc0
	s_mov_b32 m0, s57
	s_nop 0
	global_load_lds_dwordx4 v150, s[100:101] sc0
	s_barrier
	s_waitcnt lgkmcnt(0)
	v_mfma_f32_16x16x32_bf16 v[62:65], v[130:133], v[180:183], v[62:65]
	v_mfma_f32_16x16x32_bf16 v[58:61], v[138:141], v[180:183], v[58:61]
	v_mfma_f32_16x16x32_bf16 v[54:57], v[130:133], v[190:193], v[54:57]
	v_mfma_f32_16x16x32_bf16 v[46:49], v[138:141], v[190:193], v[46:49]
	v_mfma_f32_16x16x32_bf16 v[38:41], v[130:133], v[198:201], v[38:41]
	v_mfma_f32_16x16x32_bf16 v[30:33], v[138:141], v[198:201], v[30:33]
	v_mfma_f32_16x16x32_bf16 v[22:25], v[130:133], v[206:209], v[22:25]
	v_mfma_f32_16x16x32_bf16 v[14:17], v[138:141], v[206:209], v[14:17]
	v_mfma_f32_16x16x32_bf16 v[62:65], v[134:137], v[184:187], v[62:65]
	v_mfma_f32_16x16x32_bf16 v[58:61], v[142:145], v[184:187], v[58:61]
	v_mfma_f32_16x16x32_bf16 v[54:57], v[134:137], v[194:197], v[54:57]
	v_mfma_f32_16x16x32_bf16 v[46:49], v[142:145], v[194:197], v[46:49]
	v_mfma_f32_16x16x32_bf16 v[38:41], v[134:137], v[202:205], v[38:41]
	v_mfma_f32_16x16x32_bf16 v[30:33], v[142:145], v[202:205], v[30:33]
	v_mfma_f32_16x16x32_bf16 v[22:25], v[134:137], v[210:213], v[22:25]
	v_mfma_f32_16x16x32_bf16 v[14:17], v[142:145], v[210:213], v[14:17]
	s_barrier
	s_add_u32 s6, s6, 0x40080
	s_addc_u32 s7, s7, 0
	s_add_i32 s8, s8, s49
	s_mov_b32 m0, s8
	s_nop 0
	global_load_lds_dwordx4 v148, s[6:7] sc0
	s_add_i32 m0, s8, 0x2000
	s_nop 0
	global_load_lds_dwordx4 v152, s[6:7] sc0
	s_add_i32 s73, s73, 2
	s_add_u32 s2, s2, 0x100
	s_addc_u32 s3, s3, 0
	s_add_u32 s71, s71, 0x100
	s_addc_u32 s72, s72, 0
	s_cmp_gt_u32 s73, 13
	s_waitcnt vmcnt(6)
	s_barrier
	v_mfma_f32_16x16x32_bf16 v[50:53], v[214:217], v[180:183], v[50:53]
	v_mfma_f32_16x16x32_bf16 v[42:45], v[222:225], v[180:183], v[42:45]
	v_mfma_f32_16x16x32_bf16 v[34:37], v[214:217], v[190:193], v[34:37]
	v_mfma_f32_16x16x32_bf16 v[26:29], v[222:225], v[190:193], v[26:29]
	v_mfma_f32_16x16x32_bf16 v[18:21], v[214:217], v[198:201], v[18:21]
	v_mfma_f32_16x16x32_bf16 v[10:13], v[222:225], v[198:201], v[10:13]
	v_mfma_f32_16x16x32_bf16 v[6:9], v[214:217], v[206:209], v[6:9]
	v_mfma_f32_16x16x32_bf16 v[2:5], v[222:225], v[206:209], v[2:5]
	v_mfma_f32_16x16x32_bf16 v[50:53], v[218:221], v[184:187], v[50:53]
	v_mfma_f32_16x16x32_bf16 v[42:45], v[226:229], v[184:187], v[42:45]
	v_mfma_f32_16x16x32_bf16 v[34:37], v[218:221], v[194:197], v[34:37]
	v_mfma_f32_16x16x32_bf16 v[26:29], v[226:229], v[194:197], v[26:29]
	v_mfma_f32_16x16x32_bf16 v[18:21], v[218:221], v[202:205], v[18:21]
	v_mfma_f32_16x16x32_bf16 v[10:13], v[226:229], v[202:205], v[10:13]
	v_mfma_f32_16x16x32_bf16 v[6:9], v[218:221], v[210:213], v[6:9]
	v_mfma_f32_16x16x32_bf16 v[2:5], v[226:229], v[210:213], v[2:5]
	s_barrier
	s_cbranch_scc1 .Lpeel_p1_exit
.LBB0_212:
	ds_read_b128 v[130:133], v173
	ds_read_b128 v[134:137], v173 offset:1024
	ds_read_b128 v[138:141], v173 offset:2048
	ds_read_b128 v[142:145], v173 offset:3072
	s_add_u32 s6, s2, 0xfffc0080
	s_addc_u32 s7, s3, -1
	s_cmp_eq_u32 s73, 12
	s_cselect_b32 s9, s1, s7
	s_cselect_b32 s8, s33, s6
	s_cselect_b32 s7, s39, s72
	s_cselect_b32 s6, s41, s71
	s_add_i32 m0, s50, 0xc000
	ds_read_b128 v[180:183], v175
	ds_read_b128 v[184:187], v175 offset:1024
	ds_read_b128 v[190:193], v175 offset:2048
	ds_read_b128 v[194:197], v175 offset:3072
	ds_read_b128 v[198:201], v175 offset:4096
	ds_read_b128 v[202:205], v175 offset:5120
	ds_read_b128 v[206:209], v175 offset:6144
	ds_read_b128 v[210:213], v175 offset:7168
	global_load_lds_dwordx4 v156, s[2:3] sc0
	s_add_i32 m0, s50, 0xe000
	s_nop 0
	global_load_lds_dwordx4 v158, s[2:3] sc0
	s_waitcnt lgkmcnt(8)
	s_barrier
	s_waitcnt lgkmcnt(0)
	v_mfma_f32_16x16x32_bf16 v[126:129], v[130:133], v[180:183], v[126:129]
	v_mfma_f32_16x16x32_bf16 v[122:125], v[138:141], v[180:183], v[122:125]
	v_mfma_f32_16x16x32_bf16 v[118:121], v[130:133], v[190:193], v[118:121]
	v_mfma_f32_16x16x32_bf16 v[110:113], v[138:141], v[190:193], v[110:113]
	v_mfma_f32_16x16x32_bf16 v[102:105], v[130:133], v[198:201], v[102:105]
	v_mfma_f32_16x16x32_bf16 v[94:97], v[138:141], v[198:201], v[94:97]
	v_mfma_f32_16x16x32_bf16 v[86:89], v[130:133], v[206:209], v[86:89]
	v_mfma_f32_16x16x32_bf16 v[78:81], v[138:141], v[206:209], v[78:81]
	v_mfma_f32_16x16x32_bf16 v[126:129], v[134:137], v[184:187], v[126:129]
	v_mfma_f32_16x16x32_bf16 v[122:125], v[142:145], v[184:187], v[122:125]
	v_mfma_f32_16x16x32_bf16 v[118:121], v[134:137], v[194:197], v[118:121]
	v_mfma_f32_16x16x32_bf16 v[110:113], v[142:145], v[194:197], v[110:113]
	v_mfma_f32_16x16x32_bf16 v[102:105], v[134:137], v[202:205], v[102:105]
	v_mfma_f32_16x16x32_bf16 v[94:97], v[142:145], v[202:205], v[94:97]
	v_mfma_f32_16x16x32_bf16 v[86:89], v[134:137], v[210:213], v[86:89]
	v_mfma_f32_16x16x32_bf16 v[78:81], v[142:145], v[210:213], v[78:81]
	s_barrier
	s_add_i32 s74, s66, s49
	s_add_u32 s98, s6, 0x80
	s_addc_u32 s99, s7, 0
	s_mov_b32 m0, s74
	ds_read_b128 v[214:217], v177
	ds_read_b128 v[218:221], v177 offset:1024
	ds_read_b128 v[222:225], v177 offset:2048
	ds_read_b128 v[226:229], v177 offset:3072
	global_load_lds_dwordx4 v148, s[6:7] sc0
	s_add_i32 m0, s74, 0x2000
	s_nop 0
	global_load_lds_dwordx4 v152, s[6:7] sc0
	s_barrier
	s_waitcnt lgkmcnt(0)
	v_mfma_f32_16x16x32_bf16 v[114:117], v[214:217], v[180:183], v[114:117]
	v_mfma_f32_16x16x32_bf16 v[106:109], v[222:225], v[180:183], v[106:109]
	v_mfma_f32_16x16x32_bf16 v[98:101], v[214:217], v[190:193], v[98:101]
	v_mfma_f32_16x16x32_bf16 v[90:93], v[222:225], v[190:193], v[90:93]
	v_mfma_f32_16x16x32_bf16 v[82:85], v[214:217], v[198:201], v[82:85]
	v_mfma_f32_16x16x32_bf16 v[74:77], v[222:225], v[198:201], v[74:77]
	v_mfma_f32_16x16x32_bf16 v[70:73], v[214:217], v[206:209], v[70:73]
	v_mfma_f32_16x16x32_bf16 v[66:69], v[222:225], v[206:209], v[66:69]
	v_mfma_f32_16x16x32_bf16 v[114:117], v[218:221], v[184:187], v[114:117]
	v_mfma_f32_16x16x32_bf16 v[106:109], v[226:229], v[184:187], v[106:109]
	v_mfma_f32_16x16x32_bf16 v[98:101], v[218:221], v[194:197], v[98:101]
	v_mfma_f32_16x16x32_bf16 v[90:93], v[226:229], v[194:197], v[90:93]
	v_mfma_f32_16x16x32_bf16 v[82:85], v[218:221], v[202:205], v[82:85]
	v_mfma_f32_16x16x32_bf16 v[74:77], v[226:229], v[202:205], v[74:77]
	v_mfma_f32_16x16x32_bf16 v[70:73], v[218:221], v[210:213], v[70:73]
	v_mfma_f32_16x16x32_bf16 v[66:69], v[226:229], v[210:213], v[66:69]
	s_barrier
	s_mov_b32 m0, s50
	s_add_u32 s100, s8, 0x80
	s_addc_u32 s101, s9, 0
	ds_read_b128 v[180:183], v175 offset:16384
	ds_read_b128 v[184:187], v175 offset:17408
	ds_read_b128 v[190:193], v175 offset:18432
	ds_read_b128 v[194:197], v175 offset:19456
	ds_read_b128 v[198:201], v175 offset:20480
	ds_read_b128 v[202:205], v175 offset:21504
	ds_read_b128 v[206:209], v175 offset:22528
	ds_read_b128 v[210:213], v175 offset:23552
	global_load_lds_dwordx4 v146, s[8:9] sc0
	s_mov_b32 m0, s51
	s_nop 0
	global_load_lds_dwordx4 v150, s[8:9] sc0
	s_barrier
	s_waitcnt lgkmcnt(0)
	v_mfma_f32_16x16x32_bf16 v[62:65], v[130:133], v[180:183], v[62:65]
	v_mfma_f32_16x16x32_bf16 v[58:61], v[138:141], v[180:183], v[58:61]
	v_mfma_f32_16x16x32_bf16 v[54:57], v[130:133], v[190:193], v[54:57]
	v_mfma_f32_16x16x32_bf16 v[46:49], v[138:141], v[190:193], v[46:49]
	v_mfma_f32_16x16x32_bf16 v[38:41], v[130:133], v[198:201], v[38:41]
	v_mfma_f32_16x16x32_bf16 v[30:33], v[138:141], v[198:201], v[30:33]
	v_mfma_f32_16x16x32_bf16 v[22:25], v[130:133], v[206:209], v[22:25]
	v_mfma_f32_16x16x32_bf16 v[14:17], v[138:141], v[206:209], v[14:17]
	v_mfma_f32_16x16x32_bf16 v[62:65], v[134:137], v[184:187], v[62:65]
	v_mfma_f32_16x16x32_bf16 v[58:61], v[142:145], v[184:187], v[58:61]
	v_mfma_f32_16x16x32_bf16 v[54:57], v[134:137], v[194:197], v[54:57]
	v_mfma_f32_16x16x32_bf16 v[46:49], v[142:145], v[194:197], v[46:49]
	v_mfma_f32_16x16x32_bf16 v[38:41], v[134:137], v[202:205], v[38:41]
	v_mfma_f32_16x16x32_bf16 v[30:33], v[142:145], v[202:205], v[30:33]
	v_mfma_f32_16x16x32_bf16 v[22:25], v[134:137], v[210:213], v[22:25]
	v_mfma_f32_16x16x32_bf16 v[14:17], v[142:145], v[210:213], v[14:17]
	s_barrier
	s_add_u32 s74, s6, 0x40000
	s_addc_u32 s75, s7, 0
	s_add_i32 s76, s67, s49
	s_mov_b32 m0, s76
	s_nop 0
	global_load_lds_dwordx4 v148, s[74:75] sc0
	s_add_i32 m0, s76, 0x2000
	s_nop 0
	global_load_lds_dwordx4 v152, s[74:75] sc0
	s_waitcnt vmcnt(6)
	s_barrier
	v_mfma_f32_16x16x32_bf16 v[50:53], v[214:217], v[180:183], v[50:53]
	v_mfma_f32_16x16x32_bf16 v[42:45], v[222:225], v[180:183], v[42:45]
	v_mfma_f32_16x16x32_bf16 v[34:37], v[214:217], v[190:193], v[34:37]
	v_mfma_f32_16x16x32_bf16 v[26:29], v[222:225], v[190:193], v[26:29]
	v_mfma_f32_16x16x32_bf16 v[18:21], v[214:217], v[198:201], v[18:21]
	v_mfma_f32_16x16x32_bf16 v[10:13], v[222:225], v[198:201], v[10:13]
	v_mfma_f32_16x16x32_bf16 v[6:9], v[214:217], v[206:209], v[6:9]
	v_mfma_f32_16x16x32_bf16 v[2:5], v[222:225], v[206:209], v[2:5]
	v_mfma_f32_16x16x32_bf16 v[50:53], v[218:221], v[184:187], v[50:53]
	v_mfma_f32_16x16x32_bf16 v[42:45], v[226:229], v[184:187], v[42:45]
	v_mfma_f32_16x16x32_bf16 v[34:37], v[218:221], v[194:197], v[34:37]
	v_mfma_f32_16x16x32_bf16 v[26:29], v[226:229], v[194:197], v[26:29]
	v_mfma_f32_16x16x32_bf16 v[18:21], v[218:221], v[202:205], v[18:21]
	v_mfma_f32_16x16x32_bf16 v[10:13], v[226:229], v[202:205], v[10:13]
	v_mfma_f32_16x16x32_bf16 v[6:9], v[218:221], v[210:213], v[6:9]
	v_mfma_f32_16x16x32_bf16 v[2:5], v[226:229], v[210:213], v[2:5]
	s_barrier
	s_add_i32 s74, 0, 0x18000
	v_add_u32_e32 v142, s74, v171
	ds_read_b128 v[130:133], v142
	ds_read_b128 v[134:137], v142 offset:1024
	ds_read_b128 v[138:141], v142 offset:2048
	ds_read_b128 v[142:145], v142 offset:3072
	s_add_u32 s8, s8, 0x40000
	s_addc_u32 s9, s9, 0
	s_mov_b32 m0, s52
	ds_read_b128 v[180:183], v175 offset:32768
	ds_read_b128 v[184:187], v175 offset:33792
	ds_read_b128 v[190:193], v175 offset:34816
	ds_read_b128 v[194:197], v175 offset:35840
	ds_read_b128 v[198:201], v175 offset:36864
	ds_read_b128 v[202:205], v175 offset:37888
	ds_read_b128 v[206:209], v175 offset:38912
	ds_read_b128 v[210:213], v175 offset:39936
	global_load_lds_dwordx4 v146, s[8:9] sc0
	s_mov_b32 m0, s53
	s_nop 0
	global_load_lds_dwordx4 v150, s[8:9] sc0
	s_waitcnt lgkmcnt(8)
	s_barrier
	s_waitcnt lgkmcnt(0)
	v_mfma_f32_16x16x32_bf16 v[126:129], v[130:133], v[180:183], v[126:129]
	v_mfma_f32_16x16x32_bf16 v[122:125], v[138:141], v[180:183], v[122:125]
	v_mfma_f32_16x16x32_bf16 v[118:121], v[130:133], v[190:193], v[118:121]
	v_mfma_f32_16x16x32_bf16 v[110:113], v[138:141], v[190:193], v[110:113]
	v_mfma_f32_16x16x32_bf16 v[102:105], v[130:133], v[198:201], v[102:105]
	v_mfma_f32_16x16x32_bf16 v[94:97], v[138:141], v[198:201], v[94:97]
	v_mfma_f32_16x16x32_bf16 v[86:89], v[130:133], v[206:209], v[86:89]
	v_mfma_f32_16x16x32_bf16 v[78:81], v[138:141], v[206:209], v[78:81]
	v_mfma_f32_16x16x32_bf16 v[126:129], v[134:137], v[184:187], v[126:129]
	v_mfma_f32_16x16x32_bf16 v[122:125], v[142:145], v[184:187], v[122:125]
	v_mfma_f32_16x16x32_bf16 v[118:121], v[134:137], v[194:197], v[118:121]
	v_mfma_f32_16x16x32_bf16 v[110:113], v[142:145], v[194:197], v[110:113]
	v_mfma_f32_16x16x32_bf16 v[102:105], v[134:137], v[202:205], v[102:105]
	v_mfma_f32_16x16x32_bf16 v[94:97], v[142:145], v[202:205], v[94:97]
	v_mfma_f32_16x16x32_bf16 v[86:89], v[134:137], v[210:213], v[86:89]
	v_mfma_f32_16x16x32_bf16 v[78:81], v[142:145], v[210:213], v[78:81]
	s_barrier
	s_add_i32 s8, 0, 0x1c000
	s_add_i32 s9, s74, s49
	v_add_u32_e32 v154, s8, v171
	s_mov_b32 m0, s9
	ds_read_b128 v[214:217], v154
	ds_read_b128 v[218:221], v154 offset:1024
	ds_read_b128 v[222:225], v154 offset:2048
	ds_read_b128 v[226:229], v154 offset:3072
	global_load_lds_dwordx4 v148, s[98:99] sc0
	s_add_i32 m0, s9, 0x2000
	s_nop 0
	global_load_lds_dwordx4 v152, s[98:99] sc0
	s_barrier
	s_waitcnt lgkmcnt(0)
	v_mfma_f32_16x16x32_bf16 v[114:117], v[214:217], v[180:183], v[114:117]
	v_mfma_f32_16x16x32_bf16 v[106:109], v[222:225], v[180:183], v[106:109]
	v_mfma_f32_16x16x32_bf16 v[98:101], v[214:217], v[190:193], v[98:101]
	v_mfma_f32_16x16x32_bf16 v[90:93], v[222:225], v[190:193], v[90:93]
	v_mfma_f32_16x16x32_bf16 v[82:85], v[214:217], v[198:201], v[82:85]
	v_mfma_f32_16x16x32_bf16 v[74:77], v[222:225], v[198:201], v[74:77]
	v_mfma_f32_16x16x32_bf16 v[70:73], v[214:217], v[206:209], v[70:73]
	v_mfma_f32_16x16x32_bf16 v[66:69], v[222:225], v[206:209], v[66:69]
	v_mfma_f32_16x16x32_bf16 v[114:117], v[218:221], v[184:187], v[114:117]
	v_mfma_f32_16x16x32_bf16 v[106:109], v[226:229], v[184:187], v[106:109]
	v_mfma_f32_16x16x32_bf16 v[98:101], v[218:221], v[194:197], v[98:101]
	v_mfma_f32_16x16x32_bf16 v[90:93], v[226:229], v[194:197], v[90:93]
	v_mfma_f32_16x16x32_bf16 v[82:85], v[218:221], v[202:205], v[82:85]
	v_mfma_f32_16x16x32_bf16 v[74:77], v[226:229], v[202:205], v[74:77]
	v_mfma_f32_16x16x32_bf16 v[70:73], v[218:221], v[210:213], v[70:73]
	v_mfma_f32_16x16x32_bf16 v[66:69], v[226:229], v[210:213], v[66:69]
	s_barrier
	s_mov_b32 m0, s56
	ds_read_b128 v[180:183], v175 offset:49152
	ds_read_b128 v[184:187], v175 offset:50176
	ds_read_b128 v[190:193], v175 offset:51200
	ds_read_b128 v[194:197], v175 offset:52224
	ds_read_b128 v[198:201], v175 offset:53248
	ds_read_b128 v[202:205], v175 offset:54272
	ds_read_b128 v[206:209], v175 offset:55296
	ds_read_b128 v[210:213], v175 offset:56320
	global_load_lds_dwordx4 v146, s[100:101] sc0
	s_mov_b32 m0, s57
	s_nop 0
	global_load_lds_dwordx4 v150, s[100:101] sc0
	s_barrier
	s_waitcnt lgkmcnt(0)
	v_mfma_f32_16x16x32_bf16 v[62:65], v[130:133], v[180:183], v[62:65]
	v_mfma_f32_16x16x32_bf16 v[58:61], v[138:141], v[180:183], v[58:61]
	v_mfma_f32_16x16x32_bf16 v[54:57], v[130:133], v[190:193], v[54:57]
	v_mfma_f32_16x16x32_bf16 v[46:49], v[138:141], v[190:193], v[46:49]
	v_mfma_f32_16x16x32_bf16 v[38:41], v[130:133], v[198:201], v[38:41]
	v_mfma_f32_16x16x32_bf16 v[30:33], v[138:141], v[198:201], v[30:33]
	v_mfma_f32_16x16x32_bf16 v[22:25], v[130:133], v[206:209], v[22:25]
	v_mfma_f32_16x16x32_bf16 v[14:17], v[138:141], v[206:209], v[14:17]
	v_mfma_f32_16x16x32_bf16 v[62:65], v[134:137], v[184:187], v[62:65]
	v_mfma_f32_16x16x32_bf16 v[58:61], v[142:145], v[184:187], v[58:61]
	v_mfma_f32_16x16x32_bf16 v[54:57], v[134:137], v[194:197], v[54:57]
	v_mfma_f32_16x16x32_bf16 v[46:49], v[142:145], v[194:197], v[46:49]
	v_mfma_f32_16x16x32_bf16 v[38:41], v[134:137], v[202:205], v[38:41]
	v_mfma_f32_16x16x32_bf16 v[30:33], v[142:145], v[202:205], v[30:33]
	v_mfma_f32_16x16x32_bf16 v[22:25], v[134:137], v[210:213], v[22:25]
	v_mfma_f32_16x16x32_bf16 v[14:17], v[142:145], v[210:213], v[14:17]
	s_barrier
	s_add_u32 s6, s6, 0x40080
	s_addc_u32 s7, s7, 0
	s_add_i32 s8, s8, s49
	s_mov_b32 m0, s8
	s_nop 0
	global_load_lds_dwordx4 v148, s[6:7] sc0
	s_add_i32 m0, s8, 0x2000
	s_nop 0
	global_load_lds_dwordx4 v152, s[6:7] sc0
	s_add_i32 s73, s73, 2
	s_add_u32 s2, s2, 0x100
	s_addc_u32 s3, s3, 0
	s_add_u32 s71, s71, 0x100
	s_addc_u32 s72, s72, 0
	s_cmp_gt_u32 s73, 13
	s_waitcnt vmcnt(6)
	s_barrier
	v_mfma_f32_16x16x32_bf16 v[50:53], v[214:217], v[180:183], v[50:53]
	v_mfma_f32_16x16x32_bf16 v[42:45], v[222:225], v[180:183], v[42:45]
	v_mfma_f32_16x16x32_bf16 v[34:37], v[214:217], v[190:193], v[34:37]
	v_mfma_f32_16x16x32_bf16 v[26:29], v[222:225], v[190:193], v[26:29]
	v_mfma_f32_16x16x32_bf16 v[18:21], v[214:217], v[198:201], v[18:21]
	v_mfma_f32_16x16x32_bf16 v[10:13], v[222:225], v[198:201], v[10:13]
	v_mfma_f32_16x16x32_bf16 v[6:9], v[214:217], v[206:209], v[6:9]
	v_mfma_f32_16x16x32_bf16 v[2:5], v[222:225], v[206:209], v[2:5]
	v_mfma_f32_16x16x32_bf16 v[50:53], v[218:221], v[184:187], v[50:53]
	v_mfma_f32_16x16x32_bf16 v[42:45], v[226:229], v[184:187], v[42:45]
	v_mfma_f32_16x16x32_bf16 v[34:37], v[218:221], v[194:197], v[34:37]
	v_mfma_f32_16x16x32_bf16 v[26:29], v[226:229], v[194:197], v[26:29]
	v_mfma_f32_16x16x32_bf16 v[18:21], v[218:221], v[202:205], v[18:21]
	v_mfma_f32_16x16x32_bf16 v[10:13], v[226:229], v[202:205], v[10:13]
	v_mfma_f32_16x16x32_bf16 v[6:9], v[218:221], v[210:213], v[6:9]
	v_mfma_f32_16x16x32_bf16 v[2:5], v[226:229], v[210:213], v[2:5]
	s_barrier
	s_cbranch_scc0 .LBB0_212

.LBB0_924:
	s_ashr_i32 s0, s6, 3
	s_add_i32 s0, s7, s0
	s_ashr_i32 s7, s0, 31
	s_lshr_b32 s7, s7, 27
	s_add_i32 s7, s0, s7
	s_ashr_i32 s8, s7, 5
	s_andn2_b32 s7, s7, 31
	s_sub_i32 s7, s0, s7
	s_bfe_i32 s0, s7, 0x80000
	s_bfe_u32 s0, s0, 0x3000c
	s_add_i32 s9, s7, s0
	s_bfe_i32 s0, s9, 0x80000
	s_and_b32 s9, s9, 0xf8
	v_lshlrev_b32_e32 v6, 1, v5
	v_lshrrev_b32_e32 v7, 5, v0
	s_sub_i32 s7, s7, s9
	v_and_b32_e32 v6, 24, v6
	v_and_b32_e32 v7, 4, v7
	v_and_b32_e32 v5, 3, v5
	s_lshl_b32 s8, s8, 3
	s_sext_i32_i16 s0, s0
	s_sext_i32_i8 s7, s7
	s_lshr_b32 s1, s42, 8
	v_or3_b32 v5, v7, v5, v6
	s_movk_i32 s6, 0x60
	s_lshr_b32 s0, s0, 3
	s_add_i32 s28, s8, s7
	v_and_or_b32 v4, v4, s6, v5
	s_lshr_b32 s6, s42, 6
	s_ashr_i32 s29, s28, 31
	s_bfe_i64 s[10:11], s[0:1], 0x100000
	s_lshl_b32 s43, s6, 10
	s_lshl_b64 s[8:9], s[28:29], 20
	s_lshl_b64 s[10:11], s[10:11], 20
	s_add_u32 s34, s40, s10
	v_and_or_b32 v6, v179, 32, v5
	s_addc_u32 s35, s41, s11
	s_add_i32 s29, s43, 0
	v_lshl_or_b32 v174, v6, 12, v2
	s_add_i32 m0, s29, 0x10000
	v_lshl_or_b32 v176, v4, 12, v2
	global_load_lds_dwordx4 v174, s[34:35] sc0
	s_add_i32 m0, s29, 0x12000
	s_add_u32 s30, s4, s8
	global_load_lds_dwordx4 v176, s[34:35] sc0
	s_addc_u32 s31, s5, s9
	s_mov_b32 m0, s29
	s_add_i32 s44, s29, 0x2000
	global_load_lds_dwordx4 v170, s[30:31] sc0
	s_mov_b32 m0, s44
	s_add_u32 s8, s34, 0x80000
	global_load_lds_dwordx4 v172, s[30:31] sc0
	s_addc_u32 s9, s35, 0
	s_add_i32 m0, s29, 0x14000
	v_mov_b32_e32 v2, 0
	global_load_lds_dwordx4 v174, s[8:9] sc0
	s_add_i32 m0, s29, 0x16000
	v_mov_b32_e32 v175, v2
	global_load_lds_dwordx4 v176, s[8:9] sc0
	s_add_u32 s8, s30, 0x80000
	s_addc_u32 s9, s31, 0
	s_add_i32 s45, s29, 0x4000
	s_mov_b32 m0, s45
	s_add_i32 s46, s29, 0x6000
	global_load_lds_dwordx4 v170, s[8:9] sc0
	s_mov_b32 m0, s46
	v_mov_b32_e32 v177, v2
	global_load_lds_dwordx4 v172, s[8:9] sc0
	v_mov_b32_e32 v171, v2
	v_mov_b32_e32 v173, v2
	s_mov_b32 s7, 0
	s_mov_b32 s47, 0x10000
	v_lshl_add_u64 v[10:11], s[34:35], 0, v[174:175]
	v_lshl_add_u64 v[8:9], s[34:35], 0, v[176:177]
	v_lshl_add_u64 v[6:7], s[30:31], 0, v[170:171]
	s_cmp_lg_u32 s1, 1
	v_lshl_add_u64 v[4:5], s[30:31], 0, v[172:173]
	s_cbranch_scc1 .LBB0_926
	s_barrier
.LBB0_926:
	s_add_u32 s8, s94, 0xbf0cc00
	s_mov_b64 s[10:11], 0x80
	s_addc_u32 s9, s95, 0
	s_lshl_b32 s6, s6, 5
	s_add_i32 m0, s29, 0x18000
	v_lshl_add_u64 v[10:11], v[10:11], 0, s[10:11]
	s_lshl_b32 s48, s1, 6
	s_lshl_b32 s14, s1, 13
	s_and_b32 s6, s6, 0x60
	s_waitcnt vmcnt(4)
	s_barrier
	global_load_lds_dwordx4 v[10:11], off sc0
	v_lshl_add_u64 v[8:9], v[8:9], 0, s[10:11]
	s_add_i32 m0, s29, 0x1a000
	s_add_i32 s49, s29, 0x8000
	s_add_i32 s50, s29, 0xa000
	global_load_lds_dwordx4 v[8:9], off sc0
	v_lshl_add_u64 v[6:7], v[6:7], 0, s[10:11]
	s_mov_b32 m0, s49
	s_add_u32 s12, s34, 0x80080
	global_load_lds_dwordx4 v[6:7], off sc0
	v_lshl_add_u64 v[4:5], v[4:5], 0, s[10:11]
	s_mov_b32 m0, s50
	s_addc_u32 s13, s35, 0
	global_load_lds_dwordx4 v[4:5], off sc0
	s_add_i32 m0, s29, 0x1c000
	v_lshl_add_u64 v[4:5], s[12:13], 0, v[174:175]
	global_load_lds_dwordx4 v[4:5], off sc0
	v_lshl_add_u64 v[4:5], s[12:13], 0, v[176:177]
	s_add_i32 m0, s29, 0x1e000
	s_sext_i32_i8 s61, s0
	global_load_lds_dwordx4 v[4:5], off sc0
	v_lshlrev_b32_e32 v5, 2, v178
	v_lshl_or_b32 v4, v178, 6, v204
	v_and_b32_e32 v6, 32, v5
	v_bitop3_b32 v6, v4, s14, v6 bitop3:0xde
	s_lshl_b32 s0, s1, 8
	v_lshlrev_b32_e32 v4, 9, v0
	s_add_i32 s0, s0, 0
	v_and_b32_e32 v4, 0x30000, v4
	v_lshlrev_b32_e32 v7, 12, v13
	s_add_i32 s0, s0, 0x20010
	v_or3_b32 v4, v3, v4, v7
	s_mov_b64 s[12:13], 0x80080
	v_add_u32_e32 v183, s0, v5
	v_add_u32_e32 v4, v4, v12
	v_mov_b32_e32 v5, v2
	v_lshl_add_u64 v[184:185], v[4:5], 0, s[12:13]
	v_lshlrev_b32_e32 v4, 5, v14
	v_and_b32_e32 v4, 0x70000, v4
	s_waitcnt vmcnt(6)
	v_or3_b32 v3, v3, v4, v7
	v_add_u32_e32 v4, v3, v12
	v_lshl_or_b32 v181, s6, 7, v1
	v_lshl_add_u64 v[186:187], v[4:5], 0, s[12:13]
	v_mov_b64_e32 v[188:189], 0x100
	v_mov_b64_e32 v[190:191], 0xff
	s_add_i32 s51, 0, 0x10000
	v_add_u32_e32 v194, 0, v6
	s_add_i32 s52, 0, 0x14000
	s_mov_b32 s53, 0xa0000
	s_mov_b64 s[12:13], 0xa0000
	s_mov_b64 s[14:15], 0x90200
	s_mov_b32 s54, 0x90000
	s_mov_b64 s[16:17], 0x90000
	s_mov_b64 s[18:19], 0x80200
	s_mov_b32 s55, 0x80000
	s_mov_b32 s56, 0x40000
	s_mov_b32 s57, 0x48000
	s_mov_b32 s58, 0x50000
	s_mov_b32 s59, 0x58000
	s_mov_b32 s60, s7
	s_barrier
	s_branch .LBB0_928

.LBB0_940:
	s_add_u32 s36, s30, s34
	v_add_u32_e32 v3, s51, v181
	s_addc_u32 s37, s31, s35
	ds_read_b128 v[138:141], v3
	ds_read_b128 v[142:145], v3 offset:1024
	ds_read_b128 v[146:149], v3 offset:2048
	ds_read_b128 v[150:153], v3 offset:3072
	s_add_u32 s36, s36, 0x100
	s_addc_u32 s37, s37, 0
	s_add_u32 s67, s64, s34
	s_addc_u32 s68, s65, s35
	s_cmpk_eq_i32 s34, 0xf00
	s_cselect_b32 s38, s62, s36
	s_cselect_b32 s36, s63, s67
	s_cselect_b32 s39, s23, s37
	s_cselect_b32 s37, s21, s68
	v_lshl_add_u64 v[4:5], v[134:135], 0, s[34:35]
	s_add_i32 m0, s29, 0xc000
	ds_read_b128 v[154:157], v194
	ds_read_b128 v[158:161], v194 offset:1024
	ds_read_b128 v[162:165], v194 offset:2048
	ds_read_b128 v[166:169], v194 offset:3072
	ds_read_b128 v[196:199], v194 offset:4096
	ds_read_b128 v[200:203], v194 offset:5120
	ds_read_b128 v[206:209], v194 offset:6144
	ds_read_b128 v[212:215], v194 offset:7168
	global_load_lds_dwordx4 v[4:5], off sc0
	v_lshl_add_u64 v[4:5], v[136:137], 0, s[34:35]
	s_add_i32 m0, s29, 0xe000
	s_nop 0
	global_load_lds_dwordx4 v[4:5], off sc0
	s_waitcnt lgkmcnt(8)
	s_barrier
	s_waitcnt lgkmcnt(0)
	v_mfma_f32_16x16x32_bf16 v[130:133], v[138:141], v[154:157], v[130:133]
	v_mfma_f32_16x16x32_bf16 v[126:129], v[146:149], v[154:157], v[126:129]
	v_mfma_f32_16x16x32_bf16 v[114:117], v[138:141], v[162:165], v[114:117]
	v_mfma_f32_16x16x32_bf16 v[110:113], v[146:149], v[162:165], v[110:113]
	v_mfma_f32_16x16x32_bf16 v[98:101], v[138:141], v[196:199], v[98:101]
	v_mfma_f32_16x16x32_bf16 v[94:97], v[146:149], v[196:199], v[94:97]
	v_mfma_f32_16x16x32_bf16 v[82:85], v[138:141], v[206:209], v[82:85]
	v_mfma_f32_16x16x32_bf16 v[78:81], v[146:149], v[206:209], v[78:81]
	v_mfma_f32_16x16x32_bf16 v[130:133], v[142:145], v[158:161], v[130:133]
	v_mfma_f32_16x16x32_bf16 v[126:129], v[150:153], v[158:161], v[126:129]
	v_mfma_f32_16x16x32_bf16 v[114:117], v[142:145], v[166:169], v[114:117]
	v_mfma_f32_16x16x32_bf16 v[110:113], v[150:153], v[166:169], v[110:113]
	v_mfma_f32_16x16x32_bf16 v[98:101], v[142:145], v[200:203], v[98:101]
	v_mfma_f32_16x16x32_bf16 v[94:97], v[150:153], v[200:203], v[94:97]
	v_mfma_f32_16x16x32_bf16 v[82:85], v[142:145], v[212:215], v[82:85]
	v_mfma_f32_16x16x32_bf16 v[78:81], v[150:153], v[212:215], v[78:81]
	s_barrier
	s_add_i32 s67, s51, s43
	v_add_u32_e32 v3, s52, v181
	v_lshl_add_u64 v[192:193], s[36:37], 0, v[174:175]
	s_mov_b32 m0, s67
	ds_read_b128 v[216:219], v3
	ds_read_b128 v[220:223], v3 offset:1024
	ds_read_b128 v[224:227], v3 offset:2048
	ds_read_b128 v[228:231], v3 offset:3072
	global_load_lds_dwordx4 v[192:193], off sc0
	v_lshl_add_u64 v[232:233], s[36:37], 0, v[176:177]
	s_add_i32 m0, s67, 0x2000
	s_nop 0
	global_load_lds_dwordx4 v[232:233], off sc0
	s_barrier
	s_waitcnt lgkmcnt(0)
	v_mfma_f32_16x16x32_bf16 v[122:125], v[216:219], v[154:157], v[122:125]
	v_mfma_f32_16x16x32_bf16 v[118:121], v[224:227], v[154:157], v[118:121]
	v_mfma_f32_16x16x32_bf16 v[106:109], v[216:219], v[162:165], v[106:109]
	v_mfma_f32_16x16x32_bf16 v[102:105], v[224:227], v[162:165], v[102:105]
	v_mfma_f32_16x16x32_bf16 v[90:93], v[216:219], v[196:199], v[90:93]
	v_mfma_f32_16x16x32_bf16 v[86:89], v[224:227], v[196:199], v[86:89]
	v_mfma_f32_16x16x32_bf16 v[74:77], v[216:219], v[206:209], v[74:77]
	v_mfma_f32_16x16x32_bf16 v[70:73], v[224:227], v[206:209], v[70:73]
	v_mfma_f32_16x16x32_bf16 v[122:125], v[220:223], v[158:161], v[122:125]
	v_mfma_f32_16x16x32_bf16 v[118:121], v[228:231], v[158:161], v[118:121]
	v_mfma_f32_16x16x32_bf16 v[106:109], v[220:223], v[166:169], v[106:109]
	v_mfma_f32_16x16x32_bf16 v[102:105], v[228:231], v[166:169], v[102:105]
	v_mfma_f32_16x16x32_bf16 v[90:93], v[220:223], v[200:203], v[90:93]
	v_mfma_f32_16x16x32_bf16 v[86:89], v[228:231], v[200:203], v[86:89]
	v_mfma_f32_16x16x32_bf16 v[74:77], v[220:223], v[212:215], v[74:77]
	v_mfma_f32_16x16x32_bf16 v[70:73], v[228:231], v[212:215], v[70:73]
	s_mov_b32 m0, s29
	v_lshl_add_u64 v[234:235], s[38:39], 0, v[170:171]
	s_barrier
	ds_read_b128 v[154:157], v194 offset:16384
	ds_read_b128 v[158:161], v194 offset:17408
	ds_read_b128 v[162:165], v194 offset:18432
	ds_read_b128 v[166:169], v194 offset:19456
	ds_read_b128 v[196:199], v194 offset:20480
	ds_read_b128 v[200:203], v194 offset:21504
	ds_read_b128 v[206:209], v194 offset:22528
	ds_read_b128 v[212:215], v194 offset:23552
	global_load_lds_dwordx4 v[234:235], off sc0
	v_lshl_add_u64 v[236:237], s[38:39], 0, v[172:173]
	s_mov_b32 m0, s44
	s_nop 0
	global_load_lds_dwordx4 v[236:237], off sc0
	s_barrier
	s_waitcnt lgkmcnt(0)
	v_mfma_f32_16x16x32_bf16 v[66:69], v[138:141], v[154:157], v[66:69]
	v_mfma_f32_16x16x32_bf16 v[62:65], v[146:149], v[154:157], v[62:65]
	v_mfma_f32_16x16x32_bf16 v[50:53], v[138:141], v[162:165], v[50:53]
	v_mfma_f32_16x16x32_bf16 v[46:49], v[146:149], v[162:165], v[46:49]
	v_mfma_f32_16x16x32_bf16 v[34:37], v[138:141], v[196:199], v[34:37]
	v_mfma_f32_16x16x32_bf16 v[30:33], v[146:149], v[196:199], v[30:33]
	v_mfma_f32_16x16x32_bf16 v[18:21], v[138:141], v[206:209], v[18:21]
	v_mfma_f32_16x16x32_bf16 v[14:17], v[146:149], v[206:209], v[14:17]
	v_mfma_f32_16x16x32_bf16 v[66:69], v[142:145], v[158:161], v[66:69]
	v_mfma_f32_16x16x32_bf16 v[62:65], v[150:153], v[158:161], v[62:65]
	v_mfma_f32_16x16x32_bf16 v[50:53], v[142:145], v[166:169], v[50:53]
	v_mfma_f32_16x16x32_bf16 v[46:49], v[150:153], v[166:169], v[46:49]
	v_mfma_f32_16x16x32_bf16 v[34:37], v[142:145], v[200:203], v[34:37]
	v_mfma_f32_16x16x32_bf16 v[30:33], v[150:153], v[200:203], v[30:33]
	v_mfma_f32_16x16x32_bf16 v[18:21], v[142:145], v[212:215], v[18:21]
	v_mfma_f32_16x16x32_bf16 v[14:17], v[150:153], v[212:215], v[14:17]
	s_barrier
	s_add_u32 s68, s36, 0x80000
	s_addc_u32 s69, s37, 0
	s_add_i32 s67, s52, s43
	v_lshl_add_u64 v[4:5], s[68:69], 0, v[174:175]
	s_mov_b32 m0, s67
	s_nop 0
	global_load_lds_dwordx4 v[4:5], off sc0
	v_lshl_add_u64 v[4:5], s[68:69], 0, v[176:177]
	s_add_i32 m0, s67, 0x2000
	s_nop 0
	global_load_lds_dwordx4 v[4:5], off sc0
	s_waitcnt vmcnt(6)
	s_barrier
	v_mfma_f32_16x16x32_bf16 v[58:61], v[216:219], v[154:157], v[58:61]
	v_mfma_f32_16x16x32_bf16 v[54:57], v[224:227], v[154:157], v[54:57]
	v_mfma_f32_16x16x32_bf16 v[42:45], v[216:219], v[162:165], v[42:45]
	v_mfma_f32_16x16x32_bf16 v[38:41], v[224:227], v[162:165], v[38:41]
	v_mfma_f32_16x16x32_bf16 v[26:29], v[216:219], v[196:199], v[26:29]
	v_mfma_f32_16x16x32_bf16 v[22:25], v[224:227], v[196:199], v[22:25]
	v_mfma_f32_16x16x32_bf16 v[10:13], v[216:219], v[206:209], v[10:13]
	v_mfma_f32_16x16x32_bf16 v[4:7], v[224:227], v[206:209], v[6:9]
	v_mfma_f32_16x16x32_bf16 v[58:61], v[220:223], v[158:161], v[58:61]
	v_mfma_f32_16x16x32_bf16 v[54:57], v[228:231], v[158:161], v[54:57]
	v_mfma_f32_16x16x32_bf16 v[42:45], v[220:223], v[166:169], v[42:45]
	v_mfma_f32_16x16x32_bf16 v[38:41], v[228:231], v[166:169], v[38:41]
	v_mfma_f32_16x16x32_bf16 v[26:29], v[220:223], v[200:203], v[26:29]
	v_mfma_f32_16x16x32_bf16 v[22:25], v[228:231], v[200:203], v[22:25]
	v_mfma_f32_16x16x32_bf16 v[10:13], v[220:223], v[212:215], v[10:13]
	v_mfma_f32_16x16x32_bf16 v[4:7], v[228:231], v[212:215], v[4:7]
	s_add_i32 s67, 0, 0x18000
	v_add_u32_e32 v3, s67, v181
	s_barrier
	ds_read_b128 v[138:141], v3
	ds_read_b128 v[142:145], v3 offset:1024
	ds_read_b128 v[146:149], v3 offset:2048
	ds_read_b128 v[150:153], v3 offset:3072
	s_add_u32 s38, s38, 0x80000
	s_addc_u32 s39, s39, 0
	s_mov_b32 m0, s45
	v_lshl_add_u64 v[8:9], s[38:39], 0, v[170:171]
	ds_read_b128 v[154:157], v194 offset:32768
	ds_read_b128 v[158:161], v194 offset:33792
	ds_read_b128 v[162:165], v194 offset:34816
	ds_read_b128 v[166:169], v194 offset:35840
	ds_read_b128 v[196:199], v194 offset:36864
	ds_read_b128 v[200:203], v194 offset:37888
	ds_read_b128 v[206:209], v194 offset:38912
	ds_read_b128 v[212:215], v194 offset:39936
	global_load_lds_dwordx4 v[8:9], off sc0
	v_lshl_add_u64 v[8:9], s[38:39], 0, v[172:173]
	s_mov_b32 m0, s46
	s_nop 0
	global_load_lds_dwordx4 v[8:9], off sc0
	s_waitcnt lgkmcnt(8)
	s_barrier
	s_waitcnt lgkmcnt(0)
	v_mfma_f32_16x16x32_bf16 v[130:133], v[138:141], v[154:157], v[130:133]
	v_mfma_f32_16x16x32_bf16 v[126:129], v[146:149], v[154:157], v[126:129]
	v_mfma_f32_16x16x32_bf16 v[114:117], v[138:141], v[162:165], v[114:117]
	v_mfma_f32_16x16x32_bf16 v[110:113], v[146:149], v[162:165], v[110:113]
	v_mfma_f32_16x16x32_bf16 v[98:101], v[138:141], v[196:199], v[98:101]
	v_mfma_f32_16x16x32_bf16 v[94:97], v[146:149], v[196:199], v[94:97]
	v_mfma_f32_16x16x32_bf16 v[82:85], v[138:141], v[206:209], v[82:85]
	v_mfma_f32_16x16x32_bf16 v[78:81], v[146:149], v[206:209], v[78:81]
	v_mfma_f32_16x16x32_bf16 v[130:133], v[142:145], v[158:161], v[130:133]
	v_mfma_f32_16x16x32_bf16 v[126:129], v[150:153], v[158:161], v[126:129]
	v_mfma_f32_16x16x32_bf16 v[114:117], v[142:145], v[166:169], v[114:117]
	v_mfma_f32_16x16x32_bf16 v[110:113], v[150:153], v[166:169], v[110:113]
	v_mfma_f32_16x16x32_bf16 v[98:101], v[142:145], v[200:203], v[98:101]
	v_mfma_f32_16x16x32_bf16 v[94:97], v[150:153], v[200:203], v[94:97]
	v_mfma_f32_16x16x32_bf16 v[82:85], v[142:145], v[212:215], v[82:85]
	v_mfma_f32_16x16x32_bf16 v[78:81], v[150:153], v[212:215], v[78:81]
	s_barrier
	s_add_i32 s38, 0, 0x1c000
	s_add_i32 s39, s67, s43
	v_add_u32_e32 v3, s38, v181
	v_lshl_add_u64 v[8:9], v[192:193], 0, s[10:11]
	s_mov_b32 m0, s39
	ds_read_b128 v[216:219], v3
	ds_read_b128 v[220:223], v3 offset:1024
	ds_read_b128 v[224:227], v3 offset:2048
	ds_read_b128 v[228:231], v3 offset:3072
	global_load_lds_dwordx4 v[8:9], off sc0
	v_lshl_add_u64 v[8:9], v[232:233], 0, s[10:11]
	s_add_i32 m0, s39, 0x2000
	s_nop 0
	global_load_lds_dwordx4 v[8:9], off sc0
	s_barrier
	s_waitcnt lgkmcnt(0)
	v_mfma_f32_16x16x32_bf16 v[122:125], v[216:219], v[154:157], v[122:125]
	v_mfma_f32_16x16x32_bf16 v[118:121], v[224:227], v[154:157], v[118:121]
	v_mfma_f32_16x16x32_bf16 v[106:109], v[216:219], v[162:165], v[106:109]
	v_mfma_f32_16x16x32_bf16 v[102:105], v[224:227], v[162:165], v[102:105]
	v_mfma_f32_16x16x32_bf16 v[90:93], v[216:219], v[196:199], v[90:93]
	v_mfma_f32_16x16x32_bf16 v[86:89], v[224:227], v[196:199], v[86:89]
	v_mfma_f32_16x16x32_bf16 v[74:77], v[216:219], v[206:209], v[74:77]
	v_mfma_f32_16x16x32_bf16 v[70:73], v[224:227], v[206:209], v[70:73]
	v_mfma_f32_16x16x32_bf16 v[122:125], v[220:223], v[158:161], v[122:125]
	v_mfma_f32_16x16x32_bf16 v[118:121], v[228:231], v[158:161], v[118:121]
	v_mfma_f32_16x16x32_bf16 v[106:109], v[220:223], v[166:169], v[106:109]
	v_mfma_f32_16x16x32_bf16 v[102:105], v[228:231], v[166:169], v[102:105]
	v_mfma_f32_16x16x32_bf16 v[90:93], v[220:223], v[200:203], v[90:93]
	v_mfma_f32_16x16x32_bf16 v[86:89], v[228:231], v[200:203], v[86:89]
	v_mfma_f32_16x16x32_bf16 v[74:77], v[220:223], v[212:215], v[74:77]
	v_mfma_f32_16x16x32_bf16 v[70:73], v[228:231], v[212:215], v[70:73]
	s_mov_b32 m0, s49
	v_lshl_add_u64 v[8:9], v[234:235], 0, s[10:11]
	s_barrier
	ds_read_b128 v[154:157], v194 offset:49152
	ds_read_b128 v[158:161], v194 offset:50176
	ds_read_b128 v[162:165], v194 offset:51200
	ds_read_b128 v[166:169], v194 offset:52224
	ds_read_b128 v[196:199], v194 offset:53248
	ds_read_b128 v[200:203], v194 offset:54272
	ds_read_b128 v[206:209], v194 offset:55296
	ds_read_b128 v[212:215], v194 offset:56320
	global_load_lds_dwordx4 v[8:9], off sc0
	v_lshl_add_u64 v[8:9], v[236:237], 0, s[10:11]
	s_mov_b32 m0, s50
	s_nop 0
	global_load_lds_dwordx4 v[8:9], off sc0
	s_barrier
	s_waitcnt lgkmcnt(0)
	v_mfma_f32_16x16x32_bf16 v[66:69], v[138:141], v[154:157], v[66:69]
	v_mfma_f32_16x16x32_bf16 v[62:65], v[146:149], v[154:157], v[62:65]
	v_mfma_f32_16x16x32_bf16 v[50:53], v[138:141], v[162:165], v[50:53]
	v_mfma_f32_16x16x32_bf16 v[46:49], v[146:149], v[162:165], v[46:49]
	v_mfma_f32_16x16x32_bf16 v[34:37], v[138:141], v[196:199], v[34:37]
	v_mfma_f32_16x16x32_bf16 v[30:33], v[146:149], v[196:199], v[30:33]
	v_mfma_f32_16x16x32_bf16 v[18:21], v[138:141], v[206:209], v[18:21]
	v_mfma_f32_16x16x32_bf16 v[14:17], v[146:149], v[206:209], v[14:17]
	v_mfma_f32_16x16x32_bf16 v[66:69], v[142:145], v[158:161], v[66:69]
	v_mfma_f32_16x16x32_bf16 v[62:65], v[150:153], v[158:161], v[62:65]
	v_mfma_f32_16x16x32_bf16 v[50:53], v[142:145], v[166:169], v[50:53]
	v_mfma_f32_16x16x32_bf16 v[46:49], v[150:153], v[166:169], v[46:49]
	v_mfma_f32_16x16x32_bf16 v[34:37], v[142:145], v[200:203], v[34:37]
	v_mfma_f32_16x16x32_bf16 v[30:33], v[150:153], v[200:203], v[30:33]
	v_mfma_f32_16x16x32_bf16 v[18:21], v[142:145], v[212:215], v[18:21]
	v_mfma_f32_16x16x32_bf16 v[14:17], v[150:153], v[212:215], v[14:17]
	s_barrier
	s_add_u32 s36, s36, 0x80080
	s_addc_u32 s37, s37, 0
	s_add_i32 s38, s38, s43
	v_lshl_add_u64 v[8:9], s[36:37], 0, v[174:175]
	s_mov_b32 m0, s38
	s_nop 0
	global_load_lds_dwordx4 v[8:9], off sc0
	v_lshl_add_u64 v[8:9], s[36:37], 0, v[176:177]
	s_add_i32 m0, s38, 0x2000
	s_nop 0
	global_load_lds_dwordx4 v[8:9], off sc0
	s_waitcnt vmcnt(6)
	s_barrier
	v_mfma_f32_16x16x32_bf16 v[58:61], v[216:219], v[154:157], v[58:61]
	v_mfma_f32_16x16x32_bf16 v[54:57], v[224:227], v[154:157], v[54:57]
	v_mfma_f32_16x16x32_bf16 v[42:45], v[216:219], v[162:165], v[42:45]
	v_mfma_f32_16x16x32_bf16 v[38:41], v[224:227], v[162:165], v[38:41]
	v_mfma_f32_16x16x32_bf16 v[26:29], v[216:219], v[196:199], v[26:29]
	v_mfma_f32_16x16x32_bf16 v[22:25], v[224:227], v[196:199], v[22:25]
	v_mfma_f32_16x16x32_bf16 v[8:11], v[216:219], v[206:209], v[10:13]
	v_mfma_f32_16x16x32_bf16 v[4:7], v[224:227], v[206:209], v[4:7]
	v_mfma_f32_16x16x32_bf16 v[58:61], v[220:223], v[158:161], v[58:61]
	v_mfma_f32_16x16x32_bf16 v[54:57], v[228:231], v[158:161], v[54:57]
	v_mfma_f32_16x16x32_bf16 v[42:45], v[220:223], v[166:169], v[42:45]
	v_mfma_f32_16x16x32_bf16 v[38:41], v[228:231], v[166:169], v[38:41]
	v_mfma_f32_16x16x32_bf16 v[26:29], v[220:223], v[200:203], v[26:29]
	v_mfma_f32_16x16x32_bf16 v[22:25], v[228:231], v[200:203], v[22:25]
	v_mfma_f32_16x16x32_bf16 v[10:13], v[220:223], v[212:215], v[8:11]
	v_mfma_f32_16x16x32_bf16 v[6:9], v[228:231], v[212:215], v[4:7]
	s_add_i32 s36, s66, 2
	s_add_u32 s34, s34, 0x100
	s_addc_u32 s35, s35, 0
	s_cmp_gt_u32 s66, 29
	s_barrier
	s_cbranch_scc1 .LBB0_927
	s_mov_b32 s66, s36
	s_cmp_lt_i32 s66, 16
	s_cbranch_scc1 .LBB0_936
	s_branch .LBB0_935

.LBB0_945:
	s_cmp_gt_i32 s82, 31
	v_readfirstlane_b32 s6, v0
	s_cbranch_scc1 .LBB0_951
	s_lshl_b32 s0, s82, 6
	s_and_b32 s0, s0, 0xffffff00
	s_lshr_b32 s8, s6, 6
	s_and_b32 s7, s82, 3
	s_ashr_i32 s1, s0, 31
	s_lshr_b32 s20, s6, 8
	s_lshl_b32 s19, s8, 10
	s_lshl_b64 s[0:1], s[0:1], 1
	s_lshl_b32 s4, s7, 20
	s_add_u32 s4, s40, s4
	s_addc_u32 s5, s41, 0
	s_add_u32 s4, s4, s0
	s_addc_u32 s5, s5, s1
	s_add_i32 s9, s19, 0
	s_add_i32 m0, s9, 0x10000
	v_mov_b32_e32 v171, 0
	global_load_lds_dwordx4 v170, s[4:5] sc0
	s_add_i32 m0, s9, 0x12000
	s_add_u32 s12, s94, s0
	s_addc_u32 s13, s95, s1
	s_add_u32 s0, s12, 0xb2d2400
	global_load_lds_dwordx4 v172, s[4:5] sc0
	s_addc_u32 s1, s13, 0
	s_mov_b32 m0, s9
	s_add_i32 s18, s9, 0x2000
	global_load_lds_dwordx4 v170, s[0:1] sc0
	s_mov_b32 m0, s18
	s_add_u32 s10, s4, 0x80000
	global_load_lds_dwordx4 v172, s[0:1] sc0
	s_addc_u32 s11, s5, 0
	s_add_i32 m0, s9, 0x14000
	v_mov_b32_e32 v173, v171
	global_load_lds_dwordx4 v170, s[10:11] sc0
	s_add_i32 m0, s9, 0x16000
	s_add_u32 s12, s12, 0xb352400
	s_addc_u32 s13, s13, 0
	s_add_i32 s14, s9, 0x4000
	global_load_lds_dwordx4 v172, s[10:11] sc0
	s_mov_b32 m0, s14
	s_add_i32 s15, s9, 0x6000
	global_load_lds_dwordx4 v170, s[12:13] sc0
	s_mov_b32 m0, s15
	v_lshl_add_u64 v[34:35], s[4:5], 0, v[170:171]
	global_load_lds_dwordx4 v172, s[12:13] sc0
	v_lshl_add_u64 v[36:37], s[4:5], 0, v[172:173]
	v_lshl_add_u64 v[32:33], s[0:1], 0, v[170:171]
	v_lshl_add_u64 v[30:31], s[0:1], 0, v[172:173]
	v_lshl_add_u64 v[28:29], s[10:11], 0, v[170:171]
	v_lshl_add_u64 v[26:27], s[10:11], 0, v[172:173]
	v_lshl_add_u64 v[22:23], s[12:13], 0, v[170:171]
	s_cmp_lg_u32 s20, 1
	v_lshl_add_u64 v[24:25], s[12:13], 0, v[172:173]
	s_cbranch_scc1 .LBB0_948
	s_barrier
.LBB0_948:
	s_add_i32 s24, 0, 0x18000
	s_lshl_b32 s8, s8, 5
	s_add_i32 s16, s24, s19
	s_mov_b64 s[12:13], 0x80
	s_lshl_b32 s21, s20, 13
	s_and_b32 s8, s8, 0x60
	v_lshl_add_u64 v[18:19], v[34:35], 0, s[12:13]
	s_mov_b32 m0, s16
	s_add_i32 s17, s16, 0x2000
	s_add_i32 s10, s9, 0x8000
	s_add_i32 s11, s9, 0xa000
	s_waitcnt vmcnt(4)
	s_barrier
	global_load_lds_dwordx4 v[18:19], off sc0
	v_lshl_add_u64 v[20:21], v[36:37], 0, s[12:13]
	s_mov_b32 m0, s17
	s_add_u32 s22, s4, 0x80080
	global_load_lds_dwordx4 v[20:21], off sc0
	v_lshl_add_u64 v[2:3], v[32:33], 0, s[12:13]
	s_mov_b32 m0, s10
	s_addc_u32 s23, s5, 0
	s_add_i32 s25, 0, 0x1c000
	global_load_lds_dwordx4 v[2:3], off sc0
	v_lshl_add_u64 v[6:7], v[30:31], 0, s[12:13]
	s_mov_b32 m0, s11
	s_add_i32 s12, s25, s19
	global_load_lds_dwordx4 v[6:7], off sc0
	v_lshl_add_u64 v[10:11], s[22:23], 0, v[170:171]
	s_mov_b32 m0, s12
	s_add_i32 s13, s12, 0x2000
	global_load_lds_dwordx4 v[10:11], off sc0
	v_lshl_add_u64 v[12:13], s[22:23], 0, v[172:173]
	s_mov_b32 m0, s13
	v_lshl_or_b32 v1, s8, 7, v1
	global_load_lds_dwordx4 v[12:13], off sc0
	s_add_i32 s22, 0, 0x10000
	v_add_u32_e32 v152, s22, v1
	s_waitcnt vmcnt(6)
	s_barrier
	ds_read_b128 v[38:41], v152
	ds_read_b128 v[42:45], v152 offset:1024
	ds_read_b128 v[46:49], v152 offset:2048
	ds_read_b128 v[50:53], v152 offset:3072
	v_lshlrev_b32_e32 v5, 2, v178
	v_lshl_or_b32 v4, v178, 6, v204
	v_and_b32_e32 v5, 32, v5
	v_lshl_or_b32 v14, s20, 6, v178
	v_bitop3_b32 v4, v4, s21, v5 bitop3:0xde
	v_mov_b32_e32 v15, v171
	v_add_u32_e32 v153, 0, v4
	s_add_i32 s26, 0, 0x14000
	v_lshlrev_b64 v[8:9], 12, v[14:15]
	v_or_b32_e32 v4, 16, v14
	v_mov_b32_e32 v5, v171
	v_or_b32_e32 v16, 32, v14
	v_mov_b32_e32 v17, v171
	v_or_b32_e32 v14, 48, v14
	v_add_u32_e32 v154, s26, v1
	v_add_u32_e32 v155, s24, v1
	v_add_u32_e32 v1, s25, v1
	v_lshlrev_b64 v[4:5], 12, v[4:5]
	v_lshlrev_b64 v[16:17], 12, v[16:17]
	v_lshlrev_b64 v[14:15], 12, v[14:15]
	s_add_u32 s20, s0, 0x80080
	s_addc_u32 s21, s1, 0
	s_add_i32 s23, s9, 0xc000
	v_lshl_add_u64 v[86:87], s[20:21], 0, v[170:171]
	s_mov_b32 m0, s23
	ds_read_b128 v[54:57], v153
	ds_read_b128 v[58:61], v153 offset:1024
	ds_read_b128 v[62:65], v153 offset:2048
	ds_read_b128 v[66:69], v153 offset:3072
	ds_read_b128 v[70:73], v153 offset:4096
	ds_read_b128 v[74:77], v153 offset:5120
	ds_read_b128 v[78:81], v153 offset:6144
	ds_read_b128 v[82:85], v153 offset:7168
	global_load_lds_dwordx4 v[86:87], off sc0
	v_lshl_add_u64 v[86:87], s[20:21], 0, v[172:173]
	s_add_i32 s20, s9, 0xe000
	s_mov_b32 m0, s20
	s_nop 0
	global_load_lds_dwordx4 v[86:87], off sc0
	s_waitcnt lgkmcnt(8)
	s_barrier
	s_waitcnt lgkmcnt(0)
	v_mfma_f32_16x16x32_bf16 v[86:89], v[38:41], v[54:57], 0
	v_mfma_f32_16x16x32_bf16 v[94:97], v[38:41], v[62:65], 0
	v_mfma_f32_16x16x32_bf16 v[102:105], v[38:41], v[70:73], 0
	v_mfma_f32_16x16x32_bf16 v[38:41], v[38:41], v[78:81], 0
	v_mfma_f32_16x16x32_bf16 v[86:89], v[42:45], v[58:61], v[86:89]
	v_mfma_f32_16x16x32_bf16 v[90:93], v[46:49], v[54:57], 0
	v_mfma_f32_16x16x32_bf16 v[94:97], v[42:45], v[66:69], v[94:97]
	v_mfma_f32_16x16x32_bf16 v[98:101], v[46:49], v[62:65], 0
	v_mfma_f32_16x16x32_bf16 v[102:105], v[42:45], v[74:77], v[102:105]
	v_mfma_f32_16x16x32_bf16 v[106:109], v[46:49], v[70:73], 0
	v_mfma_f32_16x16x32_bf16 v[38:41], v[42:45], v[82:85], v[38:41]
	v_mfma_f32_16x16x32_bf16 v[42:45], v[46:49], v[78:81], 0
	v_mfma_f32_16x16x32_bf16 v[90:93], v[50:53], v[58:61], v[90:93]
	v_mfma_f32_16x16x32_bf16 v[98:101], v[50:53], v[66:69], v[98:101]
	v_mfma_f32_16x16x32_bf16 v[106:109], v[50:53], v[74:77], v[106:109]
	v_mfma_f32_16x16x32_bf16 v[42:45], v[50:53], v[82:85], v[42:45]
	s_barrier
	s_mov_b64 s[24:25], 0x100
	s_add_i32 s21, s22, s19
	v_lshl_add_u64 v[118:119], v[34:35], 0, s[24:25]
	s_mov_b32 m0, s21
	s_add_i32 s22, s21, 0x2000
	ds_read_b128 v[46:49], v154
	ds_read_b128 v[50:53], v154 offset:1024
	ds_read_b128 v[110:113], v154 offset:2048
	ds_read_b128 v[114:117], v154 offset:3072
	global_load_lds_dwordx4 v[118:119], off sc0
	v_lshl_add_u64 v[118:119], v[36:37], 0, s[24:25]
	s_mov_b32 m0, s22
	s_nop 0
	global_load_lds_dwordx4 v[118:119], off sc0
	s_barrier
	s_waitcnt lgkmcnt(0)
	v_mfma_f32_16x16x32_bf16 v[118:121], v[46:49], v[54:57], 0
	v_mfma_f32_16x16x32_bf16 v[54:57], v[110:113], v[54:57], 0
	v_mfma_f32_16x16x32_bf16 v[118:121], v[50:53], v[58:61], v[118:121]
	v_mfma_f32_16x16x32_bf16 v[54:57], v[114:117], v[58:61], v[54:57]
	v_mfma_f32_16x16x32_bf16 v[58:61], v[46:49], v[62:65], 0
	v_mfma_f32_16x16x32_bf16 v[62:65], v[110:113], v[62:65], 0
	v_mfma_f32_16x16x32_bf16 v[58:61], v[50:53], v[66:69], v[58:61]
	v_mfma_f32_16x16x32_bf16 v[62:65], v[114:117], v[66:69], v[62:65]
	v_mfma_f32_16x16x32_bf16 v[66:69], v[46:49], v[70:73], 0
	v_mfma_f32_16x16x32_bf16 v[46:49], v[46:49], v[78:81], 0
	v_mfma_f32_16x16x32_bf16 v[66:69], v[50:53], v[74:77], v[66:69]
	v_mfma_f32_16x16x32_bf16 v[70:73], v[110:113], v[70:73], 0
	v_mfma_f32_16x16x32_bf16 v[46:49], v[50:53], v[82:85], v[46:49]
	v_mfma_f32_16x16x32_bf16 v[50:53], v[110:113], v[78:81], 0
	v_mfma_f32_16x16x32_bf16 v[70:73], v[114:117], v[74:77], v[70:73]
	v_mfma_f32_16x16x32_bf16 v[50:53], v[114:117], v[82:85], v[50:53]
	s_mov_b32 m0, s9
	v_lshl_add_u64 v[74:75], v[32:33], 0, s[24:25]
	s_barrier
	global_load_lds_dwordx4 v[74:75], off sc0
	v_lshl_add_u64 v[74:75], v[30:31], 0, s[24:25]
	s_mov_b32 m0, s18
	s_nop 0
	global_load_lds_dwordx4 v[74:75], off sc0
	s_barrier
	s_waitcnt lgkmcnt(0)
	s_barrier
	s_add_u32 s24, s4, 0x80100
	s_addc_u32 s25, s5, 0
	s_add_i32 s19, s26, s19
	v_lshl_add_u64 v[74:75], s[24:25], 0, v[170:171]
	s_mov_b32 m0, s19
	s_nop 0
	global_load_lds_dwordx4 v[74:75], off sc0
	v_lshl_add_u64 v[74:75], s[24:25], 0, v[172:173]
	s_add_i32 s24, s19, 0x2000
	s_mov_b32 m0, s24
	s_nop 0
	global_load_lds_dwordx4 v[74:75], off sc0
	s_waitcnt vmcnt(6)
	s_barrier
	s_barrier
	ds_read_b128 v[74:77], v155
	ds_read_b128 v[78:81], v155 offset:1024
	ds_read_b128 v[82:85], v155 offset:2048
	ds_read_b128 v[110:113], v155 offset:3072
	s_add_u32 s26, s0, 0x80100
	s_addc_u32 s27, s1, 0
	s_mov_b32 m0, s14
	v_lshl_add_u64 v[150:151], s[26:27], 0, v[170:171]
	ds_read_b128 v[114:117], v153 offset:32768
	ds_read_b128 v[122:125], v153 offset:33792
	ds_read_b128 v[126:129], v153 offset:34816
	ds_read_b128 v[130:133], v153 offset:35840
	ds_read_b128 v[134:137], v153 offset:36864
	ds_read_b128 v[138:141], v153 offset:37888
	ds_read_b128 v[142:145], v153 offset:38912
	ds_read_b128 v[146:149], v153 offset:39936
	global_load_lds_dwordx4 v[150:151], off sc0
	v_lshl_add_u64 v[150:151], s[26:27], 0, v[172:173]
	s_mov_b32 m0, s15
	s_nop 0
	global_load_lds_dwordx4 v[150:151], off sc0
	s_waitcnt lgkmcnt(8)
	s_barrier
	s_waitcnt lgkmcnt(0)
	v_mfma_f32_16x16x32_bf16 v[86:89], v[74:77], v[114:117], v[86:89]
	v_mfma_f32_16x16x32_bf16 v[90:93], v[82:85], v[114:117], v[90:93]
	v_mfma_f32_16x16x32_bf16 v[94:97], v[74:77], v[126:129], v[94:97]
	v_mfma_f32_16x16x32_bf16 v[98:101], v[82:85], v[126:129], v[98:101]
	v_mfma_f32_16x16x32_bf16 v[102:105], v[74:77], v[134:137], v[102:105]
	v_mfma_f32_16x16x32_bf16 v[106:109], v[82:85], v[134:137], v[106:109]
	v_mfma_f32_16x16x32_bf16 v[38:41], v[74:77], v[142:145], v[38:41]
	v_mfma_f32_16x16x32_bf16 v[42:45], v[82:85], v[142:145], v[42:45]
	v_mfma_f32_16x16x32_bf16 v[86:89], v[78:81], v[122:125], v[86:89]
	v_mfma_f32_16x16x32_bf16 v[90:93], v[110:113], v[122:125], v[90:93]
	v_mfma_f32_16x16x32_bf16 v[94:97], v[78:81], v[130:133], v[94:97]
	v_mfma_f32_16x16x32_bf16 v[98:101], v[110:113], v[130:133], v[98:101]
	v_mfma_f32_16x16x32_bf16 v[102:105], v[78:81], v[138:141], v[102:105]
	v_mfma_f32_16x16x32_bf16 v[106:109], v[110:113], v[138:141], v[106:109]
	v_mfma_f32_16x16x32_bf16 v[38:41], v[78:81], v[146:149], v[38:41]
	v_mfma_f32_16x16x32_bf16 v[42:45], v[110:113], v[146:149], v[42:45]
	s_barrier
	s_mov_b64 s[26:27], 0x180
	s_mov_b32 m0, s16
	v_lshl_add_u64 v[150:151], v[34:35], 0, s[26:27]
	ds_read_b128 v[74:77], v1
	ds_read_b128 v[78:81], v1 offset:1024
	ds_read_b128 v[82:85], v1 offset:2048
	ds_read_b128 v[110:113], v1 offset:3072
	global_load_lds_dwordx4 v[150:151], off sc0
	v_lshl_add_u64 v[150:151], v[36:37], 0, s[26:27]
	s_mov_b32 m0, s17
	s_nop 0
	global_load_lds_dwordx4 v[150:151], off sc0
	s_barrier
	s_waitcnt lgkmcnt(0)
	v_mfma_f32_16x16x32_bf16 v[118:121], v[74:77], v[114:117], v[118:121]
	v_mfma_f32_16x16x32_bf16 v[54:57], v[82:85], v[114:117], v[54:57]
	v_mfma_f32_16x16x32_bf16 v[58:61], v[74:77], v[126:129], v[58:61]
	v_mfma_f32_16x16x32_bf16 v[62:65], v[82:85], v[126:129], v[62:65]
	v_mfma_f32_16x16x32_bf16 v[66:69], v[74:77], v[134:137], v[66:69]
	v_mfma_f32_16x16x32_bf16 v[70:73], v[82:85], v[134:137], v[70:73]
	v_mfma_f32_16x16x32_bf16 v[46:49], v[74:77], v[142:145], v[46:49]
	v_mfma_f32_16x16x32_bf16 v[50:53], v[82:85], v[142:145], v[50:53]
	v_mfma_f32_16x16x32_bf16 v[118:121], v[78:81], v[122:125], v[118:121]
	v_mfma_f32_16x16x32_bf16 v[54:57], v[110:113], v[122:125], v[54:57]
	v_mfma_f32_16x16x32_bf16 v[58:61], v[78:81], v[130:133], v[58:61]
	v_mfma_f32_16x16x32_bf16 v[62:65], v[110:113], v[130:133], v[62:65]
	v_mfma_f32_16x16x32_bf16 v[66:69], v[78:81], v[138:141], v[66:69]
	v_mfma_f32_16x16x32_bf16 v[70:73], v[110:113], v[138:141], v[70:73]
	v_mfma_f32_16x16x32_bf16 v[46:49], v[78:81], v[146:149], v[46:49]
	v_mfma_f32_16x16x32_bf16 v[50:53], v[110:113], v[146:149], v[50:53]
	s_mov_b32 m0, s10
	v_lshl_add_u64 v[74:75], v[32:33], 0, s[26:27]
	s_barrier
	global_load_lds_dwordx4 v[74:75], off sc0
	v_lshl_add_u64 v[74:75], v[30:31], 0, s[26:27]
	s_mov_b32 m0, s11
	s_nop 0
	global_load_lds_dwordx4 v[74:75], off sc0
	s_barrier
	s_waitcnt lgkmcnt(0)
	s_barrier
	s_add_u32 s4, s4, 0x80180
	s_addc_u32 s5, s5, 0
	s_mov_b32 m0, s12
	v_lshl_add_u64 v[74:75], s[4:5], 0, v[170:171]
	global_load_lds_dwordx4 v[74:75], off sc0
	v_lshl_add_u64 v[74:75], s[4:5], 0, v[172:173]
	s_mov_b32 m0, s13
	s_nop 0
	global_load_lds_dwordx4 v[74:75], off sc0
	s_waitcnt vmcnt(6)
	s_barrier
	s_barrier
	ds_read_b128 v[74:77], v152
	ds_read_b128 v[78:81], v152 offset:1024
	ds_read_b128 v[82:85], v152 offset:2048
	ds_read_b128 v[110:113], v152 offset:3072
	s_add_u32 s0, s0, 0x80180
	s_addc_u32 s1, s1, 0
	s_mov_b32 m0, s23
	v_lshl_add_u64 v[150:151], s[0:1], 0, v[170:171]
	ds_read_b128 v[114:117], v153
	ds_read_b128 v[122:125], v153 offset:1024
	ds_read_b128 v[126:129], v153 offset:2048
	ds_read_b128 v[130:133], v153 offset:3072
	ds_read_b128 v[134:137], v153 offset:4096
	ds_read_b128 v[138:141], v153 offset:5120
	ds_read_b128 v[142:145], v153 offset:6144
	ds_read_b128 v[146:149], v153 offset:7168
	global_load_lds_dwordx4 v[150:151], off sc0
	v_lshl_add_u64 v[150:151], s[0:1], 0, v[172:173]
	s_mov_b32 m0, s20
	s_nop 0
	global_load_lds_dwordx4 v[150:151], off sc0
	s_waitcnt lgkmcnt(8)
	s_barrier
	s_waitcnt lgkmcnt(0)
	v_mfma_f32_16x16x32_bf16 v[86:89], v[74:77], v[114:117], v[86:89]
	v_mfma_f32_16x16x32_bf16 v[90:93], v[82:85], v[114:117], v[90:93]
	v_mfma_f32_16x16x32_bf16 v[94:97], v[74:77], v[126:129], v[94:97]
	v_mfma_f32_16x16x32_bf16 v[98:101], v[82:85], v[126:129], v[98:101]
	v_mfma_f32_16x16x32_bf16 v[102:105], v[74:77], v[134:137], v[102:105]
	v_mfma_f32_16x16x32_bf16 v[106:109], v[82:85], v[134:137], v[106:109]
	v_mfma_f32_16x16x32_bf16 v[38:41], v[74:77], v[142:145], v[38:41]
	v_mfma_f32_16x16x32_bf16 v[42:45], v[82:85], v[142:145], v[42:45]
	v_mfma_f32_16x16x32_bf16 v[86:89], v[78:81], v[122:125], v[86:89]
	v_mfma_f32_16x16x32_bf16 v[90:93], v[110:113], v[122:125], v[90:93]
	v_mfma_f32_16x16x32_bf16 v[94:97], v[78:81], v[130:133], v[94:97]
	v_mfma_f32_16x16x32_bf16 v[98:101], v[110:113], v[130:133], v[98:101]
	v_mfma_f32_16x16x32_bf16 v[102:105], v[78:81], v[138:141], v[102:105]
	v_mfma_f32_16x16x32_bf16 v[106:109], v[110:113], v[138:141], v[106:109]
	v_mfma_f32_16x16x32_bf16 v[38:41], v[78:81], v[146:149], v[38:41]
	v_mfma_f32_16x16x32_bf16 v[42:45], v[110:113], v[146:149], v[42:45]
	s_barrier
	s_mov_b32 m0, s21
	ds_read_b128 v[74:77], v154
	ds_read_b128 v[78:81], v154 offset:1024
	ds_read_b128 v[82:85], v154 offset:2048
	ds_read_b128 v[110:113], v154 offset:3072
	global_load_lds_dwordx4 v[34:35], off sc0
	s_mov_b32 m0, s22
	s_nop 0
	global_load_lds_dwordx4 v[36:37], off sc0
	s_barrier
	s_waitcnt lgkmcnt(0)
	v_mfma_f32_16x16x32_bf16 v[34:37], v[74:77], v[114:117], v[118:121]
	v_mfma_f32_16x16x32_bf16 v[54:57], v[82:85], v[114:117], v[54:57]
	v_mfma_f32_16x16x32_bf16 v[58:61], v[74:77], v[126:129], v[58:61]
	v_mfma_f32_16x16x32_bf16 v[62:65], v[82:85], v[126:129], v[62:65]
	v_mfma_f32_16x16x32_bf16 v[66:69], v[74:77], v[134:137], v[66:69]
	v_mfma_f32_16x16x32_bf16 v[70:73], v[82:85], v[134:137], v[70:73]
	v_mfma_f32_16x16x32_bf16 v[46:49], v[74:77], v[142:145], v[46:49]
	v_mfma_f32_16x16x32_bf16 v[50:53], v[82:85], v[142:145], v[50:53]
	v_mfma_f32_16x16x32_bf16 v[34:37], v[78:81], v[122:125], v[34:37]
	v_mfma_f32_16x16x32_bf16 v[54:57], v[110:113], v[122:125], v[54:57]
	v_mfma_f32_16x16x32_bf16 v[58:61], v[78:81], v[130:133], v[58:61]
	v_mfma_f32_16x16x32_bf16 v[62:65], v[110:113], v[130:133], v[62:65]
	v_mfma_f32_16x16x32_bf16 v[66:69], v[78:81], v[138:141], v[66:69]
	v_mfma_f32_16x16x32_bf16 v[70:73], v[110:113], v[138:141], v[70:73]
	v_mfma_f32_16x16x32_bf16 v[46:49], v[78:81], v[146:149], v[46:49]
	v_mfma_f32_16x16x32_bf16 v[50:53], v[110:113], v[146:149], v[50:53]
	s_mov_b32 m0, s9
	s_barrier
	global_load_lds_dwordx4 v[32:33], off sc0
	s_mov_b32 m0, s18
	s_nop 0
	global_load_lds_dwordx4 v[30:31], off sc0
	s_barrier
	s_waitcnt lgkmcnt(0)
	s_barrier
	s_mov_b32 m0, s19
	s_nop 0
	global_load_lds_dwordx4 v[28:29], off sc0
	s_mov_b32 m0, s24
	s_nop 0
	global_load_lds_dwordx4 v[26:27], off sc0
	s_waitcnt vmcnt(6)
	s_barrier
	s_barrier
	ds_read_b128 v[26:29], v155
	ds_read_b128 v[30:33], v155 offset:1024
	ds_read_b128 v[74:77], v155 offset:2048
	ds_read_b128 v[78:81], v155 offset:3072
	s_mov_b32 m0, s14
	ds_read_b128 v[82:85], v153 offset:32768
	ds_read_b128 v[110:113], v153 offset:33792
	ds_read_b128 v[114:117], v153 offset:34816
	ds_read_b128 v[118:121], v153 offset:35840
	ds_read_b128 v[122:125], v153 offset:36864
	ds_read_b128 v[126:129], v153 offset:37888
	ds_read_b128 v[130:133], v153 offset:38912
	ds_read_b128 v[134:137], v153 offset:39936
	global_load_lds_dwordx4 v[22:23], off sc0
	s_mov_b32 m0, s15
	s_nop 0
	global_load_lds_dwordx4 v[24:25], off sc0
	s_waitcnt lgkmcnt(8)
	s_barrier
	s_waitcnt lgkmcnt(0)
	v_mfma_f32_16x16x32_bf16 v[22:25], v[26:29], v[82:85], v[86:89]
	v_mfma_f32_16x16x32_bf16 v[86:89], v[74:77], v[82:85], v[90:93]
	v_mfma_f32_16x16x32_bf16 v[90:93], v[26:29], v[114:117], v[94:97]
	v_mfma_f32_16x16x32_bf16 v[94:97], v[74:77], v[114:117], v[98:101]
	v_mfma_f32_16x16x32_bf16 v[98:101], v[26:29], v[122:125], v[102:105]
	v_mfma_f32_16x16x32_bf16 v[26:29], v[26:29], v[130:133], v[38:41]
	v_mfma_f32_16x16x32_bf16 v[22:25], v[30:33], v[110:113], v[22:25]
	v_mfma_f32_16x16x32_bf16 v[90:93], v[30:33], v[118:121], v[90:93]
	v_mfma_f32_16x16x32_bf16 v[98:101], v[30:33], v[126:129], v[98:101]
	v_mfma_f32_16x16x32_bf16 v[102:105], v[74:77], v[122:125], v[106:109]
	v_mfma_f32_16x16x32_bf16 v[26:29], v[30:33], v[134:137], v[26:29]
	v_mfma_f32_16x16x32_bf16 v[30:33], v[74:77], v[130:133], v[42:45]
	v_mfma_f32_16x16x32_bf16 v[86:89], v[78:81], v[110:113], v[86:89]
	v_mfma_f32_16x16x32_bf16 v[94:97], v[78:81], v[118:121], v[94:97]
	v_mfma_f32_16x16x32_bf16 v[102:105], v[78:81], v[126:129], v[102:105]
	v_mfma_f32_16x16x32_bf16 v[30:33], v[78:81], v[134:137], v[30:33]
	s_barrier
	s_mov_b32 m0, s16
	ds_read_b128 v[38:41], v1
	ds_read_b128 v[42:45], v1 offset:1024
	ds_read_b128 v[74:77], v1 offset:2048
	ds_read_b128 v[78:81], v1 offset:3072
	global_load_lds_dwordx4 v[18:19], off sc0
	s_mov_b32 m0, s17
	s_nop 0
	global_load_lds_dwordx4 v[20:21], off sc0
	s_barrier
	s_waitcnt lgkmcnt(0)
	v_mfma_f32_16x16x32_bf16 v[18:21], v[38:41], v[82:85], v[34:37]
	v_mfma_f32_16x16x32_bf16 v[34:37], v[74:77], v[82:85], v[54:57]
	v_mfma_f32_16x16x32_bf16 v[54:57], v[38:41], v[114:117], v[58:61]
	v_mfma_f32_16x16x32_bf16 v[58:61], v[74:77], v[114:117], v[62:65]
	v_mfma_f32_16x16x32_bf16 v[62:65], v[38:41], v[122:125], v[66:69]
	v_mfma_f32_16x16x32_bf16 v[38:41], v[38:41], v[130:133], v[46:49]
	v_mfma_f32_16x16x32_bf16 v[18:21], v[42:45], v[110:113], v[18:21]
	v_mfma_f32_16x16x32_bf16 v[54:57], v[42:45], v[118:121], v[54:57]
	v_mfma_f32_16x16x32_bf16 v[62:65], v[42:45], v[126:129], v[62:65]
	v_mfma_f32_16x16x32_bf16 v[66:69], v[74:77], v[122:125], v[70:73]
	v_mfma_f32_16x16x32_bf16 v[38:41], v[42:45], v[134:137], v[38:41]
	v_mfma_f32_16x16x32_bf16 v[42:45], v[74:77], v[130:133], v[50:53]
	v_mfma_f32_16x16x32_bf16 v[34:37], v[78:81], v[110:113], v[34:37]
	v_mfma_f32_16x16x32_bf16 v[58:61], v[78:81], v[118:121], v[58:61]
	v_mfma_f32_16x16x32_bf16 v[66:69], v[78:81], v[126:129], v[66:69]
	v_mfma_f32_16x16x32_bf16 v[42:45], v[78:81], v[134:137], v[42:45]
	s_mov_b32 m0, s10
	s_barrier
	global_load_lds_dwordx4 v[2:3], off sc0
	s_mov_b32 m0, s11
	s_nop 0
	global_load_lds_dwordx4 v[6:7], off sc0
	s_barrier
	s_waitcnt lgkmcnt(0)
	s_barrier
	s_mov_b32 m0, s12
	s_nop 0
	global_load_lds_dwordx4 v[10:11], off sc0
	s_mov_b32 m0, s13
	s_nop 0
	global_load_lds_dwordx4 v[12:13], off sc0
	s_waitcnt vmcnt(6)
	s_barrier
	s_lshl_b32 s0, s7, 8
	v_lshl_or_b32 v1, v211, 2, s0
	s_ashr_i32 s0, s82, 2
	s_ashr_i32 s1, s0, 31
	s_lshl_b64 s[0:1], s[0:1], 19
	v_or_b32_e32 v1, s8, v1
	s_add_u32 s0, s94, s0
	s_addc_u32 s1, s95, s1
	v_lshlrev_b32_e32 v170, 2, v1
	v_lshl_add_u64 v[2:3], s[0:1], 0, v[170:171]
	s_mov_b64 s[0:1], 0xb3d6400
	v_lshl_add_u64 v[2:3], v[2:3], 0, s[0:1]
	v_lshl_add_u64 v[6:7], v[2:3], 0, v[8:9]
	v_lshl_add_u64 v[4:5], v[2:3], 0, v[4:5]
	s_barrier
	global_store_dwordx4 v[6:7], v[22:25], off
	global_store_dwordx4 v[6:7], v[86:89], off offset:64
	global_store_dwordx4 v[6:7], v[18:21], off offset:512
	global_store_dwordx4 v[6:7], v[34:37], off offset:576
	global_store_dwordx4 v[4:5], v[90:93], off
	global_store_dwordx4 v[4:5], v[94:97], off offset:64
	global_store_dwordx4 v[4:5], v[54:57], off offset:512
	global_store_dwordx4 v[4:5], v[58:61], off offset:576
	v_lshl_add_u64 v[4:5], v[2:3], 0, v[16:17]
	v_lshl_add_u64 v[2:3], v[2:3], 0, v[14:15]
	global_store_dwordx4 v[4:5], v[98:101], off
	global_store_dwordx4 v[4:5], v[102:105], off offset:64
	global_store_dwordx4 v[4:5], v[62:65], off offset:512
	global_store_dwordx4 v[4:5], v[66:69], off offset:576
	global_store_dwordx4 v[2:3], v[26:29], off
	global_store_dwordx4 v[2:3], v[30:33], off offset:64
	global_store_dwordx4 v[2:3], v[38:41], off offset:512
	global_store_dwordx4 v[2:3], v[42:45], off offset:576
	s_waitcnt vmcnt(0)
	s_cmpk_gt_u32 s6, 0xff
	s_cbranch_scc1 .LBB0_950
	s_barrier

.LBB0_1079:
	s_ashr_i32 s0, s3, 3
	v_and_b32_e32 v1, 32, v0
	v_lshrrev_b32_e32 v2, 1, v0
	v_lshrrev_b32_e32 v3, 5, v0
	s_add_u32 s47, s94, 0x1f80000
	v_bfe_u32 v12, v0, 2, 4
	v_bitop3_b32 v10, v180, v1, 48 bitop3:0x6c
	v_and_b32_e32 v11, 64, v0
	v_and_b32_e32 v2, 24, v2
	v_and_b32_e32 v3, 4, v3
	v_bfe_u32 v4, v0, 2, 2
	s_addc_u32 s48, s95, 0
	v_or_b32_e32 v1, v10, v11
	v_or3_b32 v2, v3, v4, v2
	v_and_or_b32 v3, v179, 48, v12
	v_or_b32_e32 v13, 0x2000, v180
	s_add_u32 s49, s94, 0xf00000
	v_and_or_b32 v4, v179, 32, v2
	v_lshl_or_b32 v184, v3, 11, v1
	v_lshrrev_b32_e32 v3, 7, v13
	s_movk_i32 s1, 0x70
	s_addc_u32 s50, s95, 0
	v_lshl_or_b32 v186, v4, 11, v1
	v_and_or_b32 v4, v3, s1, v12
	s_movk_i32 s1, 0x60
	s_add_i32 s0, s2, s0
	v_and_or_b32 v2, v3, s1, v2
	s_mul_hi_i32 s1, s0, 0x2e8ba2e9
	s_lshr_b32 s2, s1, 31
	s_ashr_i32 s1, s1, 5
	s_add_i32 s1, s1, s2
	s_lshl_b32 s2, s1, 3
	s_sub_i32 s3, 0x41, s2
	s_mulk_i32 s1, 0xb0
	s_min_u32 s3, s3, 8
	s_sub_i32 s6, s0, s1
	v_lshl_or_b32 v190, v2, 11, v1
	s_sext_i32_i16 s0, s6
	v_cvt_f32_ubyte0_e32 v2, s3
	v_lshl_or_b32 v188, v4, 11, v1
	v_cvt_f32_i32_e32 v1, s0
	v_rcp_iflag_f32_e32 v3, v2
	s_lshr_b32 s22, s5, 6
	s_ashr_i32 s0, s0, 30
	s_lshr_b32 s28, s5, 8
	v_mul_f32_e32 v3, v1, v3
	v_trunc_f32_e32 v3, v3
	v_fma_f32 v1, -v3, v2, v1
	v_cvt_i32_f32_e32 v3, v3
	s_lshl_b32 s51, s22, 10
	s_or_b32 s4, s0, 1
	v_cmp_ge_f32_e64 s[0:1], |v1|, v2
	s_and_b64 s[0:1], s[0:1], exec
	s_cselect_b32 s0, s4, 0
	v_readfirstlane_b32 s1, v3
	s_add_i32 s4, s1, s0
	s_mul_i32 s0, s4, s3
	s_sub_i32 s0, s6, s0
	s_sext_i32_i16 s0, s0
	s_add_i32 s6, s2, s0
	s_ashr_i32 s7, s6, 31
	s_bfe_i64 s[2:3], s[4:5], 0x100000
	s_lshl_b64 s[0:1], s[6:7], 19
	s_lshl_b64 s[2:3], s[2:3], 19
	s_add_u32 s2, s49, s2
	s_addc_u32 s3, s50, s3
	s_add_i32 s52, s51, 0
	s_add_i32 m0, s52, 0x10000
	v_mov_b32_e32 v187, 0
	global_load_lds_dwordx4 v186, s[2:3] sc0
	s_add_i32 m0, s52, 0x12000
	s_add_u32 s0, s47, s0
	global_load_lds_dwordx4 v190, s[2:3] sc0
	s_addc_u32 s1, s48, s1
	s_mov_b32 m0, s52
	s_add_i32 s53, s52, 0x2000
	global_load_lds_dwordx4 v184, s[0:1] sc0
	s_mov_b32 m0, s53
	s_add_u32 s10, s2, 0x40000
	global_load_lds_dwordx4 v188, s[0:1] sc0
	s_addc_u32 s11, s3, 0
	s_add_i32 m0, s52, 0x14000
	v_mov_b32_e32 v191, v187
	global_load_lds_dwordx4 v186, s[10:11] sc0
	s_add_i32 m0, s52, 0x16000
	v_mov_b32_e32 v185, v187
	global_load_lds_dwordx4 v190, s[10:11] sc0
	s_add_u32 s10, s0, 0x40000
	s_addc_u32 s11, s1, 0
	s_add_i32 s54, s52, 0x4000
	s_mov_b32 m0, s54
	s_add_i32 s55, s52, 0x6000
	global_load_lds_dwordx4 v184, s[10:11] sc0
	s_mov_b32 m0, s55
	s_cmp_eq_u32 s28, 1
	global_load_lds_dwordx4 v188, s[10:11] sc0
	v_mov_b32_e32 v189, v187
	s_cselect_b64 s[8:9], -1, 0
	s_mov_b32 s56, 0
	v_lshl_add_u64 v[6:7], s[2:3], 0, v[186:187]
	v_lshl_add_u64 v[4:5], s[2:3], 0, v[190:191]
	v_lshl_add_u64 v[2:3], s[0:1], 0, v[184:185]
	v_writelane_b32 v248, s8, 51
	s_cmp_lg_u32 s28, 1
	v_lshl_add_u64 v[8:9], s[0:1], 0, v[188:189]
	v_writelane_b32 v248, s9, 52
	s_cbranch_scc1 .LBB0_1081
	s_barrier
.LBB0_1081:
	s_add_u32 s88, s94, 0x4212400
	s_addc_u32 s89, s95, 0
	s_add_u32 s16, s94, 0xb956400
	s_addc_u32 s17, s95, 0
	s_add_u32 s8, s94, 0xbabbc00
	s_addc_u32 s9, s95, 0
	s_add_u32 s18, s94, 0xbc21400
	s_addc_u32 s19, s95, 0
	s_add_u32 s20, s92, 0x8820000
	s_addc_u32 s21, s93, 0
	s_lshl_b32 s7, s22, 5
	s_mov_b64 s[22:23], 0x80
	s_and_b32 s58, s7, 0x60
	s_add_i32 m0, s52, 0x18000
	v_lshl_add_u64 v[6:7], v[6:7], 0, s[22:23]
	s_lshl_b32 s57, s28, 6
	s_lshl_b32 s26, s28, 13
	s_lshl_b32 s27, s58, 7
	s_waitcnt vmcnt(4)
	s_barrier
	global_load_lds_dwordx4 v[6:7], off sc0
	v_lshl_add_u64 v[4:5], v[4:5], 0, s[22:23]
	s_add_i32 m0, s52, 0x1a000
	s_add_i32 s59, s52, 0x8000
	s_add_i32 s60, s52, 0xa000
	global_load_lds_dwordx4 v[4:5], off sc0
	v_lshl_add_u64 v[2:3], v[2:3], 0, s[22:23]
	s_mov_b32 m0, s59
	s_add_u32 s24, s2, 0x40080
	global_load_lds_dwordx4 v[2:3], off sc0
	v_lshl_add_u64 v[2:3], v[8:9], 0, s[22:23]
	s_mov_b32 m0, s60
	s_addc_u32 s25, s3, 0
	global_load_lds_dwordx4 v[2:3], off sc0
	s_add_i32 m0, s52, 0x1c000
	v_lshl_add_u64 v[2:3], s[24:25], 0, v[186:187]
	global_load_lds_dwordx4 v[2:3], off sc0
	v_lshl_add_u64 v[2:3], s[24:25], 0, v[190:191]
	s_add_i32 m0, s52, 0x1e000
	v_lshl_or_b32 v1, v178, 6, v204
	global_load_lds_dwordx4 v[2:3], off sc0
	v_lshlrev_b32_e32 v2, 2, v0
	v_and_b32_e32 v2, 32, v2
	s_lshl_b32 s61, s28, 1
	s_sext_i32_i16 s7, s4
	v_bitop3_b32 v3, v1, s26, v2 bitop3:0xde
	v_lshlrev_b32_e32 v1, 6, v0
	s_movk_i32 s4, 0x3c0
	s_add_i32 s61, s61, 0x7ffff2
	v_and_or_b32 v1, v1, s4, v204
	s_cmpk_lt_u32 s5, 0x100
	v_bitop3_b32 v1, s27, v1, v2 bitop3:0xf6
	s_cselect_b64 s[24:25], -1, 0
	s_cmpk_gt_u32 s5, 0xff
	v_lshlrev_b32_e32 v2, 8, v0
	s_cselect_b64 s[26:27], -1, 0
	s_lshl_b32 s4, s28, 10
	s_waitcnt lgkmcnt(0)
	s_ashr_i32 s62, s96, 31
	v_and_b32_e32 v2, 0x18000, v2
	v_lshlrev_b32_e32 v4, 11, v12
	s_add_u32 s28, s84, 0x2c00
	v_or3_b32 v2, v10, v2, v4
	s_addc_u32 s29, s85, 0
	v_add_u32_e32 v192, v2, v11
	v_lshlrev_b32_e32 v2, 4, v13
	s_waitcnt vmcnt(6)
	s_add_u32 s30, s84, 0x5800
	v_and_b32_e32 v2, 0x38000, v2
	s_addc_u32 s31, s85, 0
	s_add_i32 s65, s4, 0
	v_or3_b32 v2, v10, v2, v4
	s_add_i32 s66, 0, 0x10000
	s_add_i32 s67, 0, 0x14000
	v_writelane_b32 v248, s8, 43
	s_add_i32 s63, s65, 0x20010
	s_add_i32 s64, s65, 0x1fc10
	s_add_i32 s65, s65, 0x1fe10
	v_mov_b32_e32 v193, v187
	v_add_u32_e32 v194, v2, v11
	v_mov_b32_e32 v195, v187
	v_mov_b64_e32 v[196:197], 0x596
	v_mov_b64_e32 v[198:199], 0x595
	v_add_u32_e32 v181, s66, v1
	v_add_u32_e32 v183, 0, v3
	v_add_u32_e32 v206, s67, v1
	s_add_i32 s68, 0, 0x20810
	s_movk_i32 s69, 0x2c00
	s_xor_b64 s[34:35], s[24:25], -1
	s_movk_i32 s70, 0x1600
	v_writelane_b32 v248, s9, 44
	s_barrier
	s_branch .LBB0_1083

.Lpeel_p8:
	ds_read_b128 v[130:133], v181
	ds_read_b128 v[134:137], v181 offset:1024
	ds_read_b128 v[138:141], v181 offset:2048
	ds_read_b128 v[142:145], v181 offset:3072
	s_add_u32 s2, s0, 0xfffc0080
	s_addc_u32 s3, s1, -1
	s_cmp_eq_u32 s74, 12
	s_cselect_b32 s45, s33, s3
	s_cselect_b32 s44, s39, s2
	s_cselect_b32 s3, s37, s73
	s_cselect_b32 s2, s71, s72
	s_add_i32 m0, s52, 0xc000
	ds_read_b128 v[146:149], v183
	ds_read_b128 v[150:153], v183 offset:1024
	ds_read_b128 v[154:157], v183 offset:2048
	ds_read_b128 v[158:161], v183 offset:3072
	ds_read_b128 v[162:165], v183 offset:4096
	ds_read_b128 v[166:169], v183 offset:5120
	ds_read_b128 v[170:173], v183 offset:6144
	ds_read_b128 v[174:177], v183 offset:7168
	global_load_lds_dwordx4 v192, s[0:1] sc0
	s_add_i32 m0, s52, 0xe000
	s_nop 0
	global_load_lds_dwordx4 v194, s[0:1] sc0
	s_waitcnt lgkmcnt(8)
	s_barrier
	s_waitcnt lgkmcnt(0)
	v_mfma_f32_16x16x32_bf16 v[62:65], v[130:133], v[146:149], 0
	v_mfma_f32_16x16x32_bf16 v[30:33], v[138:141], v[146:149], 0
	v_mfma_f32_16x16x32_bf16 v[54:57], v[130:133], v[154:157], 0
	v_mfma_f32_16x16x32_bf16 v[22:25], v[138:141], v[154:157], 0
	v_mfma_f32_16x16x32_bf16 v[46:49], v[130:133], v[162:165], 0
	v_mfma_f32_16x16x32_bf16 v[14:17], v[138:141], v[162:165], 0
	v_mfma_f32_16x16x32_bf16 v[38:41], v[130:133], v[170:173], 0
	v_mfma_f32_16x16x32_bf16 v[6:9], v[138:141], v[170:173], 0
	v_mfma_f32_16x16x32_bf16 v[62:65], v[134:137], v[150:153], v[62:65]
	v_mfma_f32_16x16x32_bf16 v[30:33], v[142:145], v[150:153], v[30:33]
	v_mfma_f32_16x16x32_bf16 v[54:57], v[134:137], v[158:161], v[54:57]
	v_mfma_f32_16x16x32_bf16 v[22:25], v[142:145], v[158:161], v[22:25]
	v_mfma_f32_16x16x32_bf16 v[46:49], v[134:137], v[166:169], v[46:49]
	v_mfma_f32_16x16x32_bf16 v[14:17], v[142:145], v[166:169], v[14:17]
	v_mfma_f32_16x16x32_bf16 v[38:41], v[134:137], v[174:177], v[38:41]
	v_mfma_f32_16x16x32_bf16 v[6:9], v[142:145], v[174:177], v[6:9]
	s_barrier
	s_add_i32 s75, s66, s51
	s_add_u32 s98, s2, 0x80
	s_addc_u32 s99, s3, 0
	s_mov_b32 m0, s75
	ds_read_b128 v[200:203], v206
	ds_read_b128 v[212:215], v206 offset:1024
	ds_read_b128 v[216:219], v206 offset:2048
	ds_read_b128 v[220:223], v206 offset:3072
	global_load_lds_dwordx4 v186, s[2:3] sc0
	s_add_i32 m0, s75, 0x2000
	s_nop 0
	global_load_lds_dwordx4 v190, s[2:3] sc0
	s_barrier
	s_waitcnt lgkmcnt(0)
	v_mfma_f32_16x16x32_bf16 v[58:61], v[200:203], v[146:149], 0
	v_mfma_f32_16x16x32_bf16 v[26:29], v[216:219], v[146:149], 0
	v_mfma_f32_16x16x32_bf16 v[50:53], v[200:203], v[154:157], 0
	v_mfma_f32_16x16x32_bf16 v[18:21], v[216:219], v[154:157], 0
	v_mfma_f32_16x16x32_bf16 v[42:45], v[200:203], v[162:165], 0
	v_mfma_f32_16x16x32_bf16 v[10:13], v[216:219], v[162:165], 0
	v_mfma_f32_16x16x32_bf16 v[34:37], v[200:203], v[170:173], 0
	v_mfma_f32_16x16x32_bf16 v[2:5], v[216:219], v[170:173], 0
	v_mfma_f32_16x16x32_bf16 v[58:61], v[212:215], v[150:153], v[58:61]
	v_mfma_f32_16x16x32_bf16 v[26:29], v[220:223], v[150:153], v[26:29]
	v_mfma_f32_16x16x32_bf16 v[50:53], v[212:215], v[158:161], v[50:53]
	v_mfma_f32_16x16x32_bf16 v[18:21], v[220:223], v[158:161], v[18:21]
	v_mfma_f32_16x16x32_bf16 v[42:45], v[212:215], v[166:169], v[42:45]
	v_mfma_f32_16x16x32_bf16 v[10:13], v[220:223], v[166:169], v[10:13]
	v_mfma_f32_16x16x32_bf16 v[34:37], v[212:215], v[174:177], v[34:37]
	v_mfma_f32_16x16x32_bf16 v[2:5], v[220:223], v[174:177], v[2:5]
	s_barrier
	s_mov_b32 m0, s52
	s_add_u32 s100, s44, 0x80
	s_addc_u32 s101, s45, 0
	ds_read_b128 v[146:149], v183 offset:16384
	ds_read_b128 v[150:153], v183 offset:17408
	ds_read_b128 v[154:157], v183 offset:18432
	ds_read_b128 v[158:161], v183 offset:19456
	ds_read_b128 v[162:165], v183 offset:20480
	ds_read_b128 v[166:169], v183 offset:21504
	ds_read_b128 v[170:173], v183 offset:22528
	ds_read_b128 v[174:177], v183 offset:23552
	global_load_lds_dwordx4 v184, s[44:45] sc0
	s_mov_b32 m0, s53
	s_nop 0
	global_load_lds_dwordx4 v188, s[44:45] sc0
	s_barrier
	s_waitcnt lgkmcnt(0)
	v_mfma_f32_16x16x32_bf16 v[126:129], v[130:133], v[146:149], 0
	v_mfma_f32_16x16x32_bf16 v[102:105], v[138:141], v[146:149], 0
	v_mfma_f32_16x16x32_bf16 v[122:125], v[130:133], v[154:157], 0
	v_mfma_f32_16x16x32_bf16 v[90:93], v[138:141], v[154:157], 0
	v_mfma_f32_16x16x32_bf16 v[118:121], v[130:133], v[162:165], 0
	v_mfma_f32_16x16x32_bf16 v[78:81], v[138:141], v[162:165], 0
	v_mfma_f32_16x16x32_bf16 v[106:109], v[130:133], v[170:173], 0
	v_mfma_f32_16x16x32_bf16 v[70:73], v[138:141], v[170:173], 0
	v_mfma_f32_16x16x32_bf16 v[126:129], v[134:137], v[150:153], v[126:129]
	v_mfma_f32_16x16x32_bf16 v[102:105], v[142:145], v[150:153], v[102:105]
	v_mfma_f32_16x16x32_bf16 v[122:125], v[134:137], v[158:161], v[122:125]
	v_mfma_f32_16x16x32_bf16 v[90:93], v[142:145], v[158:161], v[90:93]
	v_mfma_f32_16x16x32_bf16 v[118:121], v[134:137], v[166:169], v[118:121]
	v_mfma_f32_16x16x32_bf16 v[78:81], v[142:145], v[166:169], v[78:81]
	v_mfma_f32_16x16x32_bf16 v[106:109], v[134:137], v[174:177], v[106:109]
	v_mfma_f32_16x16x32_bf16 v[70:73], v[142:145], v[174:177], v[70:73]
	s_barrier
	s_add_u32 s76, s2, 0x40000
	s_addc_u32 s77, s3, 0
	s_add_i32 s75, s67, s51
	s_mov_b32 m0, s75
	s_nop 0
	global_load_lds_dwordx4 v186, s[76:77] sc0
	s_add_i32 m0, s75, 0x2000
	s_nop 0
	global_load_lds_dwordx4 v190, s[76:77] sc0
	s_waitcnt vmcnt(6)
	s_barrier
	v_mfma_f32_16x16x32_bf16 v[114:117], v[200:203], v[146:149], 0
	v_mfma_f32_16x16x32_bf16 v[86:89], v[216:219], v[146:149], 0
	v_mfma_f32_16x16x32_bf16 v[110:113], v[200:203], v[154:157], 0
	v_mfma_f32_16x16x32_bf16 v[82:85], v[216:219], v[154:157], 0
	v_mfma_f32_16x16x32_bf16 v[98:101], v[200:203], v[162:165], 0
	v_mfma_f32_16x16x32_bf16 v[74:77], v[216:219], v[162:165], 0
	v_mfma_f32_16x16x32_bf16 v[94:97], v[200:203], v[170:173], 0
	v_mfma_f32_16x16x32_bf16 v[66:69], v[216:219], v[170:173], 0
	v_mfma_f32_16x16x32_bf16 v[114:117], v[212:215], v[150:153], v[114:117]
	v_mfma_f32_16x16x32_bf16 v[86:89], v[220:223], v[150:153], v[86:89]
	v_mfma_f32_16x16x32_bf16 v[110:113], v[212:215], v[158:161], v[110:113]
	v_mfma_f32_16x16x32_bf16 v[82:85], v[220:223], v[158:161], v[82:85]
	v_mfma_f32_16x16x32_bf16 v[98:101], v[212:215], v[166:169], v[98:101]
	v_mfma_f32_16x16x32_bf16 v[74:77], v[220:223], v[166:169], v[74:77]
	v_mfma_f32_16x16x32_bf16 v[94:97], v[212:215], v[174:177], v[94:97]
	v_mfma_f32_16x16x32_bf16 v[66:69], v[220:223], v[174:177], v[66:69]
	s_barrier
	s_add_i32 s75, 0, 0x18000
	v_add_u32_e32 v142, s75, v1
	ds_read_b128 v[130:133], v142
	ds_read_b128 v[134:137], v142 offset:1024
	ds_read_b128 v[138:141], v142 offset:2048
	ds_read_b128 v[142:145], v142 offset:3072
	s_add_u32 s44, s44, 0x40000
	s_addc_u32 s45, s45, 0
	s_mov_b32 m0, s54
	ds_read_b128 v[146:149], v183 offset:32768
	ds_read_b128 v[150:153], v183 offset:33792
	ds_read_b128 v[154:157], v183 offset:34816
	ds_read_b128 v[158:161], v183 offset:35840
	ds_read_b128 v[162:165], v183 offset:36864
	ds_read_b128 v[166:169], v183 offset:37888
	ds_read_b128 v[170:173], v183 offset:38912
	ds_read_b128 v[174:177], v183 offset:39936
	global_load_lds_dwordx4 v184, s[44:45] sc0
	s_mov_b32 m0, s55
	s_nop 0
	global_load_lds_dwordx4 v188, s[44:45] sc0
	s_waitcnt lgkmcnt(8)
	s_barrier
	s_waitcnt lgkmcnt(0)
	v_mfma_f32_16x16x32_bf16 v[62:65], v[130:133], v[146:149], v[62:65]
	v_mfma_f32_16x16x32_bf16 v[30:33], v[138:141], v[146:149], v[30:33]
	v_mfma_f32_16x16x32_bf16 v[54:57], v[130:133], v[154:157], v[54:57]
	v_mfma_f32_16x16x32_bf16 v[22:25], v[138:141], v[154:157], v[22:25]
	v_mfma_f32_16x16x32_bf16 v[46:49], v[130:133], v[162:165], v[46:49]
	v_mfma_f32_16x16x32_bf16 v[14:17], v[138:141], v[162:165], v[14:17]
	v_mfma_f32_16x16x32_bf16 v[38:41], v[130:133], v[170:173], v[38:41]
	v_mfma_f32_16x16x32_bf16 v[6:9], v[138:141], v[170:173], v[6:9]
	v_mfma_f32_16x16x32_bf16 v[62:65], v[134:137], v[150:153], v[62:65]
	v_mfma_f32_16x16x32_bf16 v[30:33], v[142:145], v[150:153], v[30:33]
	v_mfma_f32_16x16x32_bf16 v[54:57], v[134:137], v[158:161], v[54:57]
	v_mfma_f32_16x16x32_bf16 v[22:25], v[142:145], v[158:161], v[22:25]
	v_mfma_f32_16x16x32_bf16 v[46:49], v[134:137], v[166:169], v[46:49]
	v_mfma_f32_16x16x32_bf16 v[14:17], v[142:145], v[166:169], v[14:17]
	v_mfma_f32_16x16x32_bf16 v[38:41], v[134:137], v[174:177], v[38:41]
	v_mfma_f32_16x16x32_bf16 v[6:9], v[142:145], v[174:177], v[6:9]
	s_barrier
	s_add_i32 s44, 0, 0x1c000
	s_add_i32 s45, s75, s51
	v_add_u32_e32 v207, s44, v1
	s_mov_b32 m0, s45
	ds_read_b128 v[200:203], v207
	ds_read_b128 v[212:215], v207 offset:1024
	ds_read_b128 v[216:219], v207 offset:2048
	ds_read_b128 v[220:223], v207 offset:3072
	global_load_lds_dwordx4 v186, s[98:99] sc0
	s_add_i32 m0, s45, 0x2000
	s_nop 0
	global_load_lds_dwordx4 v190, s[98:99] sc0
	s_barrier
	s_waitcnt lgkmcnt(0)
	v_mfma_f32_16x16x32_bf16 v[58:61], v[200:203], v[146:149], v[58:61]
	v_mfma_f32_16x16x32_bf16 v[26:29], v[216:219], v[146:149], v[26:29]
	v_mfma_f32_16x16x32_bf16 v[50:53], v[200:203], v[154:157], v[50:53]
	v_mfma_f32_16x16x32_bf16 v[18:21], v[216:219], v[154:157], v[18:21]
	v_mfma_f32_16x16x32_bf16 v[42:45], v[200:203], v[162:165], v[42:45]
	v_mfma_f32_16x16x32_bf16 v[10:13], v[216:219], v[162:165], v[10:13]
	v_mfma_f32_16x16x32_bf16 v[34:37], v[200:203], v[170:173], v[34:37]
	v_mfma_f32_16x16x32_bf16 v[2:5], v[216:219], v[170:173], v[2:5]
	v_mfma_f32_16x16x32_bf16 v[58:61], v[212:215], v[150:153], v[58:61]
	v_mfma_f32_16x16x32_bf16 v[26:29], v[220:223], v[150:153], v[26:29]
	v_mfma_f32_16x16x32_bf16 v[50:53], v[212:215], v[158:161], v[50:53]
	v_mfma_f32_16x16x32_bf16 v[18:21], v[220:223], v[158:161], v[18:21]
	v_mfma_f32_16x16x32_bf16 v[42:45], v[212:215], v[166:169], v[42:45]
	v_mfma_f32_16x16x32_bf16 v[10:13], v[220:223], v[166:169], v[10:13]
	v_mfma_f32_16x16x32_bf16 v[34:37], v[212:215], v[174:177], v[34:37]
	v_mfma_f32_16x16x32_bf16 v[2:5], v[220:223], v[174:177], v[2:5]
	s_barrier
	s_mov_b32 m0, s59
	ds_read_b128 v[146:149], v183 offset:49152
	ds_read_b128 v[150:153], v183 offset:50176
	ds_read_b128 v[154:157], v183 offset:51200
	ds_read_b128 v[158:161], v183 offset:52224
	ds_read_b128 v[162:165], v183 offset:53248
	ds_read_b128 v[166:169], v183 offset:54272
	ds_read_b128 v[170:173], v183 offset:55296
	ds_read_b128 v[174:177], v183 offset:56320
	global_load_lds_dwordx4 v184, s[100:101] sc0
	s_mov_b32 m0, s60
	s_nop 0
	global_load_lds_dwordx4 v188, s[100:101] sc0
	s_barrier
	s_waitcnt lgkmcnt(0)
	v_mfma_f32_16x16x32_bf16 v[126:129], v[130:133], v[146:149], v[126:129]
	v_mfma_f32_16x16x32_bf16 v[102:105], v[138:141], v[146:149], v[102:105]
	v_mfma_f32_16x16x32_bf16 v[122:125], v[130:133], v[154:157], v[122:125]
	v_mfma_f32_16x16x32_bf16 v[90:93], v[138:141], v[154:157], v[90:93]
	v_mfma_f32_16x16x32_bf16 v[118:121], v[130:133], v[162:165], v[118:121]
	v_mfma_f32_16x16x32_bf16 v[78:81], v[138:141], v[162:165], v[78:81]
	v_mfma_f32_16x16x32_bf16 v[106:109], v[130:133], v[170:173], v[106:109]
	v_mfma_f32_16x16x32_bf16 v[70:73], v[138:141], v[170:173], v[70:73]
	v_mfma_f32_16x16x32_bf16 v[126:129], v[134:137], v[150:153], v[126:129]
	v_mfma_f32_16x16x32_bf16 v[102:105], v[142:145], v[150:153], v[102:105]
	v_mfma_f32_16x16x32_bf16 v[122:125], v[134:137], v[158:161], v[122:125]
	v_mfma_f32_16x16x32_bf16 v[90:93], v[142:145], v[158:161], v[90:93]
	v_mfma_f32_16x16x32_bf16 v[118:121], v[134:137], v[166:169], v[118:121]
	v_mfma_f32_16x16x32_bf16 v[78:81], v[142:145], v[166:169], v[78:81]
	v_mfma_f32_16x16x32_bf16 v[106:109], v[134:137], v[174:177], v[106:109]
	v_mfma_f32_16x16x32_bf16 v[70:73], v[142:145], v[174:177], v[70:73]
	s_barrier
	s_add_u32 s2, s2, 0x40080
	s_addc_u32 s3, s3, 0
	s_add_i32 s44, s44, s51
	s_mov_b32 m0, s44
	s_nop 0
	global_load_lds_dwordx4 v186, s[2:3] sc0
	s_add_i32 m0, s44, 0x2000
	s_nop 0
	global_load_lds_dwordx4 v190, s[2:3] sc0
	s_add_i32 s74, s74, 2
	s_add_u32 s0, s0, 0x100
	s_addc_u32 s1, s1, 0
	s_add_u32 s72, s72, 0x100
	s_addc_u32 s73, s73, 0
	s_cmp_gt_u32 s74, 13
	s_waitcnt vmcnt(6)
	s_barrier
	v_mfma_f32_16x16x32_bf16 v[114:117], v[200:203], v[146:149], v[114:117]
	v_mfma_f32_16x16x32_bf16 v[86:89], v[216:219], v[146:149], v[86:89]
	v_mfma_f32_16x16x32_bf16 v[110:113], v[200:203], v[154:157], v[110:113]
	v_mfma_f32_16x16x32_bf16 v[82:85], v[216:219], v[154:157], v[82:85]
	v_mfma_f32_16x16x32_bf16 v[98:101], v[200:203], v[162:165], v[98:101]
	v_mfma_f32_16x16x32_bf16 v[74:77], v[216:219], v[162:165], v[74:77]
	v_mfma_f32_16x16x32_bf16 v[94:97], v[200:203], v[170:173], v[94:97]
	v_mfma_f32_16x16x32_bf16 v[66:69], v[216:219], v[170:173], v[66:69]
	v_mfma_f32_16x16x32_bf16 v[114:117], v[212:215], v[150:153], v[114:117]
	v_mfma_f32_16x16x32_bf16 v[86:89], v[220:223], v[150:153], v[86:89]
	v_mfma_f32_16x16x32_bf16 v[110:113], v[212:215], v[158:161], v[110:113]
	v_mfma_f32_16x16x32_bf16 v[82:85], v[220:223], v[158:161], v[82:85]
	v_mfma_f32_16x16x32_bf16 v[98:101], v[212:215], v[166:169], v[98:101]
	v_mfma_f32_16x16x32_bf16 v[74:77], v[220:223], v[166:169], v[74:77]
	v_mfma_f32_16x16x32_bf16 v[94:97], v[212:215], v[174:177], v[94:97]
	v_mfma_f32_16x16x32_bf16 v[66:69], v[220:223], v[174:177], v[66:69]
	s_barrier
	s_cbranch_scc1 .Lpeel_p8_exit
.LBB0_1090:
	ds_read_b128 v[130:133], v181
	ds_read_b128 v[134:137], v181 offset:1024
	ds_read_b128 v[138:141], v181 offset:2048
	ds_read_b128 v[142:145], v181 offset:3072
	s_add_u32 s2, s0, 0xfffc0080
	s_addc_u32 s3, s1, -1
	s_cmp_eq_u32 s74, 12
	s_cselect_b32 s45, s33, s3
	s_cselect_b32 s44, s39, s2
	s_cselect_b32 s3, s37, s73
	s_cselect_b32 s2, s71, s72
	s_add_i32 m0, s52, 0xc000
	ds_read_b128 v[146:149], v183
	ds_read_b128 v[150:153], v183 offset:1024
	ds_read_b128 v[154:157], v183 offset:2048
	ds_read_b128 v[158:161], v183 offset:3072
	ds_read_b128 v[162:165], v183 offset:4096
	ds_read_b128 v[166:169], v183 offset:5120
	ds_read_b128 v[170:173], v183 offset:6144
	ds_read_b128 v[174:177], v183 offset:7168
	global_load_lds_dwordx4 v192, s[0:1] sc0
	s_add_i32 m0, s52, 0xe000
	s_nop 0
	global_load_lds_dwordx4 v194, s[0:1] sc0
	s_waitcnt lgkmcnt(8)
	s_barrier
	s_waitcnt lgkmcnt(0)
	v_mfma_f32_16x16x32_bf16 v[62:65], v[130:133], v[146:149], v[62:65]
	v_mfma_f32_16x16x32_bf16 v[30:33], v[138:141], v[146:149], v[30:33]
	v_mfma_f32_16x16x32_bf16 v[54:57], v[130:133], v[154:157], v[54:57]
	v_mfma_f32_16x16x32_bf16 v[22:25], v[138:141], v[154:157], v[22:25]
	v_mfma_f32_16x16x32_bf16 v[46:49], v[130:133], v[162:165], v[46:49]
	v_mfma_f32_16x16x32_bf16 v[14:17], v[138:141], v[162:165], v[14:17]
	v_mfma_f32_16x16x32_bf16 v[38:41], v[130:133], v[170:173], v[38:41]
	v_mfma_f32_16x16x32_bf16 v[6:9], v[138:141], v[170:173], v[6:9]
	v_mfma_f32_16x16x32_bf16 v[62:65], v[134:137], v[150:153], v[62:65]
	v_mfma_f32_16x16x32_bf16 v[30:33], v[142:145], v[150:153], v[30:33]
	v_mfma_f32_16x16x32_bf16 v[54:57], v[134:137], v[158:161], v[54:57]
	v_mfma_f32_16x16x32_bf16 v[22:25], v[142:145], v[158:161], v[22:25]
	v_mfma_f32_16x16x32_bf16 v[46:49], v[134:137], v[166:169], v[46:49]
	v_mfma_f32_16x16x32_bf16 v[14:17], v[142:145], v[166:169], v[14:17]
	v_mfma_f32_16x16x32_bf16 v[38:41], v[134:137], v[174:177], v[38:41]
	v_mfma_f32_16x16x32_bf16 v[6:9], v[142:145], v[174:177], v[6:9]
	s_barrier
	s_add_i32 s75, s66, s51
	s_add_u32 s98, s2, 0x80
	s_addc_u32 s99, s3, 0
	s_mov_b32 m0, s75
	ds_read_b128 v[200:203], v206
	ds_read_b128 v[212:215], v206 offset:1024
	ds_read_b128 v[216:219], v206 offset:2048
	ds_read_b128 v[220:223], v206 offset:3072
	global_load_lds_dwordx4 v186, s[2:3] sc0
	s_add_i32 m0, s75, 0x2000
	s_nop 0
	global_load_lds_dwordx4 v190, s[2:3] sc0
	s_barrier
	s_waitcnt lgkmcnt(0)
	v_mfma_f32_16x16x32_bf16 v[58:61], v[200:203], v[146:149], v[58:61]
	v_mfma_f32_16x16x32_bf16 v[26:29], v[216:219], v[146:149], v[26:29]
	v_mfma_f32_16x16x32_bf16 v[50:53], v[200:203], v[154:157], v[50:53]
	v_mfma_f32_16x16x32_bf16 v[18:21], v[216:219], v[154:157], v[18:21]
	v_mfma_f32_16x16x32_bf16 v[42:45], v[200:203], v[162:165], v[42:45]
	v_mfma_f32_16x16x32_bf16 v[10:13], v[216:219], v[162:165], v[10:13]
	v_mfma_f32_16x16x32_bf16 v[34:37], v[200:203], v[170:173], v[34:37]
	v_mfma_f32_16x16x32_bf16 v[2:5], v[216:219], v[170:173], v[2:5]
	v_mfma_f32_16x16x32_bf16 v[58:61], v[212:215], v[150:153], v[58:61]
	v_mfma_f32_16x16x32_bf16 v[26:29], v[220:223], v[150:153], v[26:29]
	v_mfma_f32_16x16x32_bf16 v[50:53], v[212:215], v[158:161], v[50:53]
	v_mfma_f32_16x16x32_bf16 v[18:21], v[220:223], v[158:161], v[18:21]
	v_mfma_f32_16x16x32_bf16 v[42:45], v[212:215], v[166:169], v[42:45]
	v_mfma_f32_16x16x32_bf16 v[10:13], v[220:223], v[166:169], v[10:13]
	v_mfma_f32_16x16x32_bf16 v[34:37], v[212:215], v[174:177], v[34:37]
	v_mfma_f32_16x16x32_bf16 v[2:5], v[220:223], v[174:177], v[2:5]
	s_barrier
	s_mov_b32 m0, s52
	s_add_u32 s100, s44, 0x80
	s_addc_u32 s101, s45, 0
	ds_read_b128 v[146:149], v183 offset:16384
	ds_read_b128 v[150:153], v183 offset:17408
	ds_read_b128 v[154:157], v183 offset:18432
	ds_read_b128 v[158:161], v183 offset:19456
	ds_read_b128 v[162:165], v183 offset:20480
	ds_read_b128 v[166:169], v183 offset:21504
	ds_read_b128 v[170:173], v183 offset:22528
	ds_read_b128 v[174:177], v183 offset:23552
	global_load_lds_dwordx4 v184, s[44:45] sc0
	s_mov_b32 m0, s53
	s_nop 0
	global_load_lds_dwordx4 v188, s[44:45] sc0
	s_barrier
	s_waitcnt lgkmcnt(0)
	v_mfma_f32_16x16x32_bf16 v[126:129], v[130:133], v[146:149], v[126:129]
	v_mfma_f32_16x16x32_bf16 v[102:105], v[138:141], v[146:149], v[102:105]
	v_mfma_f32_16x16x32_bf16 v[122:125], v[130:133], v[154:157], v[122:125]
	v_mfma_f32_16x16x32_bf16 v[90:93], v[138:141], v[154:157], v[90:93]
	v_mfma_f32_16x16x32_bf16 v[118:121], v[130:133], v[162:165], v[118:121]
	v_mfma_f32_16x16x32_bf16 v[78:81], v[138:141], v[162:165], v[78:81]
	v_mfma_f32_16x16x32_bf16 v[106:109], v[130:133], v[170:173], v[106:109]
	v_mfma_f32_16x16x32_bf16 v[70:73], v[138:141], v[170:173], v[70:73]
	v_mfma_f32_16x16x32_bf16 v[126:129], v[134:137], v[150:153], v[126:129]
	v_mfma_f32_16x16x32_bf16 v[102:105], v[142:145], v[150:153], v[102:105]
	v_mfma_f32_16x16x32_bf16 v[122:125], v[134:137], v[158:161], v[122:125]
	v_mfma_f32_16x16x32_bf16 v[90:93], v[142:145], v[158:161], v[90:93]
	v_mfma_f32_16x16x32_bf16 v[118:121], v[134:137], v[166:169], v[118:121]
	v_mfma_f32_16x16x32_bf16 v[78:81], v[142:145], v[166:169], v[78:81]
	v_mfma_f32_16x16x32_bf16 v[106:109], v[134:137], v[174:177], v[106:109]
	v_mfma_f32_16x16x32_bf16 v[70:73], v[142:145], v[174:177], v[70:73]
	s_barrier
	s_add_u32 s76, s2, 0x40000
	s_addc_u32 s77, s3, 0
	s_add_i32 s75, s67, s51
	s_mov_b32 m0, s75
	s_nop 0
	global_load_lds_dwordx4 v186, s[76:77] sc0
	s_add_i32 m0, s75, 0x2000
	s_nop 0
	global_load_lds_dwordx4 v190, s[76:77] sc0
	s_waitcnt vmcnt(6)
	s_barrier
	v_mfma_f32_16x16x32_bf16 v[114:117], v[200:203], v[146:149], v[114:117]
	v_mfma_f32_16x16x32_bf16 v[86:89], v[216:219], v[146:149], v[86:89]
	v_mfma_f32_16x16x32_bf16 v[110:113], v[200:203], v[154:157], v[110:113]
	v_mfma_f32_16x16x32_bf16 v[82:85], v[216:219], v[154:157], v[82:85]
	v_mfma_f32_16x16x32_bf16 v[98:101], v[200:203], v[162:165], v[98:101]
	v_mfma_f32_16x16x32_bf16 v[74:77], v[216:219], v[162:165], v[74:77]
	v_mfma_f32_16x16x32_bf16 v[94:97], v[200:203], v[170:173], v[94:97]
	v_mfma_f32_16x16x32_bf16 v[66:69], v[216:219], v[170:173], v[66:69]
	v_mfma_f32_16x16x32_bf16 v[114:117], v[212:215], v[150:153], v[114:117]
	v_mfma_f32_16x16x32_bf16 v[86:89], v[220:223], v[150:153], v[86:89]
	v_mfma_f32_16x16x32_bf16 v[110:113], v[212:215], v[158:161], v[110:113]
	v_mfma_f32_16x16x32_bf16 v[82:85], v[220:223], v[158:161], v[82:85]
	v_mfma_f32_16x16x32_bf16 v[98:101], v[212:215], v[166:169], v[98:101]
	v_mfma_f32_16x16x32_bf16 v[74:77], v[220:223], v[166:169], v[74:77]
	v_mfma_f32_16x16x32_bf16 v[94:97], v[212:215], v[174:177], v[94:97]
	v_mfma_f32_16x16x32_bf16 v[66:69], v[220:223], v[174:177], v[66:69]
	s_barrier
	s_add_i32 s75, 0, 0x18000
	v_add_u32_e32 v142, s75, v1
	ds_read_b128 v[130:133], v142
	ds_read_b128 v[134:137], v142 offset:1024
	ds_read_b128 v[138:141], v142 offset:2048
	ds_read_b128 v[142:145], v142 offset:3072
	s_add_u32 s44, s44, 0x40000
	s_addc_u32 s45, s45, 0
	s_mov_b32 m0, s54
	ds_read_b128 v[146:149], v183 offset:32768
	ds_read_b128 v[150:153], v183 offset:33792
	ds_read_b128 v[154:157], v183 offset:34816
	ds_read_b128 v[158:161], v183 offset:35840
	ds_read_b128 v[162:165], v183 offset:36864
	ds_read_b128 v[166:169], v183 offset:37888
	ds_read_b128 v[170:173], v183 offset:38912
	ds_read_b128 v[174:177], v183 offset:39936
	global_load_lds_dwordx4 v184, s[44:45] sc0
	s_mov_b32 m0, s55
	s_nop 0
	global_load_lds_dwordx4 v188, s[44:45] sc0
	s_waitcnt lgkmcnt(8)
	s_barrier
	s_waitcnt lgkmcnt(0)
	v_mfma_f32_16x16x32_bf16 v[62:65], v[130:133], v[146:149], v[62:65]
	v_mfma_f32_16x16x32_bf16 v[30:33], v[138:141], v[146:149], v[30:33]
	v_mfma_f32_16x16x32_bf16 v[54:57], v[130:133], v[154:157], v[54:57]
	v_mfma_f32_16x16x32_bf16 v[22:25], v[138:141], v[154:157], v[22:25]
	v_mfma_f32_16x16x32_bf16 v[46:49], v[130:133], v[162:165], v[46:49]
	v_mfma_f32_16x16x32_bf16 v[14:17], v[138:141], v[162:165], v[14:17]
	v_mfma_f32_16x16x32_bf16 v[38:41], v[130:133], v[170:173], v[38:41]
	v_mfma_f32_16x16x32_bf16 v[6:9], v[138:141], v[170:173], v[6:9]
	v_mfma_f32_16x16x32_bf16 v[62:65], v[134:137], v[150:153], v[62:65]
	v_mfma_f32_16x16x32_bf16 v[30:33], v[142:145], v[150:153], v[30:33]
	v_mfma_f32_16x16x32_bf16 v[54:57], v[134:137], v[158:161], v[54:57]
	v_mfma_f32_16x16x32_bf16 v[22:25], v[142:145], v[158:161], v[22:25]
	v_mfma_f32_16x16x32_bf16 v[46:49], v[134:137], v[166:169], v[46:49]
	v_mfma_f32_16x16x32_bf16 v[14:17], v[142:145], v[166:169], v[14:17]
	v_mfma_f32_16x16x32_bf16 v[38:41], v[134:137], v[174:177], v[38:41]
	v_mfma_f32_16x16x32_bf16 v[6:9], v[142:145], v[174:177], v[6:9]
	s_barrier
	s_add_i32 s44, 0, 0x1c000
	s_add_i32 s45, s75, s51
	v_add_u32_e32 v207, s44, v1
	s_mov_b32 m0, s45
	ds_read_b128 v[200:203], v207
	ds_read_b128 v[212:215], v207 offset:1024
	ds_read_b128 v[216:219], v207 offset:2048
	ds_read_b128 v[220:223], v207 offset:3072
	global_load_lds_dwordx4 v186, s[98:99] sc0
	s_add_i32 m0, s45, 0x2000
	s_nop 0
	global_load_lds_dwordx4 v190, s[98:99] sc0
	s_barrier
	s_waitcnt lgkmcnt(0)
	v_mfma_f32_16x16x32_bf16 v[58:61], v[200:203], v[146:149], v[58:61]
	v_mfma_f32_16x16x32_bf16 v[26:29], v[216:219], v[146:149], v[26:29]
	v_mfma_f32_16x16x32_bf16 v[50:53], v[200:203], v[154:157], v[50:53]
	v_mfma_f32_16x16x32_bf16 v[18:21], v[216:219], v[154:157], v[18:21]
	v_mfma_f32_16x16x32_bf16 v[42:45], v[200:203], v[162:165], v[42:45]
	v_mfma_f32_16x16x32_bf16 v[10:13], v[216:219], v[162:165], v[10:13]
	v_mfma_f32_16x16x32_bf16 v[34:37], v[200:203], v[170:173], v[34:37]
	v_mfma_f32_16x16x32_bf16 v[2:5], v[216:219], v[170:173], v[2:5]
	v_mfma_f32_16x16x32_bf16 v[58:61], v[212:215], v[150:153], v[58:61]
	v_mfma_f32_16x16x32_bf16 v[26:29], v[220:223], v[150:153], v[26:29]
	v_mfma_f32_16x16x32_bf16 v[50:53], v[212:215], v[158:161], v[50:53]
	v_mfma_f32_16x16x32_bf16 v[18:21], v[220:223], v[158:161], v[18:21]
	v_mfma_f32_16x16x32_bf16 v[42:45], v[212:215], v[166:169], v[42:45]
	v_mfma_f32_16x16x32_bf16 v[10:13], v[220:223], v[166:169], v[10:13]
	v_mfma_f32_16x16x32_bf16 v[34:37], v[212:215], v[174:177], v[34:37]
	v_mfma_f32_16x16x32_bf16 v[2:5], v[220:223], v[174:177], v[2:5]
	s_barrier
	s_mov_b32 m0, s59
	ds_read_b128 v[146:149], v183 offset:49152
	ds_read_b128 v[150:153], v183 offset:50176
	ds_read_b128 v[154:157], v183 offset:51200
	ds_read_b128 v[158:161], v183 offset:52224
	ds_read_b128 v[162:165], v183 offset:53248
	ds_read_b128 v[166:169], v183 offset:54272
	ds_read_b128 v[170:173], v183 offset:55296
	ds_read_b128 v[174:177], v183 offset:56320
	global_load_lds_dwordx4 v184, s[100:101] sc0
	s_mov_b32 m0, s60
	s_nop 0
	global_load_lds_dwordx4 v188, s[100:101] sc0
	s_barrier
	s_waitcnt lgkmcnt(0)
	v_mfma_f32_16x16x32_bf16 v[126:129], v[130:133], v[146:149], v[126:129]
	v_mfma_f32_16x16x32_bf16 v[102:105], v[138:141], v[146:149], v[102:105]
	v_mfma_f32_16x16x32_bf16 v[122:125], v[130:133], v[154:157], v[122:125]
	v_mfma_f32_16x16x32_bf16 v[90:93], v[138:141], v[154:157], v[90:93]
	v_mfma_f32_16x16x32_bf16 v[118:121], v[130:133], v[162:165], v[118:121]
	v_mfma_f32_16x16x32_bf16 v[78:81], v[138:141], v[162:165], v[78:81]
	v_mfma_f32_16x16x32_bf16 v[106:109], v[130:133], v[170:173], v[106:109]
	v_mfma_f32_16x16x32_bf16 v[70:73], v[138:141], v[170:173], v[70:73]
	v_mfma_f32_16x16x32_bf16 v[126:129], v[134:137], v[150:153], v[126:129]
	v_mfma_f32_16x16x32_bf16 v[102:105], v[142:145], v[150:153], v[102:105]
	v_mfma_f32_16x16x32_bf16 v[122:125], v[134:137], v[158:161], v[122:125]
	v_mfma_f32_16x16x32_bf16 v[90:93], v[142:145], v[158:161], v[90:93]
	v_mfma_f32_16x16x32_bf16 v[118:121], v[134:137], v[166:169], v[118:121]
	v_mfma_f32_16x16x32_bf16 v[78:81], v[142:145], v[166:169], v[78:81]
	v_mfma_f32_16x16x32_bf16 v[106:109], v[134:137], v[174:177], v[106:109]
	v_mfma_f32_16x16x32_bf16 v[70:73], v[142:145], v[174:177], v[70:73]
	s_barrier
	s_add_u32 s2, s2, 0x40080
	s_addc_u32 s3, s3, 0
	s_add_i32 s44, s44, s51
	s_mov_b32 m0, s44
	s_nop 0
	global_load_lds_dwordx4 v186, s[2:3] sc0
	s_add_i32 m0, s44, 0x2000
	s_nop 0
	global_load_lds_dwordx4 v190, s[2:3] sc0
	s_add_i32 s74, s74, 2
	s_add_u32 s0, s0, 0x100
	s_addc_u32 s1, s1, 0
	s_add_u32 s72, s72, 0x100
	s_addc_u32 s73, s73, 0
	s_cmp_gt_u32 s74, 13
	s_waitcnt vmcnt(6)
	s_barrier
	v_mfma_f32_16x16x32_bf16 v[114:117], v[200:203], v[146:149], v[114:117]
	v_mfma_f32_16x16x32_bf16 v[86:89], v[216:219], v[146:149], v[86:89]
	v_mfma_f32_16x16x32_bf16 v[110:113], v[200:203], v[154:157], v[110:113]
	v_mfma_f32_16x16x32_bf16 v[82:85], v[216:219], v[154:157], v[82:85]
	v_mfma_f32_16x16x32_bf16 v[98:101], v[200:203], v[162:165], v[98:101]
	v_mfma_f32_16x16x32_bf16 v[74:77], v[216:219], v[162:165], v[74:77]
	v_mfma_f32_16x16x32_bf16 v[94:97], v[200:203], v[170:173], v[94:97]
	v_mfma_f32_16x16x32_bf16 v[66:69], v[216:219], v[170:173], v[66:69]
	v_mfma_f32_16x16x32_bf16 v[114:117], v[212:215], v[150:153], v[114:117]
	v_mfma_f32_16x16x32_bf16 v[86:89], v[220:223], v[150:153], v[86:89]
	v_mfma_f32_16x16x32_bf16 v[110:113], v[212:215], v[158:161], v[110:113]
	v_mfma_f32_16x16x32_bf16 v[82:85], v[220:223], v[158:161], v[82:85]
	v_mfma_f32_16x16x32_bf16 v[98:101], v[212:215], v[166:169], v[98:101]
	v_mfma_f32_16x16x32_bf16 v[74:77], v[220:223], v[166:169], v[74:77]
	v_mfma_f32_16x16x32_bf16 v[94:97], v[212:215], v[174:177], v[94:97]
	v_mfma_f32_16x16x32_bf16 v[66:69], v[220:223], v[174:177], v[66:69]
	s_barrier
	s_cbranch_scc0 .LBB0_1090

.LBB0_1183:
	v_lshlrev_b32_e32 v5, 1, v4
	v_lshrrev_b32_e32 v6, 5, v0
	v_and_b32_e32 v5, 24, v5
	v_and_b32_e32 v6, 4, v6
	v_and_b32_e32 v4, 3, v4
	v_or3_b32 v4, v6, v4, v5
	s_movk_i32 s2, 0x60
	v_and_or_b32 v3, v3, s2, v4
	s_lshr_b32 s2, s26, 6
	s_lshr_b32 s1, s26, 8
	s_lshl_b32 s27, s2, 10
	s_add_u32 s28, s94, 0x4212400
	s_addc_u32 s29, s95, 0
	s_add_i32 s0, s3, s0
	s_ashr_i32 s3, s0, 31
	s_lshr_b32 s3, s3, 27
	s_add_i32 s3, s0, s3
	s_ashr_i32 s4, s3, 5
	s_and_b32 s3, s3, 0xffe0
	s_sub_i32 s3, s0, s3
	s_bfe_i32 s0, s3, 0x80000
	s_bfe_u32 s0, s0, 0x3000c
	s_add_i32 s5, s3, s0
	s_bfe_i32 s0, s5, 0x80000
	s_and_b32 s5, s5, 0xf8
	s_sext_i32_i16 s8, s0
	s_sub_i32 s3, s3, s5
	s_lshl_b32 s4, s4, 3
	s_sext_i32_i8 s3, s3
	s_ashr_i32 s5, s8, 3
	v_and_or_b32 v5, v179, 32, v4
	s_lshr_b32 s0, s8, 3
	s_add_i32 s50, s4, s3
	s_mul_hi_i32 s8, s5, 0x160000
	s_mul_i32 s5, s5, 0x160000
	v_mul_u32_u24_e32 v5, 0xb00, v5
	s_add_u32 s18, s24, s5
	v_or_b32_e32 v5, v5, v2
	s_addc_u32 s19, s25, s8
	s_add_i32 s30, s27, 0
	v_lshlrev_b32_e32 v134, 1, v5
	v_mul_u32_u24_e32 v3, 0xb00, v3
	s_add_i32 m0, s30, 0x10000
	v_or_b32_e32 v2, v3, v2
	s_mul_i32 s4, s50, 0x160000
	global_load_lds_dwordx4 v134, s[18:19] sc0
	s_add_i32 m0, s30, 0x12000
	v_lshlrev_b32_e32 v136, 1, v2
	s_mul_hi_i32 s3, s50, 0x160000
	s_add_u32 s16, s28, s4
	global_load_lds_dwordx4 v136, s[18:19] sc0
	s_addc_u32 s17, s29, s3
	s_mov_b32 m0, s30
	s_add_i32 s31, s30, 0x2000
	global_load_lds_dwordx4 v130, s[16:17] sc0
	s_mov_b32 m0, s31
	s_add_u32 s4, s18, 0xb0000
	global_load_lds_dwordx4 v132, s[16:17] sc0
	s_addc_u32 s5, s19, 0
	s_add_i32 m0, s30, 0x14000
	v_mov_b32_e32 v135, 0
	global_load_lds_dwordx4 v134, s[4:5] sc0
	s_add_i32 m0, s30, 0x16000
	v_mov_b32_e32 v137, v135
	global_load_lds_dwordx4 v136, s[4:5] sc0
	s_add_u32 s4, s16, 0xb0000
	s_addc_u32 s5, s17, 0
	s_add_i32 s33, s30, 0x4000
	s_mov_b32 m0, s33
	s_add_i32 s34, s30, 0x6000
	global_load_lds_dwordx4 v130, s[4:5] sc0
	s_mov_b32 m0, s34
	v_mov_b32_e32 v131, v135
	global_load_lds_dwordx4 v132, s[4:5] sc0
	v_mov_b32_e32 v133, v135
	s_mov_b32 s9, 0
	s_mov_b32 s35, 0x10000
	v_lshl_add_u64 v[8:9], s[18:19], 0, v[134:135]
	v_lshl_add_u64 v[6:7], s[18:19], 0, v[136:137]
	v_lshl_add_u64 v[4:5], s[16:17], 0, v[130:131]
	s_cmp_lg_u32 s1, 1
	v_lshl_add_u64 v[2:3], s[16:17], 0, v[132:133]
	s_cbranch_scc1 .LBB0_1185
	s_barrier
.LBB0_1185:
	s_add_u32 s10, s94, 0xbf0cc00
	s_addc_u32 s11, s95, 0
	s_add_u32 s12, s94, 0x1f80000
	s_mov_b64 s[14:15], 0x80
	s_addc_u32 s13, s95, 0
	s_lshl_b32 s2, s2, 5
	s_add_i32 m0, s30, 0x18000
	v_lshl_add_u64 v[8:9], v[8:9], 0, s[14:15]
	s_lshl_b32 s36, s1, 6
	s_lshl_b32 s1, s1, 13
	s_and_b32 s8, s2, 0x60
	s_waitcnt vmcnt(4)
	s_barrier
	global_load_lds_dwordx4 v[8:9], off sc0
	v_lshl_add_u64 v[6:7], v[6:7], 0, s[14:15]
	s_add_i32 m0, s30, 0x1a000
	s_add_i32 s37, s30, 0x8000
	s_add_i32 s38, s30, 0xa000
	global_load_lds_dwordx4 v[6:7], off sc0
	v_lshl_add_u64 v[4:5], v[4:5], 0, s[14:15]
	s_mov_b32 m0, s37
	s_add_u32 s2, s18, 0xb0080
	global_load_lds_dwordx4 v[4:5], off sc0
	v_lshl_add_u64 v[2:3], v[2:3], 0, s[14:15]
	s_mov_b32 m0, s38
	s_addc_u32 s3, s19, 0
	global_load_lds_dwordx4 v[2:3], off sc0
	s_add_i32 m0, s30, 0x1c000
	v_lshl_add_u64 v[2:3], s[2:3], 0, v[134:135]
	global_load_lds_dwordx4 v[2:3], off sc0
	v_lshl_add_u64 v[2:3], s[2:3], 0, v[136:137]
	s_add_i32 m0, s30, 0x1e000
	v_lshl_or_b32 v148, s8, 7, v1
	global_load_lds_dwordx4 v[2:3], off sc0
	v_lshlrev_b32_e32 v3, 2, v178
	v_lshl_or_b32 v2, v178, 6, v204
	v_and_b32_e32 v3, 32, v3
	v_bitop3_b32 v2, v2, s1, v3 bitop3:0xde
	s_waitcnt vmcnt(6)
	v_add_u16_e32 v3, v10, v11
	v_lshrrev_b16_e32 v3, 1, v3
	s_add_i32 s41, 0, 0x10000
	s_add_i32 s42, 0, 0x14000
	s_sext_i32_i8 s51, s0
	s_mov_b32 s39, 0x18000
	s_mov_b32 s40, 0x8000
	v_add_lshl_u32 v138, v12, v3, 1
	v_mov_b32_e32 v139, v135
	v_add_lshl_u32 v140, v13, v3, 1
	v_mov_b32_e32 v141, v135
	v_mov_b64_e32 v[142:143], 0x100
	v_mov_b64_e32 v[144:145], 0xff
	v_add_u32_e32 v149, s41, v148
	v_add_u32_e32 v150, 0, v2
	v_add_u32_e32 v151, s42, v148
	s_mov_b32 s43, 0x40000
	s_mov_b32 s44, 0x48000
	s_mov_b32 s45, 0x50000
	s_mov_b32 s46, 0x58000
	s_mov_b32 s47, s9
	s_barrier

.Lpeel_p10:
	ds_read_b128 v[152:155], v149
	ds_read_b128 v[156:159], v149 offset:1024
	ds_read_b128 v[160:163], v149 offset:2048
	ds_read_b128 v[164:167], v149 offset:3072
	s_add_u32 s18, s16, 0xfff50080
	s_addc_u32 s19, s17, -1
	s_cmp_eq_u32 s54, 40
	s_cselect_b32 s21, s3, s19
	s_cselect_b32 s20, s2, s18
	s_cselect_b32 s19, s5, s53
	s_cselect_b32 s18, s4, s52
	s_add_i32 m0, s30, 0xc000
	ds_read_b128 v[168:171], v150
	ds_read_b128 v[172:175], v150 offset:1024
	ds_read_b128 v[180:183], v150 offset:2048
	ds_read_b128 v[184:187], v150 offset:3072
	ds_read_b128 v[188:191], v150 offset:4096
	ds_read_b128 v[192:195], v150 offset:5120
	ds_read_b128 v[196:199], v150 offset:6144
	ds_read_b128 v[200:203], v150 offset:7168
	global_load_lds_dwordx4 v138, s[16:17] sc0
	s_add_i32 m0, s30, 0xe000
	s_nop 0
	global_load_lds_dwordx4 v140, s[16:17] sc0
	s_waitcnt lgkmcnt(8)
	s_barrier
	s_waitcnt lgkmcnt(0)
	v_mfma_f32_16x16x32_bf16 v[126:129], v[152:155], v[168:171], 0
	v_mfma_f32_16x16x32_bf16 v[122:125], v[160:163], v[168:171], 0
	v_mfma_f32_16x16x32_bf16 v[114:117], v[152:155], v[180:183], 0
	v_mfma_f32_16x16x32_bf16 v[106:109], v[160:163], v[180:183], 0
	v_mfma_f32_16x16x32_bf16 v[98:101], v[152:155], v[188:191], 0
	v_mfma_f32_16x16x32_bf16 v[90:93], v[160:163], v[188:191], 0
	v_mfma_f32_16x16x32_bf16 v[82:85], v[152:155], v[196:199], 0
	v_mfma_f32_16x16x32_bf16 v[74:77], v[160:163], v[196:199], 0
	v_mfma_f32_16x16x32_bf16 v[126:129], v[156:159], v[172:175], v[126:129]
	v_mfma_f32_16x16x32_bf16 v[122:125], v[164:167], v[172:175], v[122:125]
	v_mfma_f32_16x16x32_bf16 v[114:117], v[156:159], v[184:187], v[114:117]
	v_mfma_f32_16x16x32_bf16 v[106:109], v[164:167], v[184:187], v[106:109]
	v_mfma_f32_16x16x32_bf16 v[98:101], v[156:159], v[192:195], v[98:101]
	v_mfma_f32_16x16x32_bf16 v[90:93], v[164:167], v[192:195], v[90:93]
	v_mfma_f32_16x16x32_bf16 v[82:85], v[156:159], v[200:203], v[82:85]
	v_mfma_f32_16x16x32_bf16 v[74:77], v[164:167], v[200:203], v[74:77]
	s_barrier
	s_add_i32 s55, s41, s27
	s_add_u32 s98, s18, 0x80
	s_addc_u32 s99, s19, 0
	s_mov_b32 m0, s55
	ds_read_b128 v[206:209], v151
	ds_read_b128 v[212:215], v151 offset:1024
	ds_read_b128 v[216:219], v151 offset:2048
	ds_read_b128 v[220:223], v151 offset:3072
	global_load_lds_dwordx4 v134, s[18:19] sc0
	s_add_i32 m0, s55, 0x2000
	s_nop 0
	global_load_lds_dwordx4 v136, s[18:19] sc0
	s_barrier
	s_waitcnt lgkmcnt(0)
	v_mfma_f32_16x16x32_bf16 v[118:121], v[206:209], v[168:171], 0
	v_mfma_f32_16x16x32_bf16 v[110:113], v[216:219], v[168:171], 0
	v_mfma_f32_16x16x32_bf16 v[102:105], v[206:209], v[180:183], 0
	v_mfma_f32_16x16x32_bf16 v[94:97], v[216:219], v[180:183], 0
	v_mfma_f32_16x16x32_bf16 v[86:89], v[206:209], v[188:191], 0
	v_mfma_f32_16x16x32_bf16 v[78:81], v[216:219], v[188:191], 0
	v_mfma_f32_16x16x32_bf16 v[70:73], v[206:209], v[196:199], 0
	v_mfma_f32_16x16x32_bf16 v[66:69], v[216:219], v[196:199], 0
	v_mfma_f32_16x16x32_bf16 v[118:121], v[212:215], v[172:175], v[118:121]
	v_mfma_f32_16x16x32_bf16 v[110:113], v[220:223], v[172:175], v[110:113]
	v_mfma_f32_16x16x32_bf16 v[102:105], v[212:215], v[184:187], v[102:105]
	v_mfma_f32_16x16x32_bf16 v[94:97], v[220:223], v[184:187], v[94:97]
	v_mfma_f32_16x16x32_bf16 v[86:89], v[212:215], v[192:195], v[86:89]
	v_mfma_f32_16x16x32_bf16 v[78:81], v[220:223], v[192:195], v[78:81]
	v_mfma_f32_16x16x32_bf16 v[70:73], v[212:215], v[200:203], v[70:73]
	v_mfma_f32_16x16x32_bf16 v[66:69], v[220:223], v[200:203], v[66:69]
	s_barrier
	s_mov_b32 m0, s30
	s_add_u32 s100, s20, 0x80
	s_addc_u32 s101, s21, 0
	ds_read_b128 v[168:171], v150 offset:16384
	ds_read_b128 v[172:175], v150 offset:17408
	ds_read_b128 v[180:183], v150 offset:18432
	ds_read_b128 v[184:187], v150 offset:19456
	ds_read_b128 v[188:191], v150 offset:20480
	ds_read_b128 v[192:195], v150 offset:21504
	ds_read_b128 v[196:199], v150 offset:22528
	ds_read_b128 v[200:203], v150 offset:23552
	global_load_lds_dwordx4 v130, s[20:21] sc0
	s_mov_b32 m0, s31
	s_nop 0
	global_load_lds_dwordx4 v132, s[20:21] sc0
	s_barrier
	s_waitcnt lgkmcnt(0)
	v_mfma_f32_16x16x32_bf16 v[62:65], v[152:155], v[168:171], 0
	v_mfma_f32_16x16x32_bf16 v[58:61], v[160:163], v[168:171], 0
	v_mfma_f32_16x16x32_bf16 v[50:53], v[152:155], v[180:183], 0
	v_mfma_f32_16x16x32_bf16 v[42:45], v[160:163], v[180:183], 0
	v_mfma_f32_16x16x32_bf16 v[34:37], v[152:155], v[188:191], 0
	v_mfma_f32_16x16x32_bf16 v[26:29], v[160:163], v[188:191], 0
	v_mfma_f32_16x16x32_bf16 v[18:21], v[152:155], v[196:199], 0
	v_mfma_f32_16x16x32_bf16 v[10:13], v[160:163], v[196:199], 0
	v_mfma_f32_16x16x32_bf16 v[62:65], v[156:159], v[172:175], v[62:65]
	v_mfma_f32_16x16x32_bf16 v[58:61], v[164:167], v[172:175], v[58:61]
	v_mfma_f32_16x16x32_bf16 v[50:53], v[156:159], v[184:187], v[50:53]
	v_mfma_f32_16x16x32_bf16 v[42:45], v[164:167], v[184:187], v[42:45]
	v_mfma_f32_16x16x32_bf16 v[34:37], v[156:159], v[192:195], v[34:37]
	v_mfma_f32_16x16x32_bf16 v[26:29], v[164:167], v[192:195], v[26:29]
	v_mfma_f32_16x16x32_bf16 v[18:21], v[156:159], v[200:203], v[18:21]
	v_mfma_f32_16x16x32_bf16 v[10:13], v[164:167], v[200:203], v[10:13]
	s_barrier
	s_add_u32 s56, s18, 0xb0000
	s_addc_u32 s57, s19, 0
	s_add_i32 s55, s42, s27
	s_mov_b32 m0, s55
	s_nop 0
	global_load_lds_dwordx4 v134, s[56:57] sc0
	s_add_i32 m0, s55, 0x2000
	s_nop 0
	global_load_lds_dwordx4 v136, s[56:57] sc0
	s_waitcnt vmcnt(6)
	s_barrier
	v_mfma_f32_16x16x32_bf16 v[54:57], v[206:209], v[168:171], 0
	v_mfma_f32_16x16x32_bf16 v[46:49], v[216:219], v[168:171], 0
	v_mfma_f32_16x16x32_bf16 v[38:41], v[206:209], v[180:183], 0
	v_mfma_f32_16x16x32_bf16 v[30:33], v[216:219], v[180:183], 0
	v_mfma_f32_16x16x32_bf16 v[22:25], v[206:209], v[188:191], 0
	v_mfma_f32_16x16x32_bf16 v[14:17], v[216:219], v[188:191], 0
	v_mfma_f32_16x16x32_bf16 v[6:9], v[206:209], v[196:199], 0
	v_mfma_f32_16x16x32_bf16 v[2:5], v[216:219], v[196:199], 0
	v_mfma_f32_16x16x32_bf16 v[54:57], v[212:215], v[172:175], v[54:57]
	v_mfma_f32_16x16x32_bf16 v[46:49], v[220:223], v[172:175], v[46:49]
	v_mfma_f32_16x16x32_bf16 v[38:41], v[212:215], v[184:187], v[38:41]
	v_mfma_f32_16x16x32_bf16 v[30:33], v[220:223], v[184:187], v[30:33]
	v_mfma_f32_16x16x32_bf16 v[22:25], v[212:215], v[192:195], v[22:25]
	v_mfma_f32_16x16x32_bf16 v[14:17], v[220:223], v[192:195], v[14:17]
	v_mfma_f32_16x16x32_bf16 v[6:9], v[212:215], v[200:203], v[6:9]
	v_mfma_f32_16x16x32_bf16 v[2:5], v[220:223], v[200:203], v[2:5]
	s_barrier
	s_add_i32 s55, 0, 0x18000
	v_add_u32_e32 v164, s55, v148
	ds_read_b128 v[152:155], v164
	ds_read_b128 v[156:159], v164 offset:1024
	ds_read_b128 v[160:163], v164 offset:2048
	ds_read_b128 v[164:167], v164 offset:3072
	s_add_u32 s20, s20, 0xb0000
	s_addc_u32 s21, s21, 0
	s_mov_b32 m0, s33
	ds_read_b128 v[168:171], v150 offset:32768
	ds_read_b128 v[172:175], v150 offset:33792
	ds_read_b128 v[180:183], v150 offset:34816
	ds_read_b128 v[184:187], v150 offset:35840
	ds_read_b128 v[188:191], v150 offset:36864
	ds_read_b128 v[192:195], v150 offset:37888
	ds_read_b128 v[196:199], v150 offset:38912
	ds_read_b128 v[200:203], v150 offset:39936
	global_load_lds_dwordx4 v130, s[20:21] sc0
	s_mov_b32 m0, s34
	s_nop 0
	global_load_lds_dwordx4 v132, s[20:21] sc0
	s_waitcnt lgkmcnt(8)
	s_barrier
	s_waitcnt lgkmcnt(0)
	v_mfma_f32_16x16x32_bf16 v[126:129], v[152:155], v[168:171], v[126:129]
	v_mfma_f32_16x16x32_bf16 v[122:125], v[160:163], v[168:171], v[122:125]
	v_mfma_f32_16x16x32_bf16 v[114:117], v[152:155], v[180:183], v[114:117]
	v_mfma_f32_16x16x32_bf16 v[106:109], v[160:163], v[180:183], v[106:109]
	v_mfma_f32_16x16x32_bf16 v[98:101], v[152:155], v[188:191], v[98:101]
	v_mfma_f32_16x16x32_bf16 v[90:93], v[160:163], v[188:191], v[90:93]
	v_mfma_f32_16x16x32_bf16 v[82:85], v[152:155], v[196:199], v[82:85]
	v_mfma_f32_16x16x32_bf16 v[74:77], v[160:163], v[196:199], v[74:77]
	v_mfma_f32_16x16x32_bf16 v[126:129], v[156:159], v[172:175], v[126:129]
	v_mfma_f32_16x16x32_bf16 v[122:125], v[164:167], v[172:175], v[122:125]
	v_mfma_f32_16x16x32_bf16 v[114:117], v[156:159], v[184:187], v[114:117]
	v_mfma_f32_16x16x32_bf16 v[106:109], v[164:167], v[184:187], v[106:109]
	v_mfma_f32_16x16x32_bf16 v[98:101], v[156:159], v[192:195], v[98:101]
	v_mfma_f32_16x16x32_bf16 v[90:93], v[164:167], v[192:195], v[90:93]
	v_mfma_f32_16x16x32_bf16 v[82:85], v[156:159], v[200:203], v[82:85]
	v_mfma_f32_16x16x32_bf16 v[74:77], v[164:167], v[200:203], v[74:77]
	s_barrier
	s_add_i32 s20, 0, 0x1c000
	s_add_i32 s21, s55, s27
	v_add_u32_e32 v179, s20, v148
	s_mov_b32 m0, s21
	ds_read_b128 v[206:209], v179
	ds_read_b128 v[212:215], v179 offset:1024
	ds_read_b128 v[216:219], v179 offset:2048
	ds_read_b128 v[220:223], v179 offset:3072
	global_load_lds_dwordx4 v134, s[98:99] sc0
	s_add_i32 m0, s21, 0x2000
	s_nop 0
	global_load_lds_dwordx4 v136, s[98:99] sc0
	s_barrier
	s_waitcnt lgkmcnt(0)
	v_mfma_f32_16x16x32_bf16 v[118:121], v[206:209], v[168:171], v[118:121]
	v_mfma_f32_16x16x32_bf16 v[110:113], v[216:219], v[168:171], v[110:113]
	v_mfma_f32_16x16x32_bf16 v[102:105], v[206:209], v[180:183], v[102:105]
	v_mfma_f32_16x16x32_bf16 v[94:97], v[216:219], v[180:183], v[94:97]
	v_mfma_f32_16x16x32_bf16 v[86:89], v[206:209], v[188:191], v[86:89]
	v_mfma_f32_16x16x32_bf16 v[78:81], v[216:219], v[188:191], v[78:81]
	v_mfma_f32_16x16x32_bf16 v[70:73], v[206:209], v[196:199], v[70:73]
	v_mfma_f32_16x16x32_bf16 v[66:69], v[216:219], v[196:199], v[66:69]
	v_mfma_f32_16x16x32_bf16 v[118:121], v[212:215], v[172:175], v[118:121]
	v_mfma_f32_16x16x32_bf16 v[110:113], v[220:223], v[172:175], v[110:113]
	v_mfma_f32_16x16x32_bf16 v[102:105], v[212:215], v[184:187], v[102:105]
	v_mfma_f32_16x16x32_bf16 v[94:97], v[220:223], v[184:187], v[94:97]
	v_mfma_f32_16x16x32_bf16 v[86:89], v[212:215], v[192:195], v[86:89]
	v_mfma_f32_16x16x32_bf16 v[78:81], v[220:223], v[192:195], v[78:81]
	v_mfma_f32_16x16x32_bf16 v[70:73], v[212:215], v[200:203], v[70:73]
	v_mfma_f32_16x16x32_bf16 v[66:69], v[220:223], v[200:203], v[66:69]
	s_barrier
	s_mov_b32 m0, s37
	ds_read_b128 v[168:171], v150 offset:49152
	ds_read_b128 v[172:175], v150 offset:50176
	ds_read_b128 v[180:183], v150 offset:51200
	ds_read_b128 v[184:187], v150 offset:52224
	ds_read_b128 v[188:191], v150 offset:53248
	ds_read_b128 v[192:195], v150 offset:54272
	ds_read_b128 v[196:199], v150 offset:55296
	ds_read_b128 v[200:203], v150 offset:56320
	global_load_lds_dwordx4 v130, s[100:101] sc0
	s_mov_b32 m0, s38
	s_nop 0
	global_load_lds_dwordx4 v132, s[100:101] sc0
	s_barrier
	s_waitcnt lgkmcnt(0)
	v_mfma_f32_16x16x32_bf16 v[62:65], v[152:155], v[168:171], v[62:65]
	v_mfma_f32_16x16x32_bf16 v[58:61], v[160:163], v[168:171], v[58:61]
	v_mfma_f32_16x16x32_bf16 v[50:53], v[152:155], v[180:183], v[50:53]
	v_mfma_f32_16x16x32_bf16 v[42:45], v[160:163], v[180:183], v[42:45]
	v_mfma_f32_16x16x32_bf16 v[34:37], v[152:155], v[188:191], v[34:37]
	v_mfma_f32_16x16x32_bf16 v[26:29], v[160:163], v[188:191], v[26:29]
	v_mfma_f32_16x16x32_bf16 v[18:21], v[152:155], v[196:199], v[18:21]
	v_mfma_f32_16x16x32_bf16 v[10:13], v[160:163], v[196:199], v[10:13]
	v_mfma_f32_16x16x32_bf16 v[62:65], v[156:159], v[172:175], v[62:65]
	v_mfma_f32_16x16x32_bf16 v[58:61], v[164:167], v[172:175], v[58:61]
	v_mfma_f32_16x16x32_bf16 v[50:53], v[156:159], v[184:187], v[50:53]
	v_mfma_f32_16x16x32_bf16 v[42:45], v[164:167], v[184:187], v[42:45]
	v_mfma_f32_16x16x32_bf16 v[34:37], v[156:159], v[192:195], v[34:37]
	v_mfma_f32_16x16x32_bf16 v[26:29], v[164:167], v[192:195], v[26:29]
	v_mfma_f32_16x16x32_bf16 v[18:21], v[156:159], v[200:203], v[18:21]
	v_mfma_f32_16x16x32_bf16 v[10:13], v[164:167], v[200:203], v[10:13]
	s_barrier
	s_add_u32 s18, s18, 0xb0080
	s_addc_u32 s19, s19, 0
	s_add_i32 s20, s20, s27
	s_mov_b32 m0, s20
	s_nop 0
	global_load_lds_dwordx4 v134, s[18:19] sc0
	s_add_i32 m0, s20, 0x2000
	s_nop 0
	global_load_lds_dwordx4 v136, s[18:19] sc0
	s_add_i32 s54, s54, 2
	s_add_u32 s16, s16, 0x100
	s_addc_u32 s17, s17, 0
	s_add_u32 s52, s52, 0x100
	s_addc_u32 s53, s53, 0
	s_cmp_gt_u32 s54, 41
	s_waitcnt vmcnt(6)
	s_barrier
	v_mfma_f32_16x16x32_bf16 v[54:57], v[206:209], v[168:171], v[54:57]
	v_mfma_f32_16x16x32_bf16 v[46:49], v[216:219], v[168:171], v[46:49]
	v_mfma_f32_16x16x32_bf16 v[38:41], v[206:209], v[180:183], v[38:41]
	v_mfma_f32_16x16x32_bf16 v[30:33], v[216:219], v[180:183], v[30:33]
	v_mfma_f32_16x16x32_bf16 v[22:25], v[206:209], v[188:191], v[22:25]
	v_mfma_f32_16x16x32_bf16 v[14:17], v[216:219], v[188:191], v[14:17]
	v_mfma_f32_16x16x32_bf16 v[6:9], v[206:209], v[196:199], v[6:9]
	v_mfma_f32_16x16x32_bf16 v[2:5], v[216:219], v[196:199], v[2:5]
	v_mfma_f32_16x16x32_bf16 v[54:57], v[212:215], v[172:175], v[54:57]
	v_mfma_f32_16x16x32_bf16 v[46:49], v[220:223], v[172:175], v[46:49]
	v_mfma_f32_16x16x32_bf16 v[38:41], v[212:215], v[184:187], v[38:41]
	v_mfma_f32_16x16x32_bf16 v[30:33], v[220:223], v[184:187], v[30:33]
	v_mfma_f32_16x16x32_bf16 v[22:25], v[212:215], v[192:195], v[22:25]
	v_mfma_f32_16x16x32_bf16 v[14:17], v[220:223], v[192:195], v[14:17]
	v_mfma_f32_16x16x32_bf16 v[6:9], v[212:215], v[200:203], v[6:9]
	v_mfma_f32_16x16x32_bf16 v[2:5], v[220:223], v[200:203], v[2:5]
	s_barrier
	s_cbranch_scc1 .Lpeel_p10_exit
.LBB0_1197:
	ds_read_b128 v[152:155], v149
	ds_read_b128 v[156:159], v149 offset:1024
	ds_read_b128 v[160:163], v149 offset:2048
	ds_read_b128 v[164:167], v149 offset:3072
	s_add_u32 s18, s16, 0xfff50080
	s_addc_u32 s19, s17, -1
	s_cmp_eq_u32 s54, 40
	s_cselect_b32 s21, s3, s19
	s_cselect_b32 s20, s2, s18
	s_cselect_b32 s19, s5, s53
	s_cselect_b32 s18, s4, s52
	s_add_i32 m0, s30, 0xc000
	ds_read_b128 v[168:171], v150
	ds_read_b128 v[172:175], v150 offset:1024
	ds_read_b128 v[180:183], v150 offset:2048
	ds_read_b128 v[184:187], v150 offset:3072
	ds_read_b128 v[188:191], v150 offset:4096
	ds_read_b128 v[192:195], v150 offset:5120
	ds_read_b128 v[196:199], v150 offset:6144
	ds_read_b128 v[200:203], v150 offset:7168
	global_load_lds_dwordx4 v138, s[16:17] sc0
	s_add_i32 m0, s30, 0xe000
	s_nop 0
	global_load_lds_dwordx4 v140, s[16:17] sc0
	s_waitcnt lgkmcnt(8)
	s_barrier
	s_waitcnt lgkmcnt(0)
	v_mfma_f32_16x16x32_bf16 v[126:129], v[152:155], v[168:171], v[126:129]
	v_mfma_f32_16x16x32_bf16 v[122:125], v[160:163], v[168:171], v[122:125]
	v_mfma_f32_16x16x32_bf16 v[114:117], v[152:155], v[180:183], v[114:117]
	v_mfma_f32_16x16x32_bf16 v[106:109], v[160:163], v[180:183], v[106:109]
	v_mfma_f32_16x16x32_bf16 v[98:101], v[152:155], v[188:191], v[98:101]
	v_mfma_f32_16x16x32_bf16 v[90:93], v[160:163], v[188:191], v[90:93]
	v_mfma_f32_16x16x32_bf16 v[82:85], v[152:155], v[196:199], v[82:85]
	v_mfma_f32_16x16x32_bf16 v[74:77], v[160:163], v[196:199], v[74:77]
	v_mfma_f32_16x16x32_bf16 v[126:129], v[156:159], v[172:175], v[126:129]
	v_mfma_f32_16x16x32_bf16 v[122:125], v[164:167], v[172:175], v[122:125]
	v_mfma_f32_16x16x32_bf16 v[114:117], v[156:159], v[184:187], v[114:117]
	v_mfma_f32_16x16x32_bf16 v[106:109], v[164:167], v[184:187], v[106:109]
	v_mfma_f32_16x16x32_bf16 v[98:101], v[156:159], v[192:195], v[98:101]
	v_mfma_f32_16x16x32_bf16 v[90:93], v[164:167], v[192:195], v[90:93]
	v_mfma_f32_16x16x32_bf16 v[82:85], v[156:159], v[200:203], v[82:85]
	v_mfma_f32_16x16x32_bf16 v[74:77], v[164:167], v[200:203], v[74:77]
	s_barrier
	s_add_i32 s55, s41, s27
	s_add_u32 s98, s18, 0x80
	s_addc_u32 s99, s19, 0
	s_mov_b32 m0, s55
	ds_read_b128 v[206:209], v151
	ds_read_b128 v[212:215], v151 offset:1024
	ds_read_b128 v[216:219], v151 offset:2048
	ds_read_b128 v[220:223], v151 offset:3072
	global_load_lds_dwordx4 v134, s[18:19] sc0
	s_add_i32 m0, s55, 0x2000
	s_nop 0
	global_load_lds_dwordx4 v136, s[18:19] sc0
	s_barrier
	s_waitcnt lgkmcnt(0)
	v_mfma_f32_16x16x32_bf16 v[118:121], v[206:209], v[168:171], v[118:121]
	v_mfma_f32_16x16x32_bf16 v[110:113], v[216:219], v[168:171], v[110:113]
	v_mfma_f32_16x16x32_bf16 v[102:105], v[206:209], v[180:183], v[102:105]
	v_mfma_f32_16x16x32_bf16 v[94:97], v[216:219], v[180:183], v[94:97]
	v_mfma_f32_16x16x32_bf16 v[86:89], v[206:209], v[188:191], v[86:89]
	v_mfma_f32_16x16x32_bf16 v[78:81], v[216:219], v[188:191], v[78:81]
	v_mfma_f32_16x16x32_bf16 v[70:73], v[206:209], v[196:199], v[70:73]
	v_mfma_f32_16x16x32_bf16 v[66:69], v[216:219], v[196:199], v[66:69]
	v_mfma_f32_16x16x32_bf16 v[118:121], v[212:215], v[172:175], v[118:121]
	v_mfma_f32_16x16x32_bf16 v[110:113], v[220:223], v[172:175], v[110:113]
	v_mfma_f32_16x16x32_bf16 v[102:105], v[212:215], v[184:187], v[102:105]
	v_mfma_f32_16x16x32_bf16 v[94:97], v[220:223], v[184:187], v[94:97]
	v_mfma_f32_16x16x32_bf16 v[86:89], v[212:215], v[192:195], v[86:89]
	v_mfma_f32_16x16x32_bf16 v[78:81], v[220:223], v[192:195], v[78:81]
	v_mfma_f32_16x16x32_bf16 v[70:73], v[212:215], v[200:203], v[70:73]
	v_mfma_f32_16x16x32_bf16 v[66:69], v[220:223], v[200:203], v[66:69]
	s_barrier
	s_mov_b32 m0, s30
	s_add_u32 s100, s20, 0x80
	s_addc_u32 s101, s21, 0
	ds_read_b128 v[168:171], v150 offset:16384
	ds_read_b128 v[172:175], v150 offset:17408
	ds_read_b128 v[180:183], v150 offset:18432
	ds_read_b128 v[184:187], v150 offset:19456
	ds_read_b128 v[188:191], v150 offset:20480
	ds_read_b128 v[192:195], v150 offset:21504
	ds_read_b128 v[196:199], v150 offset:22528
	ds_read_b128 v[200:203], v150 offset:23552
	global_load_lds_dwordx4 v130, s[20:21] sc0
	s_mov_b32 m0, s31
	s_nop 0
	global_load_lds_dwordx4 v132, s[20:21] sc0
	s_barrier
	s_waitcnt lgkmcnt(0)
	v_mfma_f32_16x16x32_bf16 v[62:65], v[152:155], v[168:171], v[62:65]
	v_mfma_f32_16x16x32_bf16 v[58:61], v[160:163], v[168:171], v[58:61]
	v_mfma_f32_16x16x32_bf16 v[50:53], v[152:155], v[180:183], v[50:53]
	v_mfma_f32_16x16x32_bf16 v[42:45], v[160:163], v[180:183], v[42:45]
	v_mfma_f32_16x16x32_bf16 v[34:37], v[152:155], v[188:191], v[34:37]
	v_mfma_f32_16x16x32_bf16 v[26:29], v[160:163], v[188:191], v[26:29]
	v_mfma_f32_16x16x32_bf16 v[18:21], v[152:155], v[196:199], v[18:21]
	v_mfma_f32_16x16x32_bf16 v[10:13], v[160:163], v[196:199], v[10:13]
	v_mfma_f32_16x16x32_bf16 v[62:65], v[156:159], v[172:175], v[62:65]
	v_mfma_f32_16x16x32_bf16 v[58:61], v[164:167], v[172:175], v[58:61]
	v_mfma_f32_16x16x32_bf16 v[50:53], v[156:159], v[184:187], v[50:53]
	v_mfma_f32_16x16x32_bf16 v[42:45], v[164:167], v[184:187], v[42:45]
	v_mfma_f32_16x16x32_bf16 v[34:37], v[156:159], v[192:195], v[34:37]
	v_mfma_f32_16x16x32_bf16 v[26:29], v[164:167], v[192:195], v[26:29]
	v_mfma_f32_16x16x32_bf16 v[18:21], v[156:159], v[200:203], v[18:21]
	v_mfma_f32_16x16x32_bf16 v[10:13], v[164:167], v[200:203], v[10:13]
	s_barrier
	s_add_u32 s56, s18, 0xb0000
	s_addc_u32 s57, s19, 0
	s_add_i32 s55, s42, s27
	s_mov_b32 m0, s55
	s_nop 0
	global_load_lds_dwordx4 v134, s[56:57] sc0
	s_add_i32 m0, s55, 0x2000
	s_nop 0
	global_load_lds_dwordx4 v136, s[56:57] sc0
	s_waitcnt vmcnt(6)
	s_barrier
	v_mfma_f32_16x16x32_bf16 v[54:57], v[206:209], v[168:171], v[54:57]
	v_mfma_f32_16x16x32_bf16 v[46:49], v[216:219], v[168:171], v[46:49]
	v_mfma_f32_16x16x32_bf16 v[38:41], v[206:209], v[180:183], v[38:41]
	v_mfma_f32_16x16x32_bf16 v[30:33], v[216:219], v[180:183], v[30:33]
	v_mfma_f32_16x16x32_bf16 v[22:25], v[206:209], v[188:191], v[22:25]
	v_mfma_f32_16x16x32_bf16 v[14:17], v[216:219], v[188:191], v[14:17]
	v_mfma_f32_16x16x32_bf16 v[6:9], v[206:209], v[196:199], v[6:9]
	v_mfma_f32_16x16x32_bf16 v[2:5], v[216:219], v[196:199], v[2:5]
	v_mfma_f32_16x16x32_bf16 v[54:57], v[212:215], v[172:175], v[54:57]
	v_mfma_f32_16x16x32_bf16 v[46:49], v[220:223], v[172:175], v[46:49]
	v_mfma_f32_16x16x32_bf16 v[38:41], v[212:215], v[184:187], v[38:41]
	v_mfma_f32_16x16x32_bf16 v[30:33], v[220:223], v[184:187], v[30:33]
	v_mfma_f32_16x16x32_bf16 v[22:25], v[212:215], v[192:195], v[22:25]
	v_mfma_f32_16x16x32_bf16 v[14:17], v[220:223], v[192:195], v[14:17]
	v_mfma_f32_16x16x32_bf16 v[6:9], v[212:215], v[200:203], v[6:9]
	v_mfma_f32_16x16x32_bf16 v[2:5], v[220:223], v[200:203], v[2:5]
	s_barrier
	s_add_i32 s55, 0, 0x18000
	v_add_u32_e32 v164, s55, v148
	ds_read_b128 v[152:155], v164
	ds_read_b128 v[156:159], v164 offset:1024
	ds_read_b128 v[160:163], v164 offset:2048
	ds_read_b128 v[164:167], v164 offset:3072
	s_add_u32 s20, s20, 0xb0000
	s_addc_u32 s21, s21, 0
	s_mov_b32 m0, s33
	ds_read_b128 v[168:171], v150 offset:32768
	ds_read_b128 v[172:175], v150 offset:33792
	ds_read_b128 v[180:183], v150 offset:34816
	ds_read_b128 v[184:187], v150 offset:35840
	ds_read_b128 v[188:191], v150 offset:36864
	ds_read_b128 v[192:195], v150 offset:37888
	ds_read_b128 v[196:199], v150 offset:38912
	ds_read_b128 v[200:203], v150 offset:39936
	global_load_lds_dwordx4 v130, s[20:21] sc0
	s_mov_b32 m0, s34
	s_nop 0
	global_load_lds_dwordx4 v132, s[20:21] sc0
	s_waitcnt lgkmcnt(8)
	s_barrier
	s_waitcnt lgkmcnt(0)
	v_mfma_f32_16x16x32_bf16 v[126:129], v[152:155], v[168:171], v[126:129]
	v_mfma_f32_16x16x32_bf16 v[122:125], v[160:163], v[168:171], v[122:125]
	v_mfma_f32_16x16x32_bf16 v[114:117], v[152:155], v[180:183], v[114:117]
	v_mfma_f32_16x16x32_bf16 v[106:109], v[160:163], v[180:183], v[106:109]
	v_mfma_f32_16x16x32_bf16 v[98:101], v[152:155], v[188:191], v[98:101]
	v_mfma_f32_16x16x32_bf16 v[90:93], v[160:163], v[188:191], v[90:93]
	v_mfma_f32_16x16x32_bf16 v[82:85], v[152:155], v[196:199], v[82:85]
	v_mfma_f32_16x16x32_bf16 v[74:77], v[160:163], v[196:199], v[74:77]
	v_mfma_f32_16x16x32_bf16 v[126:129], v[156:159], v[172:175], v[126:129]
	v_mfma_f32_16x16x32_bf16 v[122:125], v[164:167], v[172:175], v[122:125]
	v_mfma_f32_16x16x32_bf16 v[114:117], v[156:159], v[184:187], v[114:117]
	v_mfma_f32_16x16x32_bf16 v[106:109], v[164:167], v[184:187], v[106:109]
	v_mfma_f32_16x16x32_bf16 v[98:101], v[156:159], v[192:195], v[98:101]
	v_mfma_f32_16x16x32_bf16 v[90:93], v[164:167], v[192:195], v[90:93]
	v_mfma_f32_16x16x32_bf16 v[82:85], v[156:159], v[200:203], v[82:85]
	v_mfma_f32_16x16x32_bf16 v[74:77], v[164:167], v[200:203], v[74:77]
	s_barrier
	s_add_i32 s20, 0, 0x1c000
	s_add_i32 s21, s55, s27
	v_add_u32_e32 v179, s20, v148
	s_mov_b32 m0, s21
	ds_read_b128 v[206:209], v179
	ds_read_b128 v[212:215], v179 offset:1024
	ds_read_b128 v[216:219], v179 offset:2048
	ds_read_b128 v[220:223], v179 offset:3072
	global_load_lds_dwordx4 v134, s[98:99] sc0
	s_add_i32 m0, s21, 0x2000
	s_nop 0
	global_load_lds_dwordx4 v136, s[98:99] sc0
	s_barrier
	s_waitcnt lgkmcnt(0)
	v_mfma_f32_16x16x32_bf16 v[118:121], v[206:209], v[168:171], v[118:121]
	v_mfma_f32_16x16x32_bf16 v[110:113], v[216:219], v[168:171], v[110:113]
	v_mfma_f32_16x16x32_bf16 v[102:105], v[206:209], v[180:183], v[102:105]
	v_mfma_f32_16x16x32_bf16 v[94:97], v[216:219], v[180:183], v[94:97]
	v_mfma_f32_16x16x32_bf16 v[86:89], v[206:209], v[188:191], v[86:89]
	v_mfma_f32_16x16x32_bf16 v[78:81], v[216:219], v[188:191], v[78:81]
	v_mfma_f32_16x16x32_bf16 v[70:73], v[206:209], v[196:199], v[70:73]
	v_mfma_f32_16x16x32_bf16 v[66:69], v[216:219], v[196:199], v[66:69]
	v_mfma_f32_16x16x32_bf16 v[118:121], v[212:215], v[172:175], v[118:121]
	v_mfma_f32_16x16x32_bf16 v[110:113], v[220:223], v[172:175], v[110:113]
	v_mfma_f32_16x16x32_bf16 v[102:105], v[212:215], v[184:187], v[102:105]
	v_mfma_f32_16x16x32_bf16 v[94:97], v[220:223], v[184:187], v[94:97]
	v_mfma_f32_16x16x32_bf16 v[86:89], v[212:215], v[192:195], v[86:89]
	v_mfma_f32_16x16x32_bf16 v[78:81], v[220:223], v[192:195], v[78:81]
	v_mfma_f32_16x16x32_bf16 v[70:73], v[212:215], v[200:203], v[70:73]
	v_mfma_f32_16x16x32_bf16 v[66:69], v[220:223], v[200:203], v[66:69]
	s_barrier
	s_mov_b32 m0, s37
	ds_read_b128 v[168:171], v150 offset:49152
	ds_read_b128 v[172:175], v150 offset:50176
	ds_read_b128 v[180:183], v150 offset:51200
	ds_read_b128 v[184:187], v150 offset:52224
	ds_read_b128 v[188:191], v150 offset:53248
	ds_read_b128 v[192:195], v150 offset:54272
	ds_read_b128 v[196:199], v150 offset:55296
	ds_read_b128 v[200:203], v150 offset:56320
	global_load_lds_dwordx4 v130, s[100:101] sc0
	s_mov_b32 m0, s38
	s_nop 0
	global_load_lds_dwordx4 v132, s[100:101] sc0
	s_barrier
	s_waitcnt lgkmcnt(0)
	v_mfma_f32_16x16x32_bf16 v[62:65], v[152:155], v[168:171], v[62:65]
	v_mfma_f32_16x16x32_bf16 v[58:61], v[160:163], v[168:171], v[58:61]
	v_mfma_f32_16x16x32_bf16 v[50:53], v[152:155], v[180:183], v[50:53]
	v_mfma_f32_16x16x32_bf16 v[42:45], v[160:163], v[180:183], v[42:45]
	v_mfma_f32_16x16x32_bf16 v[34:37], v[152:155], v[188:191], v[34:37]
	v_mfma_f32_16x16x32_bf16 v[26:29], v[160:163], v[188:191], v[26:29]
	v_mfma_f32_16x16x32_bf16 v[18:21], v[152:155], v[196:199], v[18:21]
	v_mfma_f32_16x16x32_bf16 v[10:13], v[160:163], v[196:199], v[10:13]
	v_mfma_f32_16x16x32_bf16 v[62:65], v[156:159], v[172:175], v[62:65]
	v_mfma_f32_16x16x32_bf16 v[58:61], v[164:167], v[172:175], v[58:61]
	v_mfma_f32_16x16x32_bf16 v[50:53], v[156:159], v[184:187], v[50:53]
	v_mfma_f32_16x16x32_bf16 v[42:45], v[164:167], v[184:187], v[42:45]
	v_mfma_f32_16x16x32_bf16 v[34:37], v[156:159], v[192:195], v[34:37]
	v_mfma_f32_16x16x32_bf16 v[26:29], v[164:167], v[192:195], v[26:29]
	v_mfma_f32_16x16x32_bf16 v[18:21], v[156:159], v[200:203], v[18:21]
	v_mfma_f32_16x16x32_bf16 v[10:13], v[164:167], v[200:203], v[10:13]
	s_barrier
	s_add_u32 s18, s18, 0xb0080
	s_addc_u32 s19, s19, 0
	s_add_i32 s20, s20, s27
	s_mov_b32 m0, s20
	s_nop 0
	global_load_lds_dwordx4 v134, s[18:19] sc0
	s_add_i32 m0, s20, 0x2000
	s_nop 0
	global_load_lds_dwordx4 v136, s[18:19] sc0
	s_add_i32 s54, s54, 2
	s_add_u32 s16, s16, 0x100
	s_addc_u32 s17, s17, 0
	s_add_u32 s52, s52, 0x100
	s_addc_u32 s53, s53, 0
	s_cmp_gt_u32 s54, 41
	s_waitcnt vmcnt(6)
	s_barrier
	v_mfma_f32_16x16x32_bf16 v[54:57], v[206:209], v[168:171], v[54:57]
	v_mfma_f32_16x16x32_bf16 v[46:49], v[216:219], v[168:171], v[46:49]
	v_mfma_f32_16x16x32_bf16 v[38:41], v[206:209], v[180:183], v[38:41]
	v_mfma_f32_16x16x32_bf16 v[30:33], v[216:219], v[180:183], v[30:33]
	v_mfma_f32_16x16x32_bf16 v[22:25], v[206:209], v[188:191], v[22:25]
	v_mfma_f32_16x16x32_bf16 v[14:17], v[216:219], v[188:191], v[14:17]
	v_mfma_f32_16x16x32_bf16 v[6:9], v[206:209], v[196:199], v[6:9]
	v_mfma_f32_16x16x32_bf16 v[2:5], v[216:219], v[196:199], v[2:5]
	v_mfma_f32_16x16x32_bf16 v[54:57], v[212:215], v[172:175], v[54:57]
	v_mfma_f32_16x16x32_bf16 v[46:49], v[220:223], v[172:175], v[46:49]
	v_mfma_f32_16x16x32_bf16 v[38:41], v[212:215], v[184:187], v[38:41]
	v_mfma_f32_16x16x32_bf16 v[30:33], v[220:223], v[184:187], v[30:33]
	v_mfma_f32_16x16x32_bf16 v[22:25], v[212:215], v[192:195], v[22:25]
	v_mfma_f32_16x16x32_bf16 v[14:17], v[220:223], v[192:195], v[14:17]
	v_mfma_f32_16x16x32_bf16 v[6:9], v[212:215], v[200:203], v[6:9]
	v_mfma_f32_16x16x32_bf16 v[2:5], v[220:223], v[200:203], v[2:5]
	s_barrier
	s_cbranch_scc0 .LBB0_1197

.LBB0_1202:
	s_cmp_gt_i32 s82, 43
	v_readfirstlane_b32 s4, v0
	s_cbranch_scc1 .LBB0_1208
	s_lshl_b32 s0, s82, 6
	s_and_b32 s0, s0, 0xffffff00
	s_lshr_b32 s8, s4, 6
	s_and_b32 s5, s82, 3
	s_ashr_i32 s1, s0, 31
	s_lshr_b32 s20, s4, 8
	s_lshl_b32 s19, s8, 10
	s_lshl_b64 s[0:1], s[0:1], 1
	s_mul_i32 s2, s5, 0x160000
	s_add_u32 s2, s24, s2
	s_addc_u32 s3, s25, 0
	s_add_u32 s2, s2, s0
	s_addc_u32 s3, s3, s1
	s_add_i32 s9, s19, 0
	s_add_i32 m0, s9, 0x10000
	v_mov_b32_e32 v131, 0
	global_load_lds_dwordx4 v130, s[2:3] sc0
	s_add_i32 m0, s9, 0x12000
	s_add_u32 s12, s94, s0
	s_addc_u32 s13, s95, s1
	s_add_u32 s0, s12, 0x9a12400
	global_load_lds_dwordx4 v132, s[2:3] sc0
	s_addc_u32 s1, s13, 0
	s_mov_b32 m0, s9
	s_add_i32 s18, s9, 0x2000
	global_load_lds_dwordx4 v130, s[0:1] sc0
	s_mov_b32 m0, s18
	s_add_u32 s10, s2, 0xb0000
	global_load_lds_dwordx4 v132, s[0:1] sc0
	s_addc_u32 s11, s3, 0
	s_add_i32 m0, s9, 0x14000
	v_mov_b32_e32 v133, v131
	global_load_lds_dwordx4 v130, s[10:11] sc0
	s_add_i32 m0, s9, 0x16000
	s_add_u32 s12, s12, 0x9ac2400
	s_addc_u32 s13, s13, 0
	s_add_i32 s14, s9, 0x4000
	global_load_lds_dwordx4 v132, s[10:11] sc0
	s_mov_b32 m0, s14
	s_add_i32 s15, s9, 0x6000
	global_load_lds_dwordx4 v130, s[12:13] sc0
	s_mov_b32 m0, s15
	v_lshl_add_u64 v[34:35], s[2:3], 0, v[130:131]
	global_load_lds_dwordx4 v132, s[12:13] sc0
	v_lshl_add_u64 v[36:37], s[2:3], 0, v[132:133]
	v_lshl_add_u64 v[32:33], s[0:1], 0, v[130:131]
	v_lshl_add_u64 v[30:31], s[0:1], 0, v[132:133]
	v_lshl_add_u64 v[28:29], s[10:11], 0, v[130:131]
	v_lshl_add_u64 v[26:27], s[10:11], 0, v[132:133]
	v_lshl_add_u64 v[22:23], s[12:13], 0, v[130:131]
	s_cmp_lg_u32 s20, 1
	v_lshl_add_u64 v[24:25], s[12:13], 0, v[132:133]
	s_cbranch_scc1 .LBB0_1205
	s_barrier
.LBB0_1205:
	s_add_i32 s24, 0, 0x18000
	s_lshl_b32 s8, s8, 5
	s_add_i32 s16, s24, s19
	s_mov_b64 s[12:13], 0x80
	s_lshl_b32 s21, s20, 13
	s_and_b32 s8, s8, 0x60
	v_lshl_add_u64 v[18:19], v[34:35], 0, s[12:13]
	s_mov_b32 m0, s16
	s_add_i32 s17, s16, 0x2000
	s_add_i32 s10, s9, 0x8000
	s_add_i32 s11, s9, 0xa000
	s_waitcnt vmcnt(4)
	s_barrier
	global_load_lds_dwordx4 v[18:19], off sc0
	v_lshl_add_u64 v[20:21], v[36:37], 0, s[12:13]
	s_mov_b32 m0, s17
	s_add_u32 s22, s2, 0xb0080
	global_load_lds_dwordx4 v[20:21], off sc0
	v_lshl_add_u64 v[2:3], v[32:33], 0, s[12:13]
	s_mov_b32 m0, s10
	s_addc_u32 s23, s3, 0
	s_add_i32 s25, 0, 0x1c000
	global_load_lds_dwordx4 v[2:3], off sc0
	v_lshl_add_u64 v[6:7], v[30:31], 0, s[12:13]
	s_mov_b32 m0, s11
	s_add_i32 s12, s25, s19
	global_load_lds_dwordx4 v[6:7], off sc0
	v_lshl_add_u64 v[10:11], s[22:23], 0, v[130:131]
	s_mov_b32 m0, s12
	s_add_i32 s13, s12, 0x2000
	global_load_lds_dwordx4 v[10:11], off sc0
	v_lshl_add_u64 v[12:13], s[22:23], 0, v[132:133]
	s_mov_b32 m0, s13
	v_lshl_or_b32 v1, s8, 7, v1
	global_load_lds_dwordx4 v[12:13], off sc0
	s_add_i32 s22, 0, 0x10000
	v_add_u32_e32 v156, s22, v1
	s_waitcnt vmcnt(6)
	s_barrier
	ds_read_b128 v[38:41], v156
	ds_read_b128 v[42:45], v156 offset:1024
	ds_read_b128 v[46:49], v156 offset:2048
	ds_read_b128 v[50:53], v156 offset:3072
	v_lshlrev_b32_e32 v5, 2, v178
	v_lshl_or_b32 v4, v178, 6, v204
	v_and_b32_e32 v5, 32, v5
	v_lshl_or_b32 v14, s20, 6, v178
	v_bitop3_b32 v4, v4, s21, v5 bitop3:0xde
	v_mov_b32_e32 v15, v131
	v_add_u32_e32 v157, 0, v4
	s_add_i32 s26, 0, 0x14000
	v_lshlrev_b64 v[8:9], 12, v[14:15]
	v_or_b32_e32 v4, 16, v14
	v_mov_b32_e32 v5, v131
	v_or_b32_e32 v16, 32, v14
	v_mov_b32_e32 v17, v131
	v_or_b32_e32 v14, 48, v14
	v_add_u32_e32 v158, s26, v1
	v_add_u32_e32 v159, s24, v1
	v_add_u32_e32 v1, s25, v1
	v_lshlrev_b64 v[4:5], 12, v[4:5]
	v_lshlrev_b64 v[16:17], 12, v[16:17]
	v_lshlrev_b64 v[14:15], 12, v[14:15]
	s_add_u32 s20, s0, 0xb0080
	s_addc_u32 s21, s1, 0
	s_add_i32 s23, s9, 0xc000
	v_lshl_add_u64 v[86:87], s[20:21], 0, v[130:131]
	s_mov_b32 m0, s23
	ds_read_b128 v[54:57], v157
	ds_read_b128 v[58:61], v157 offset:1024
	ds_read_b128 v[62:65], v157 offset:2048
	ds_read_b128 v[66:69], v157 offset:3072
	ds_read_b128 v[70:73], v157 offset:4096
	ds_read_b128 v[74:77], v157 offset:5120
	ds_read_b128 v[78:81], v157 offset:6144
	ds_read_b128 v[82:85], v157 offset:7168
	global_load_lds_dwordx4 v[86:87], off sc0
	v_lshl_add_u64 v[86:87], s[20:21], 0, v[132:133]
	s_add_i32 s20, s9, 0xe000
	s_mov_b32 m0, s20
	s_nop 0
	global_load_lds_dwordx4 v[86:87], off sc0
	s_waitcnt lgkmcnt(8)
	s_barrier
	s_waitcnt lgkmcnt(0)
	v_mfma_f32_16x16x32_bf16 v[86:89], v[38:41], v[54:57], 0
	v_mfma_f32_16x16x32_bf16 v[94:97], v[38:41], v[62:65], 0
	v_mfma_f32_16x16x32_bf16 v[102:105], v[38:41], v[70:73], 0
	v_mfma_f32_16x16x32_bf16 v[38:41], v[38:41], v[78:81], 0
	v_mfma_f32_16x16x32_bf16 v[86:89], v[42:45], v[58:61], v[86:89]
	v_mfma_f32_16x16x32_bf16 v[90:93], v[46:49], v[54:57], 0
	v_mfma_f32_16x16x32_bf16 v[94:97], v[42:45], v[66:69], v[94:97]
	v_mfma_f32_16x16x32_bf16 v[98:101], v[46:49], v[62:65], 0
	v_mfma_f32_16x16x32_bf16 v[102:105], v[42:45], v[74:77], v[102:105]
	v_mfma_f32_16x16x32_bf16 v[106:109], v[46:49], v[70:73], 0
	v_mfma_f32_16x16x32_bf16 v[38:41], v[42:45], v[82:85], v[38:41]
	v_mfma_f32_16x16x32_bf16 v[42:45], v[46:49], v[78:81], 0
	v_mfma_f32_16x16x32_bf16 v[90:93], v[50:53], v[58:61], v[90:93]
	v_mfma_f32_16x16x32_bf16 v[98:101], v[50:53], v[66:69], v[98:101]
	v_mfma_f32_16x16x32_bf16 v[106:109], v[50:53], v[74:77], v[106:109]
	v_mfma_f32_16x16x32_bf16 v[42:45], v[50:53], v[82:85], v[42:45]
	s_barrier
	s_mov_b64 s[24:25], 0x100
	s_add_i32 s21, s22, s19
	v_lshl_add_u64 v[118:119], v[34:35], 0, s[24:25]
	s_mov_b32 m0, s21
	s_add_i32 s22, s21, 0x2000
	ds_read_b128 v[46:49], v158
	ds_read_b128 v[50:53], v158 offset:1024
	ds_read_b128 v[110:113], v158 offset:2048
	ds_read_b128 v[114:117], v158 offset:3072
	global_load_lds_dwordx4 v[118:119], off sc0
	v_lshl_add_u64 v[118:119], v[36:37], 0, s[24:25]
	s_mov_b32 m0, s22
	s_nop 0
	global_load_lds_dwordx4 v[118:119], off sc0
	s_barrier
	s_waitcnt lgkmcnt(0)
	v_mfma_f32_16x16x32_bf16 v[118:121], v[46:49], v[54:57], 0
	v_mfma_f32_16x16x32_bf16 v[54:57], v[110:113], v[54:57], 0
	v_mfma_f32_16x16x32_bf16 v[118:121], v[50:53], v[58:61], v[118:121]
	v_mfma_f32_16x16x32_bf16 v[54:57], v[114:117], v[58:61], v[54:57]
	v_mfma_f32_16x16x32_bf16 v[58:61], v[46:49], v[62:65], 0
	v_mfma_f32_16x16x32_bf16 v[62:65], v[110:113], v[62:65], 0
	v_mfma_f32_16x16x32_bf16 v[58:61], v[50:53], v[66:69], v[58:61]
	v_mfma_f32_16x16x32_bf16 v[62:65], v[114:117], v[66:69], v[62:65]
	v_mfma_f32_16x16x32_bf16 v[66:69], v[46:49], v[70:73], 0
	v_mfma_f32_16x16x32_bf16 v[46:49], v[46:49], v[78:81], 0
	v_mfma_f32_16x16x32_bf16 v[66:69], v[50:53], v[74:77], v[66:69]
	v_mfma_f32_16x16x32_bf16 v[70:73], v[110:113], v[70:73], 0
	v_mfma_f32_16x16x32_bf16 v[46:49], v[50:53], v[82:85], v[46:49]
	v_mfma_f32_16x16x32_bf16 v[50:53], v[110:113], v[78:81], 0
	v_mfma_f32_16x16x32_bf16 v[70:73], v[114:117], v[74:77], v[70:73]
	v_mfma_f32_16x16x32_bf16 v[50:53], v[114:117], v[82:85], v[50:53]
	s_mov_b32 m0, s9
	v_lshl_add_u64 v[74:75], v[32:33], 0, s[24:25]
	s_barrier
	global_load_lds_dwordx4 v[74:75], off sc0
	v_lshl_add_u64 v[74:75], v[30:31], 0, s[24:25]
	s_mov_b32 m0, s18
	s_nop 0
	global_load_lds_dwordx4 v[74:75], off sc0
	s_barrier
	s_waitcnt lgkmcnt(0)
	s_barrier
	s_add_u32 s24, s2, 0xb0100
	s_addc_u32 s25, s3, 0
	s_add_i32 s19, s26, s19
	v_lshl_add_u64 v[74:75], s[24:25], 0, v[130:131]
	s_mov_b32 m0, s19
	s_nop 0
	global_load_lds_dwordx4 v[74:75], off sc0
	v_lshl_add_u64 v[74:75], s[24:25], 0, v[132:133]
	s_add_i32 s24, s19, 0x2000
	s_mov_b32 m0, s24
	s_nop 0
	global_load_lds_dwordx4 v[74:75], off sc0
	s_waitcnt vmcnt(6)
	s_barrier
	s_barrier
	ds_read_b128 v[74:77], v159
	ds_read_b128 v[78:81], v159 offset:1024
	ds_read_b128 v[82:85], v159 offset:2048
	ds_read_b128 v[110:113], v159 offset:3072
	s_add_u32 s26, s0, 0xb0100
	s_addc_u32 s27, s1, 0
	s_mov_b32 m0, s14
	v_lshl_add_u64 v[154:155], s[26:27], 0, v[130:131]
	ds_read_b128 v[114:117], v157 offset:32768
	ds_read_b128 v[122:125], v157 offset:33792
	ds_read_b128 v[126:129], v157 offset:34816
	ds_read_b128 v[134:137], v157 offset:35840
	ds_read_b128 v[138:141], v157 offset:36864
	ds_read_b128 v[142:145], v157 offset:37888
	ds_read_b128 v[146:149], v157 offset:38912
	ds_read_b128 v[150:153], v157 offset:39936
	global_load_lds_dwordx4 v[154:155], off sc0
	v_lshl_add_u64 v[154:155], s[26:27], 0, v[132:133]
	s_mov_b32 m0, s15
	s_nop 0
	global_load_lds_dwordx4 v[154:155], off sc0
	s_waitcnt lgkmcnt(8)
	s_barrier
	s_waitcnt lgkmcnt(0)
	v_mfma_f32_16x16x32_bf16 v[86:89], v[74:77], v[114:117], v[86:89]
	v_mfma_f32_16x16x32_bf16 v[90:93], v[82:85], v[114:117], v[90:93]
	v_mfma_f32_16x16x32_bf16 v[94:97], v[74:77], v[126:129], v[94:97]
	v_mfma_f32_16x16x32_bf16 v[98:101], v[82:85], v[126:129], v[98:101]
	v_mfma_f32_16x16x32_bf16 v[102:105], v[74:77], v[138:141], v[102:105]
	v_mfma_f32_16x16x32_bf16 v[106:109], v[82:85], v[138:141], v[106:109]
	v_mfma_f32_16x16x32_bf16 v[38:41], v[74:77], v[146:149], v[38:41]
	v_mfma_f32_16x16x32_bf16 v[42:45], v[82:85], v[146:149], v[42:45]
	v_mfma_f32_16x16x32_bf16 v[86:89], v[78:81], v[122:125], v[86:89]
	v_mfma_f32_16x16x32_bf16 v[90:93], v[110:113], v[122:125], v[90:93]
	v_mfma_f32_16x16x32_bf16 v[94:97], v[78:81], v[134:137], v[94:97]
	v_mfma_f32_16x16x32_bf16 v[98:101], v[110:113], v[134:137], v[98:101]
	v_mfma_f32_16x16x32_bf16 v[102:105], v[78:81], v[142:145], v[102:105]
	v_mfma_f32_16x16x32_bf16 v[106:109], v[110:113], v[142:145], v[106:109]
	v_mfma_f32_16x16x32_bf16 v[38:41], v[78:81], v[150:153], v[38:41]
	v_mfma_f32_16x16x32_bf16 v[42:45], v[110:113], v[150:153], v[42:45]
	s_barrier
	s_mov_b64 s[26:27], 0x180
	s_mov_b32 m0, s16
	v_lshl_add_u64 v[154:155], v[34:35], 0, s[26:27]
	ds_read_b128 v[74:77], v1
	ds_read_b128 v[78:81], v1 offset:1024
	ds_read_b128 v[82:85], v1 offset:2048
	ds_read_b128 v[110:113], v1 offset:3072
	global_load_lds_dwordx4 v[154:155], off sc0
	v_lshl_add_u64 v[154:155], v[36:37], 0, s[26:27]
	s_mov_b32 m0, s17
	s_nop 0
	global_load_lds_dwordx4 v[154:155], off sc0
	s_barrier
	s_waitcnt lgkmcnt(0)
	v_mfma_f32_16x16x32_bf16 v[118:121], v[74:77], v[114:117], v[118:121]
	v_mfma_f32_16x16x32_bf16 v[54:57], v[82:85], v[114:117], v[54:57]
	v_mfma_f32_16x16x32_bf16 v[58:61], v[74:77], v[126:129], v[58:61]
	v_mfma_f32_16x16x32_bf16 v[62:65], v[82:85], v[126:129], v[62:65]
	v_mfma_f32_16x16x32_bf16 v[66:69], v[74:77], v[138:141], v[66:69]
	v_mfma_f32_16x16x32_bf16 v[70:73], v[82:85], v[138:141], v[70:73]
	v_mfma_f32_16x16x32_bf16 v[46:49], v[74:77], v[146:149], v[46:49]
	v_mfma_f32_16x16x32_bf16 v[50:53], v[82:85], v[146:149], v[50:53]
	v_mfma_f32_16x16x32_bf16 v[118:121], v[78:81], v[122:125], v[118:121]
	v_mfma_f32_16x16x32_bf16 v[54:57], v[110:113], v[122:125], v[54:57]
	v_mfma_f32_16x16x32_bf16 v[58:61], v[78:81], v[134:137], v[58:61]
	v_mfma_f32_16x16x32_bf16 v[62:65], v[110:113], v[134:137], v[62:65]
	v_mfma_f32_16x16x32_bf16 v[66:69], v[78:81], v[142:145], v[66:69]
	v_mfma_f32_16x16x32_bf16 v[70:73], v[110:113], v[142:145], v[70:73]
	v_mfma_f32_16x16x32_bf16 v[46:49], v[78:81], v[150:153], v[46:49]
	v_mfma_f32_16x16x32_bf16 v[50:53], v[110:113], v[150:153], v[50:53]
	s_mov_b32 m0, s10
	v_lshl_add_u64 v[74:75], v[32:33], 0, s[26:27]
	s_barrier
	global_load_lds_dwordx4 v[74:75], off sc0
	v_lshl_add_u64 v[74:75], v[30:31], 0, s[26:27]
	s_mov_b32 m0, s11
	s_nop 0
	global_load_lds_dwordx4 v[74:75], off sc0
	s_barrier
	s_waitcnt lgkmcnt(0)
	s_barrier
	s_add_u32 s2, s2, 0xb0180
	s_addc_u32 s3, s3, 0
	s_mov_b32 m0, s12
	v_lshl_add_u64 v[74:75], s[2:3], 0, v[130:131]
	global_load_lds_dwordx4 v[74:75], off sc0
	v_lshl_add_u64 v[74:75], s[2:3], 0, v[132:133]
	s_mov_b32 m0, s13
	s_nop 0
	global_load_lds_dwordx4 v[74:75], off sc0
	s_waitcnt vmcnt(6)
	s_barrier
	s_barrier
	ds_read_b128 v[74:77], v156
	ds_read_b128 v[78:81], v156 offset:1024
	ds_read_b128 v[82:85], v156 offset:2048
	ds_read_b128 v[110:113], v156 offset:3072
	s_add_u32 s0, s0, 0xb0180
	s_addc_u32 s1, s1, 0
	s_mov_b32 m0, s23
	v_lshl_add_u64 v[154:155], s[0:1], 0, v[130:131]
	ds_read_b128 v[114:117], v157
	ds_read_b128 v[122:125], v157 offset:1024
	ds_read_b128 v[126:129], v157 offset:2048
	ds_read_b128 v[134:137], v157 offset:3072
	ds_read_b128 v[138:141], v157 offset:4096
	ds_read_b128 v[142:145], v157 offset:5120
	ds_read_b128 v[146:149], v157 offset:6144
	ds_read_b128 v[150:153], v157 offset:7168
	global_load_lds_dwordx4 v[154:155], off sc0
	v_lshl_add_u64 v[132:133], s[0:1], 0, v[132:133]
	s_mov_b32 m0, s20
	s_nop 0
	global_load_lds_dwordx4 v[132:133], off sc0
	s_waitcnt lgkmcnt(8)
	s_barrier
	s_waitcnt lgkmcnt(0)
	v_mfma_f32_16x16x32_bf16 v[86:89], v[74:77], v[114:117], v[86:89]
	v_mfma_f32_16x16x32_bf16 v[90:93], v[82:85], v[114:117], v[90:93]
	v_mfma_f32_16x16x32_bf16 v[94:97], v[74:77], v[126:129], v[94:97]
	v_mfma_f32_16x16x32_bf16 v[98:101], v[82:85], v[126:129], v[98:101]
	v_mfma_f32_16x16x32_bf16 v[102:105], v[74:77], v[138:141], v[102:105]
	v_mfma_f32_16x16x32_bf16 v[106:109], v[82:85], v[138:141], v[106:109]
	v_mfma_f32_16x16x32_bf16 v[38:41], v[74:77], v[146:149], v[38:41]
	v_mfma_f32_16x16x32_bf16 v[42:45], v[82:85], v[146:149], v[42:45]
	v_mfma_f32_16x16x32_bf16 v[86:89], v[78:81], v[122:125], v[86:89]
	v_mfma_f32_16x16x32_bf16 v[90:93], v[110:113], v[122:125], v[90:93]
	v_mfma_f32_16x16x32_bf16 v[94:97], v[78:81], v[134:137], v[94:97]
	v_mfma_f32_16x16x32_bf16 v[98:101], v[110:113], v[134:137], v[98:101]
	v_mfma_f32_16x16x32_bf16 v[102:105], v[78:81], v[142:145], v[102:105]
	v_mfma_f32_16x16x32_bf16 v[106:109], v[110:113], v[142:145], v[106:109]
	v_mfma_f32_16x16x32_bf16 v[38:41], v[78:81], v[150:153], v[38:41]
	v_mfma_f32_16x16x32_bf16 v[42:45], v[110:113], v[150:153], v[42:45]
	s_barrier
	s_mov_b32 m0, s21
	ds_read_b128 v[74:77], v158
	ds_read_b128 v[78:81], v158 offset:1024
	ds_read_b128 v[82:85], v158 offset:2048
	ds_read_b128 v[110:113], v158 offset:3072
	global_load_lds_dwordx4 v[34:35], off sc0
	s_mov_b32 m0, s22
	s_nop 0
	global_load_lds_dwordx4 v[36:37], off sc0
	s_barrier
	s_waitcnt lgkmcnt(0)
	v_mfma_f32_16x16x32_bf16 v[34:37], v[74:77], v[114:117], v[118:121]
	v_mfma_f32_16x16x32_bf16 v[54:57], v[82:85], v[114:117], v[54:57]
	v_mfma_f32_16x16x32_bf16 v[58:61], v[74:77], v[126:129], v[58:61]
	v_mfma_f32_16x16x32_bf16 v[62:65], v[82:85], v[126:129], v[62:65]
	v_mfma_f32_16x16x32_bf16 v[66:69], v[74:77], v[138:141], v[66:69]
	v_mfma_f32_16x16x32_bf16 v[70:73], v[82:85], v[138:141], v[70:73]
	v_mfma_f32_16x16x32_bf16 v[46:49], v[74:77], v[146:149], v[46:49]
	v_mfma_f32_16x16x32_bf16 v[50:53], v[82:85], v[146:149], v[50:53]
	v_mfma_f32_16x16x32_bf16 v[34:37], v[78:81], v[122:125], v[34:37]
	v_mfma_f32_16x16x32_bf16 v[54:57], v[110:113], v[122:125], v[54:57]
	v_mfma_f32_16x16x32_bf16 v[58:61], v[78:81], v[134:137], v[58:61]
	v_mfma_f32_16x16x32_bf16 v[62:65], v[110:113], v[134:137], v[62:65]
	v_mfma_f32_16x16x32_bf16 v[66:69], v[78:81], v[142:145], v[66:69]
	v_mfma_f32_16x16x32_bf16 v[70:73], v[110:113], v[142:145], v[70:73]
	v_mfma_f32_16x16x32_bf16 v[46:49], v[78:81], v[150:153], v[46:49]
	v_mfma_f32_16x16x32_bf16 v[50:53], v[110:113], v[150:153], v[50:53]
	s_mov_b32 m0, s9
	s_barrier
	global_load_lds_dwordx4 v[32:33], off sc0
	s_mov_b32 m0, s18
	s_nop 0
	global_load_lds_dwordx4 v[30:31], off sc0
	s_barrier
	s_waitcnt lgkmcnt(0)
	s_barrier
	s_mov_b32 m0, s19
	s_nop 0
	global_load_lds_dwordx4 v[28:29], off sc0
	s_mov_b32 m0, s24
	s_nop 0
	global_load_lds_dwordx4 v[26:27], off sc0
	s_waitcnt vmcnt(6)
	s_barrier
	s_barrier
	ds_read_b128 v[26:29], v159
	ds_read_b128 v[30:33], v159 offset:1024
	ds_read_b128 v[74:77], v159 offset:2048
	ds_read_b128 v[78:81], v159 offset:3072
	s_mov_b32 m0, s14
	ds_read_b128 v[82:85], v157 offset:32768
	ds_read_b128 v[110:113], v157 offset:33792
	ds_read_b128 v[114:117], v157 offset:34816
	ds_read_b128 v[118:121], v157 offset:35840
	ds_read_b128 v[122:125], v157 offset:36864
	ds_read_b128 v[126:129], v157 offset:37888
	ds_read_b128 v[132:135], v157 offset:38912
	ds_read_b128 v[136:139], v157 offset:39936
	global_load_lds_dwordx4 v[22:23], off sc0
	s_mov_b32 m0, s15
	s_nop 0
	global_load_lds_dwordx4 v[24:25], off sc0
	s_waitcnt lgkmcnt(8)
	s_barrier
	s_waitcnt lgkmcnt(0)
	v_mfma_f32_16x16x32_bf16 v[22:25], v[26:29], v[82:85], v[86:89]
	v_mfma_f32_16x16x32_bf16 v[86:89], v[74:77], v[82:85], v[90:93]
	v_mfma_f32_16x16x32_bf16 v[90:93], v[26:29], v[114:117], v[94:97]
	v_mfma_f32_16x16x32_bf16 v[94:97], v[74:77], v[114:117], v[98:101]
	v_mfma_f32_16x16x32_bf16 v[98:101], v[26:29], v[122:125], v[102:105]
	v_mfma_f32_16x16x32_bf16 v[26:29], v[26:29], v[132:135], v[38:41]
	v_mfma_f32_16x16x32_bf16 v[22:25], v[30:33], v[110:113], v[22:25]
	v_mfma_f32_16x16x32_bf16 v[90:93], v[30:33], v[118:121], v[90:93]
	v_mfma_f32_16x16x32_bf16 v[98:101], v[30:33], v[126:129], v[98:101]
	v_mfma_f32_16x16x32_bf16 v[102:105], v[74:77], v[122:125], v[106:109]
	v_mfma_f32_16x16x32_bf16 v[26:29], v[30:33], v[136:139], v[26:29]
	v_mfma_f32_16x16x32_bf16 v[30:33], v[74:77], v[132:135], v[42:45]
	v_mfma_f32_16x16x32_bf16 v[86:89], v[78:81], v[110:113], v[86:89]
	v_mfma_f32_16x16x32_bf16 v[94:97], v[78:81], v[118:121], v[94:97]
	v_mfma_f32_16x16x32_bf16 v[102:105], v[78:81], v[126:129], v[102:105]
	v_mfma_f32_16x16x32_bf16 v[30:33], v[78:81], v[136:139], v[30:33]
	s_barrier
	s_mov_b32 m0, s16
	ds_read_b128 v[38:41], v1
	ds_read_b128 v[42:45], v1 offset:1024
	ds_read_b128 v[74:77], v1 offset:2048
	ds_read_b128 v[78:81], v1 offset:3072
	global_load_lds_dwordx4 v[18:19], off sc0
	s_mov_b32 m0, s17
	s_nop 0
	global_load_lds_dwordx4 v[20:21], off sc0
	s_barrier
	s_waitcnt lgkmcnt(0)
	v_mfma_f32_16x16x32_bf16 v[18:21], v[38:41], v[82:85], v[34:37]
	v_mfma_f32_16x16x32_bf16 v[34:37], v[74:77], v[82:85], v[54:57]
	v_mfma_f32_16x16x32_bf16 v[54:57], v[38:41], v[114:117], v[58:61]
	v_mfma_f32_16x16x32_bf16 v[58:61], v[74:77], v[114:117], v[62:65]
	v_mfma_f32_16x16x32_bf16 v[62:65], v[38:41], v[122:125], v[66:69]
	v_mfma_f32_16x16x32_bf16 v[38:41], v[38:41], v[132:135], v[46:49]
	v_mfma_f32_16x16x32_bf16 v[18:21], v[42:45], v[110:113], v[18:21]
	v_mfma_f32_16x16x32_bf16 v[54:57], v[42:45], v[118:121], v[54:57]
	v_mfma_f32_16x16x32_bf16 v[62:65], v[42:45], v[126:129], v[62:65]
	v_mfma_f32_16x16x32_bf16 v[66:69], v[74:77], v[122:125], v[70:73]
	v_mfma_f32_16x16x32_bf16 v[38:41], v[42:45], v[136:139], v[38:41]
	v_mfma_f32_16x16x32_bf16 v[42:45], v[74:77], v[132:135], v[50:53]
	v_mfma_f32_16x16x32_bf16 v[34:37], v[78:81], v[110:113], v[34:37]
	v_mfma_f32_16x16x32_bf16 v[58:61], v[78:81], v[118:121], v[58:61]
	v_mfma_f32_16x16x32_bf16 v[66:69], v[78:81], v[126:129], v[66:69]
	v_mfma_f32_16x16x32_bf16 v[42:45], v[78:81], v[136:139], v[42:45]
	s_mov_b32 m0, s10
	s_barrier
	global_load_lds_dwordx4 v[2:3], off sc0
	s_mov_b32 m0, s11
	s_nop 0
	global_load_lds_dwordx4 v[6:7], off sc0
	s_barrier
	s_waitcnt lgkmcnt(0)
	s_barrier
	s_mov_b32 m0, s12
	s_nop 0
	global_load_lds_dwordx4 v[10:11], off sc0
	s_mov_b32 m0, s13
	s_nop 0
	global_load_lds_dwordx4 v[12:13], off sc0
	s_waitcnt vmcnt(6)
	s_barrier
	s_lshl_b32 s0, s5, 8
	v_lshl_or_b32 v1, v211, 2, s0
	s_ashr_i32 s0, s82, 2
	s_ashr_i32 s1, s0, 31
	s_lshl_b64 s[0:1], s[0:1], 19
	v_or_b32_e32 v1, s8, v1
	s_add_u32 s0, s94, s0
	s_addc_u32 s1, s95, s1
	v_lshlrev_b32_e32 v130, 2, v1
	v_lshl_add_u64 v[2:3], s[0:1], 0, v[130:131]
	s_mov_b64 s[0:1], 0xb3d6400
	v_lshl_add_u64 v[2:3], v[2:3], 0, s[0:1]
	v_lshl_add_u64 v[6:7], v[2:3], 0, v[8:9]
	v_lshl_add_u64 v[4:5], v[2:3], 0, v[4:5]
	s_barrier
	global_store_dwordx4 v[6:7], v[22:25], off
	global_store_dwordx4 v[6:7], v[86:89], off offset:64
	global_store_dwordx4 v[6:7], v[18:21], off offset:512
	global_store_dwordx4 v[6:7], v[34:37], off offset:576
	global_store_dwordx4 v[4:5], v[90:93], off
	global_store_dwordx4 v[4:5], v[94:97], off offset:64
	global_store_dwordx4 v[4:5], v[54:57], off offset:512
	global_store_dwordx4 v[4:5], v[58:61], off offset:576
	v_lshl_add_u64 v[4:5], v[2:3], 0, v[16:17]
	v_lshl_add_u64 v[2:3], v[2:3], 0, v[14:15]
	global_store_dwordx4 v[4:5], v[98:101], off
	global_store_dwordx4 v[4:5], v[102:105], off offset:64
	global_store_dwordx4 v[4:5], v[62:65], off offset:512
	global_store_dwordx4 v[4:5], v[66:69], off offset:576
	global_store_dwordx4 v[2:3], v[26:29], off
	global_store_dwordx4 v[2:3], v[30:33], off offset:64
	global_store_dwordx4 v[2:3], v[38:41], off offset:512
	global_store_dwordx4 v[2:3], v[42:45], off offset:576
	s_waitcnt vmcnt(0)
	s_cmpk_gt_u32 s4, 0xff
	s_cbranch_scc1 .LBB0_1207
	s_barrier
